# LayerNorm epilogue: all output stores deferred to the end of the epilogue (packed in place), so residual fetches see read-only HBM and stores drain under the next GEMM
# baseline (speedup 1.0000x reference)
; DI f32x4 mfma16(bf16x8 a, bf16x8 b, f32x4 c) { return __builtin_amdgcn_mfma_f32_16x16x32_bf16(a, b, c, 0, 0, 0); }
; template <int N> DI void wait_vm() { asm volatile("s_waitcnt vmcnt(%0)" ::"n"(N) : "memory"); }
;     ...
;         for (int part = 0; part < NIT; ++part) {
; #pragma unroll
;             for (int q = 0; q < PER; ++q) {
;                 const int idx = part * PER + q;
;                 if (idx < TOT) {
;                     const int mt = idx / NT, nt = idx % NT;
;                     acc[mt][nt] = SWAP ? mfma16(bfr[nt], af[mt], acc[mt][nt]) : mfma16(af[mt], bfr[nt], acc[mt][nt]);
;                 }
;             }
;             __builtin_amdgcn_sched_barrier(0);
;             if (do_issue) issue_one(ikt, ib, part);
;             __builtin_amdgcn_sched_barrier(0);
;         }
; DI void unit_O(const Params& p, char* lds, int l, int tile, int glu_tiles, int tile_b) {
;     ...
;     auto issue_x = [&](int half) {
;         if (l == 0) {
; #pragma unroll 1
;             for (int i = 0; i < 16; ++i) {
;                 const int pc = (wid * 16 + i + xrot) & 127, row = pc >> 2, phys = (pc & 3) * 64 + lane, logical = phys ^ (row & 15);
;                 __builtin_amdgcn_global_load_lds((const unsigned*)(xres + (r0 + half * 32 + row) * 1024 + logical * 4), (unsigned*)(XR + pc * 1024 + lane * 16), 16, 0, 0);
;             }
;         } else {
; #pragma unroll 1
;             for (int i = 0; i < 8; ++i) {
;                 const int pc = (wid * 8 + i + (xrot >> 1)) & 63, kt = pc >> 1, sub = pc & 1;
;                 __builtin_amdgcn_global_load_lds((const unsigned*)(xbres + ((size_t)kt * 128 + half * 32) * 32 + sub * 512 + lane * 8), (unsigned*)(XR + pc * 1024 + lane * 16), 16, 0, 0);
;             }
;         }
;     };
;     issue_x(0);
;     {
;         const float* gsrc = (tid < 256) ? (p.ln_g + l * 1024 + tid * 4) : (p.ln_b + l * 1024 + (tid - 256) * 4);
;         *(f32x4*)(GB + tid * 4) = *(const f32x4*)gsrc;
;     }
;     float* xo = (l == 0) ? WS_PTR(float, OFF_X1) : p.out;
;     bf16_t* xbo = WS_PTR(bf16_t, OFF_XB1);
; #pragma unroll
;     for (int half = 0; half < 2; ++half) {
;         if (half == 0) wait_vm<0>();
;         else wait_vm<8>();
;         __syncthreads();
.Lpo1_join:
.LBB0_100:
	s_waitcnt vmcnt(0)
	v_add_u32_e32 v0, 0x11000, v140
	s_barrier
	v_add_u32_e32 v134, v0, v141
	v_add_u32_e32 v0, v0, v139
	ds_read_b128 v[130:133], v134 offset:4096
	ds_read_b128 v[138:141], v0
	ds_read_b128 v[142:145], v134 offset:5120
	ds_read_b128 v[146:149], v0 offset:1024
	ds_read_b128 v[150:153], v134 offset:6144
	ds_read_b128 v[154:157], v134 offset:7168
	ds_read_b128 v[158:161], v134 offset:8192
	ds_read_b128 v[162:165], v134 offset:9216
	ds_read_b128 v[166:169], v134 offset:10240
	ds_read_b128 v[170:173], v134 offset:11264
	ds_read_b128 v[174:177], v0 offset:2048
	ds_read_b128 v[178:181], v0 offset:3072
	s_waitcnt lgkmcnt(0)
	v_mfma_f32_16x16x32_bf16 v[98:101], v[130:133], v[138:141], v[98:101]
	v_and_b32_e32 v197, 63, v136
	v_ashrrev_i32_e32 v236, 6, v136
	v_mfma_f32_16x16x32_bf16 v[94:97], v[142:145], v[138:141], v[94:97]
	v_mfma_f32_16x16x32_bf16 v[90:93], v[150:153], v[138:141], v[90:93]
	v_mfma_f32_16x16x32_bf16 v[86:89], v[154:157], v[138:141], v[86:89]
	v_mfma_f32_16x16x32_bf16 v[82:85], v[158:161], v[138:141], v[82:85]
	v_mfma_f32_16x16x32_bf16 v[78:81], v[162:165], v[138:141], v[78:81]
	v_mfma_f32_16x16x32_bf16 v[74:77], v[166:169], v[138:141], v[74:77]
	v_mfma_f32_16x16x32_bf16 v[70:73], v[170:173], v[138:141], v[70:73]
	v_mfma_f32_16x16x32_bf16 v[126:129], v[130:133], v[146:149], v[126:129]
	v_mfma_f32_16x16x32_bf16 v[122:125], v[142:145], v[146:149], v[122:125]
	v_mfma_f32_16x16x32_bf16 v[118:121], v[150:153], v[146:149], v[118:121]
	v_mfma_f32_16x16x32_bf16 v[114:117], v[154:157], v[146:149], v[114:117]
	v_mfma_f32_16x16x32_bf16 v[110:113], v[158:161], v[146:149], v[110:113]
	v_mfma_f32_16x16x32_bf16 v[106:109], v[162:165], v[146:149], v[106:109]
	v_mfma_f32_16x16x32_bf16 v[102:105], v[166:169], v[146:149], v[102:105]
	v_mfma_f32_16x16x32_bf16 v[66:69], v[170:173], v[146:149], v[66:69]
	v_mfma_f32_16x16x32_bf16 v[34:37], v[130:133], v[174:177], v[34:37]
	v_mfma_f32_16x16x32_bf16 v[30:33], v[142:145], v[174:177], v[30:33]
	v_mfma_f32_16x16x32_bf16 v[26:29], v[150:153], v[174:177], v[26:29]
	v_mfma_f32_16x16x32_bf16 v[22:25], v[154:157], v[174:177], v[22:25]
	v_mfma_f32_16x16x32_bf16 v[18:21], v[158:161], v[174:177], v[18:21]
	v_mfma_f32_16x16x32_bf16 v[14:17], v[162:165], v[174:177], v[14:17]
	v_mfma_f32_16x16x32_bf16 v[10:13], v[166:169], v[174:177], v[10:13]
	v_mfma_f32_16x16x32_bf16 v[6:9], v[170:173], v[174:177], v[6:9]
	v_mfma_f32_16x16x32_bf16 v[62:65], v[130:133], v[178:181], v[62:65]
	v_mfma_f32_16x16x32_bf16 v[58:61], v[142:145], v[178:181], v[58:61]
	v_mfma_f32_16x16x32_bf16 v[54:57], v[150:153], v[178:181], v[54:57]
	v_mfma_f32_16x16x32_bf16 v[50:53], v[154:157], v[178:181], v[50:53]
	v_mfma_f32_16x16x32_bf16 v[46:49], v[158:161], v[178:181], v[46:49]
	v_mfma_f32_16x16x32_bf16 v[42:45], v[162:165], v[178:181], v[42:45]
	v_mfma_f32_16x16x32_bf16 v[38:41], v[166:169], v[178:181], v[38:41]
	v_mfma_f32_16x16x32_bf16 v[2:5], v[170:173], v[178:181], v[2:5]
	s_barrier
	s_not_b64 s[6:7], s[10:11]
	v_and_b32_e32 v138, 15, v212
	v_bfe_u32 v139, v212, 4, 2
	v_lshrrev_b32_e32 v140, 6, v212
	v_and_b32_e32 v141, 63, v212
	v_readfirstlane_b32 s90, v140
	v_and_b32_e32 v142, 0xff, v212
	v_lshlrev_b32_e32 v142, 4, v142
	s_cmp_lt_u32 s90, 4
	s_cselect_b32 s92, s14, s12
	s_cselect_b32 s93, s15, s13
	s_nop 3
	global_load_dwordx4 v[176:179], v142, s[92:93]
	v_lshlrev_b32_e32 v143, 4, v212
	v_add_u32_e32 v143, 0x20000, v143
	v_lshlrev_b32_e32 v134, 6, v138
	v_add_u32_e32 v135, 0x22000, v134
	v_lshl_add_u32 v134, v140, 3, v135
	v_lshlrev_b32_e32 v136, 9, v140
	v_lshl_add_u32 v136, v139, 4, v136
	v_add_u32_e32 v136, 0x20000, v136
	s_cmp_lg_u64 s[10:11], 0
	s_cbranch_scc1 .Le1_l1
	s_lshl_b32 s40, s34, 18
	s_lshl_b32 s91, s90, 13
	s_add_u32 s96, s52, s40
	s_addc_u32 s97, s53, 0
	s_add_u32 s96, s96, s91
	s_addc_u32 s97, s97, 0
	s_lshl_b32 s40, s90, 1
	v_xor_b32_e32 v208, s40, v141
	v_lshlrev_b32_e32 v208, 4, v208
	s_add_u32 s40, s40, 1
	v_xor_b32_e32 v209, s40, v141
	v_lshlrev_b32_e32 v209, 4, v209
	v_lshlrev_b32_e32 v133, 12, v138
	v_lshl_add_u32 v133, v140, 9, v133
	v_add_u32_e32 v200, 0, v139
	v_xor_b32_e32 v200, v200, v138
	v_lshl_add_u32 v200, v200, 4, v133
	v_add_u32_e32 v204, 0x10000, v200
	v_add_u32_e32 v201, 4, v139
	v_xor_b32_e32 v201, v201, v138
	v_lshl_add_u32 v201, v201, 4, v133
	v_add_u32_e32 v205, 0x10000, v201
	v_add_u32_e32 v202, 8, v139
	v_xor_b32_e32 v202, v202, v138
	v_lshl_add_u32 v202, v202, 4, v133
	v_add_u32_e32 v206, 0x10000, v202
	v_add_u32_e32 v203, 12, v139
	v_xor_b32_e32 v203, v203, v138
	v_lshl_add_u32 v203, v203, 4, v133
	v_add_u32_e32 v207, 0x10000, v203
	v_and_b32_e32 v137, 1, v139
	v_lshlrev_b32_e32 v137, 5, v137
	v_lshrrev_b32_e32 v130, 1, v139
	v_lshl_or_b32 v137, v130, 4, v137
	v_lshl_or_b32 v137, v138, 6, v137
	v_lshl_or_b32 v137, v140, 15, v137
	s_lshr_b32 s40, s34, 1
	s_lshl_b32 s40, s40, 18
	s_and_b32 s46, s34, 1
	s_lshl_b32 s46, s46, 12
	s_add_u32 s40, s40, s46
	s_add_u32 s78, s56, s40
	s_addc_u32 s79, s57, 0
	s_add_u32 s92, s96, 0x0
	s_addc_u32 s93, s97, 0
	s_add_u32 s40, s91, 0x0
	s_mov_b32 m0, s40
	s_nop 0
	global_load_lds_dwordx4 v208, s[92:93]
	global_load_lds_dwordx4 v208, s[92:93] offset:1024
	global_load_lds_dwordx4 v208, s[92:93] offset:2048
	global_load_lds_dwordx4 v208, s[92:93] offset:3072
	s_add_u32 s92, s96, 0x1000
	s_addc_u32 s93, s97, 0
	s_add_u32 s40, s91, 0x1000
	s_mov_b32 m0, s40
	s_nop 0
	global_load_lds_dwordx4 v209, s[92:93]
	global_load_lds_dwordx4 v209, s[92:93] offset:1024
	global_load_lds_dwordx4 v209, s[92:93] offset:2048
	global_load_lds_dwordx4 v209, s[92:93] offset:3072
	s_add_u32 s92, s96, 0x10000
	s_addc_u32 s93, s97, 0
	s_add_u32 s40, s91, 0x10000
	s_mov_b32 m0, s40
	s_nop 0
	global_load_lds_dwordx4 v208, s[92:93]
	global_load_lds_dwordx4 v208, s[92:93] offset:1024
	global_load_lds_dwordx4 v208, s[92:93] offset:2048
	global_load_lds_dwordx4 v208, s[92:93] offset:3072
	s_add_u32 s92, s96, 0x11000
	s_addc_u32 s93, s97, 0
	s_add_u32 s40, s91, 0x11000
	s_mov_b32 m0, s40
	s_nop 0
	global_load_lds_dwordx4 v209, s[92:93]
	global_load_lds_dwordx4 v209, s[92:93] offset:1024
	global_load_lds_dwordx4 v209, s[92:93] offset:2048
	global_load_lds_dwordx4 v209, s[92:93] offset:3072
	s_waitcnt vmcnt(16)
	ds_write_b128 v143, v[176:179]
	s_waitcnt vmcnt(8) lgkmcnt(0)
	s_barrier
; DI float bf2f(unsigned b) { return __uint_as_float(b << 16); }
; DI void unit_O(const Params& p, char* lds, int l, int tile, int glu_tiles, int tile_b) {
;     ...
;         float s2[2], ss2[2];
; #pragma unroll
;         for (int mh = 0; mh < 2; ++mh) {
;             const int mt = half * 2 + mh, rl = mh * 16 + l15;
;             float s = 0.f, ss = 0.f;
; #pragma unroll
;             for (int nt = 0; nt < 8; ++nt) {
;                 f32x4 xr;
;                 if (l == 0) {
;                     const int chunk = wid * 32 + nt * 4 + quad;
;                     xr = *(const f32x4*)(XR + rl * 4096 + ((chunk ^ l15) << 4));
;                 } else {
;                     const u32x2 hb = *(const u32x2*)(XR + ((wid * 4 + (nt >> 1)) * 32 + rl) * 64 + (nt & 1) * 32 + quad * 8);
;                     xr = (f32x4){bf2f(hb[0] & 0xffffu), bf2f(hb[0] >> 16), bf2f(hb[1] & 0xffffu), bf2f(hb[1] >> 16)};
;                 }
; #pragma unroll
;                 for (int i = 0; i < 4; ++i) { const float v = acc[mt][nt][i] + DN_ALPHA * xr[i]; acc[mt][nt][i] = v; s += v; ss += v * v; }
;             }
;             s2[mh] = s; ss2[mh] = ss;
;         }
; #pragma unroll
;         for (int mh = 0; mh < 2; ++mh) { s2[mh] += __shfl_xor(s2[mh], 16); ss2[mh] += __shfl_xor(ss2[mh], 16); }
; #pragma unroll
;         for (int mh = 0; mh < 2; ++mh) { s2[mh] += __shfl_xor(s2[mh], 32); ss2[mh] += __shfl_xor(ss2[mh], 32); }
;         if (quad == 0) {
; #pragma unroll
;             for (int mh = 0; mh < 2; ++mh) *(f32x2*)&red[((mh * 16 + l15) * 8 + wid) * 2] = (f32x2){s2[mh], ss2[mh]};
;         }
;         __syncthreads();
;         if (half == 0) issue_x(1);
; #pragma unroll
;         for (int mh = 0; mh < 2; ++mh) {
;             const int mt = half * 2 + mh, rl = mh * 16 + l15, row = mt * 16 + l15;
;             float s = 0.f, ss = 0.f;
; #pragma unroll
;             for (int w = 0; w < 4; ++w) { const f32x4 v = *(const f32x4*)&red[rl * 16 + 4 * w]; s += v[0] + v[2]; ss += v[1] + v[3]; }
;             const float mu = s * (1.f / 1024.f);
;             const float var = ss * (1.f / 1024.f) - mu * mu;
;             const float rs = rsqrtf(var + LN_EPS);
	ds_read_b128 v[144:147], v200
	ds_read_b128 v[148:151], v201
	ds_read_b128 v[152:155], v202
	ds_read_b128 v[156:159], v203
	ds_read_b128 v[160:163], v200 offset:256
	ds_read_b128 v[164:167], v201 offset:256
	ds_read_b128 v[168:171], v202 offset:256
	ds_read_b128 v[172:175], v203 offset:256
	s_waitcnt lgkmcnt(7)
	v_fmac_f32_e32 v98, s58, v144
	v_fmac_f32_e32 v99, s58, v145
	v_fmac_f32_e32 v100, s58, v146
	v_fmac_f32_e32 v101, s58, v147
	v_mov_b32_e32 v196, v98
	v_mul_f32_e32 v197, v98, v98
	v_mov_b32_e32 v130, v99
	v_mul_f32_e32 v142, v99, v99
	v_add_f32_e32 v196, v196, v100
	v_fmac_f32_e32 v197, v100, v100
	v_add_f32_e32 v130, v130, v101
	v_fmac_f32_e32 v142, v101, v101
	s_waitcnt lgkmcnt(6)
	v_fmac_f32_e32 v94, s58, v148
	v_fmac_f32_e32 v95, s58, v149
	v_fmac_f32_e32 v96, s58, v150
	v_fmac_f32_e32 v97, s58, v151
	v_add_f32_e32 v196, v196, v94
	v_fmac_f32_e32 v197, v94, v94
	v_add_f32_e32 v130, v130, v95
	v_fmac_f32_e32 v142, v95, v95
	v_add_f32_e32 v196, v196, v96
	v_fmac_f32_e32 v197, v96, v96
	v_add_f32_e32 v130, v130, v97
	v_fmac_f32_e32 v142, v97, v97
	s_waitcnt lgkmcnt(5)
	v_fmac_f32_e32 v90, s58, v152
	v_fmac_f32_e32 v91, s58, v153
	v_fmac_f32_e32 v92, s58, v154
	v_fmac_f32_e32 v93, s58, v155
	v_add_f32_e32 v196, v196, v90
	v_fmac_f32_e32 v197, v90, v90
	v_add_f32_e32 v130, v130, v91
	v_fmac_f32_e32 v142, v91, v91
	v_add_f32_e32 v196, v196, v92
	v_fmac_f32_e32 v197, v92, v92
	v_add_f32_e32 v130, v130, v93
	v_fmac_f32_e32 v142, v93, v93
	s_waitcnt lgkmcnt(4)
	v_fmac_f32_e32 v86, s58, v156
	v_fmac_f32_e32 v87, s58, v157
	v_fmac_f32_e32 v88, s58, v158
	v_fmac_f32_e32 v89, s58, v159
	v_add_f32_e32 v196, v196, v86
	v_fmac_f32_e32 v197, v86, v86
	v_add_f32_e32 v130, v130, v87
	v_fmac_f32_e32 v142, v87, v87
	v_add_f32_e32 v196, v196, v88
	v_fmac_f32_e32 v197, v88, v88
	v_add_f32_e32 v130, v130, v89
	v_fmac_f32_e32 v142, v89, v89
	s_waitcnt lgkmcnt(3)
	v_fmac_f32_e32 v82, s58, v160
	v_fmac_f32_e32 v83, s58, v161
	v_fmac_f32_e32 v84, s58, v162
	v_fmac_f32_e32 v85, s58, v163
	v_add_f32_e32 v196, v196, v82
	v_fmac_f32_e32 v197, v82, v82
	v_add_f32_e32 v130, v130, v83
	v_fmac_f32_e32 v142, v83, v83
	v_add_f32_e32 v196, v196, v84
	v_fmac_f32_e32 v197, v84, v84
	v_add_f32_e32 v130, v130, v85
	v_fmac_f32_e32 v142, v85, v85
	s_waitcnt lgkmcnt(2)
	v_fmac_f32_e32 v78, s58, v164
	v_fmac_f32_e32 v79, s58, v165
	v_fmac_f32_e32 v80, s58, v166
	v_fmac_f32_e32 v81, s58, v167
	v_add_f32_e32 v196, v196, v78
	v_fmac_f32_e32 v197, v78, v78
	v_add_f32_e32 v130, v130, v79
	v_fmac_f32_e32 v142, v79, v79
	v_add_f32_e32 v196, v196, v80
	v_fmac_f32_e32 v197, v80, v80
	v_add_f32_e32 v130, v130, v81
	v_fmac_f32_e32 v142, v81, v81
	s_waitcnt lgkmcnt(1)
	v_fmac_f32_e32 v74, s58, v168
	v_fmac_f32_e32 v75, s58, v169
	v_fmac_f32_e32 v76, s58, v170
	v_fmac_f32_e32 v77, s58, v171
	v_add_f32_e32 v196, v196, v74
	v_fmac_f32_e32 v197, v74, v74
	v_add_f32_e32 v130, v130, v75
	v_fmac_f32_e32 v142, v75, v75
	v_add_f32_e32 v196, v196, v76
	v_fmac_f32_e32 v197, v76, v76
	v_add_f32_e32 v130, v130, v77
	v_fmac_f32_e32 v142, v77, v77
	s_waitcnt lgkmcnt(0)
	v_fmac_f32_e32 v70, s58, v172
	v_fmac_f32_e32 v71, s58, v173
	v_fmac_f32_e32 v72, s58, v174
	v_fmac_f32_e32 v73, s58, v175
	v_add_f32_e32 v196, v196, v70
	v_fmac_f32_e32 v197, v70, v70
	v_add_f32_e32 v130, v130, v71
	v_fmac_f32_e32 v142, v71, v71
	v_add_f32_e32 v196, v196, v72
	v_fmac_f32_e32 v197, v72, v72
	v_add_f32_e32 v130, v130, v73
	v_fmac_f32_e32 v142, v73, v73
	v_add_f32_e32 v196, v196, v130
	v_add_f32_e32 v197, v197, v142
	v_mov_b32_e32 v198, v196
	v_mov_b32_e32 v199, v197
	s_nop 1
	v_permlane16_swap_b32 v198, v196
	v_permlane16_swap_b32 v199, v197
	v_add_f32_e32 v196, v196, v198
	v_add_f32_e32 v197, v197, v199
	v_mov_b32_e32 v198, v196
	v_mov_b32_e32 v199, v197
	s_nop 1
	v_permlane32_swap_b32 v198, v196
	v_permlane32_swap_b32 v199, v197
	v_add_f32_e32 v196, v196, v198
	v_add_f32_e32 v197, v197, v199
	s_mov_b64 exec, 0xffff
	ds_write_b64 v134, v[196:197]
	s_mov_b64 exec, -1
	s_waitcnt lgkmcnt(0)
	s_barrier
	s_add_u32 s92, s96, 0x20000
	s_addc_u32 s93, s97, 0
	s_add_u32 s40, s91, 0x0
	s_mov_b32 m0, s40
	s_nop 0
	global_load_lds_dwordx4 v208, s[92:93]
	global_load_lds_dwordx4 v208, s[92:93] offset:1024
	global_load_lds_dwordx4 v208, s[92:93] offset:2048
	global_load_lds_dwordx4 v208, s[92:93] offset:3072
	s_add_u32 s92, s96, 0x21000
	s_addc_u32 s93, s97, 0
	s_add_u32 s40, s91, 0x1000
	s_mov_b32 m0, s40
	s_nop 0
	global_load_lds_dwordx4 v209, s[92:93]
	global_load_lds_dwordx4 v209, s[92:93] offset:1024
	global_load_lds_dwordx4 v209, s[92:93] offset:2048
	global_load_lds_dwordx4 v209, s[92:93] offset:3072
	ds_read_b128 v[160:163], v135 offset:0
	ds_read_b128 v[164:167], v135 offset:16
	ds_read_b128 v[168:171], v135 offset:32
	ds_read_b128 v[172:175], v135 offset:48
	s_waitcnt lgkmcnt(0)
	v_add_f32_e32 v160, v160, v162
	v_add_f32_e32 v161, v161, v163
	v_add_f32_e32 v164, v164, v166
	v_add_f32_e32 v165, v165, v167
	v_add_f32_e32 v168, v168, v170
	v_add_f32_e32 v169, v169, v171
	v_add_f32_e32 v172, v172, v174
	v_add_f32_e32 v173, v173, v175
	v_add_f32_e32 v160, v160, v164
	v_add_f32_e32 v161, v161, v165
	v_add_f32_e32 v168, v168, v172
	v_add_f32_e32 v169, v169, v173
	v_add_f32_e32 v160, v160, v168
	v_add_f32_e32 v161, v161, v169
	v_mul_f32_e32 v192, 0x3a800000, v160
	v_mul_f32_e32 v193, 0x3a800000, v161
	v_fma_f32 v193, -v192, v192, v193
	v_add_f32_e32 v193, 0x3727c5ac, v193
	v_rsq_f32_e32 v193, v193
	s_nop 0
	ds_read_b128 v[176:179], v136
	ds_read_b128 v[180:183], v136 offset:4096
	ds_read_b128 v[184:187], v136 offset:64
	ds_read_b128 v[188:191], v136 offset:4160
	s_waitcnt lgkmcnt(2)
; DI unsigned pk2(float lo, float hi) { const f32x2 v = {lo, hi}; const bf16x2_t b = __builtin_convertvector(v, bf16x2_t); return __builtin_bit_cast(unsigned, b); }
; DI size_t xb_off(int tok, int col) { return ((size_t)(((tok >> 7) * 32 + (col >> 5)) * 128 + (tok & 127))) * 32 + (col & 31); }
; DI void unit_O(const Params& p, char* lds, int l, int tile, int glu_tiles, int tile_b) {
;     ...
;             float* orow = xo + (r0 + row) * 1024 + wid * 128 + quad * 4;
;             bf16_t* brow = xbo + xb_off((int)r0 + row, wid * 128) + quad * 4;
;             const float* gp = GB + wid * 128 + quad * 4;
; #pragma unroll
;             for (int nt = 0; nt < 8; ++nt) {
;                 const f32x4 g = *(const f32x4*)(gp + nt * 16), bb = *(const f32x4*)(gp + 1024 + nt * 16);
;                 f32x4 o;
; #pragma unroll
;                 for (int i = 0; i < 4; ++i) o[i] = (acc[mt][nt][i] - mu) * rs * g[i] + bb[i];
;                 if (l == 0) *(u32x2*)(brow + (nt >> 1) * 4096 + (nt & 1) * 16) = (u32x2){pk2(o[0], o[1]), pk2(o[2], o[3])};
	v_sub_f32_e32 v98, v98, v192
	v_mul_f32_e32 v98, v98, v193
	v_fma_f32 v98, v176, v98, v180
	v_sub_f32_e32 v99, v99, v192
	v_mul_f32_e32 v99, v99, v193
	v_fma_f32 v99, v177, v99, v181
	v_sub_f32_e32 v100, v100, v192
	v_mul_f32_e32 v100, v100, v193
	v_fma_f32 v100, v178, v100, v182
	v_sub_f32_e32 v101, v101, v192
	v_mul_f32_e32 v101, v101, v193
	v_fma_f32 v101, v179, v101, v183
	v_cvt_pk_bf16_f32 v98, v98, v99
	v_cvt_pk_bf16_f32 v99, v100, v101
	ds_read_b128 v[176:179], v136 offset:128
	ds_read_b128 v[180:183], v136 offset:4224
	s_waitcnt lgkmcnt(2)
	v_sub_f32_e32 v94, v94, v192
	v_mul_f32_e32 v94, v94, v193
	v_fma_f32 v94, v184, v94, v188
	v_sub_f32_e32 v95, v95, v192
	v_mul_f32_e32 v95, v95, v193
	v_fma_f32 v95, v185, v95, v189
	v_sub_f32_e32 v96, v96, v192
	v_mul_f32_e32 v96, v96, v193
	v_fma_f32 v96, v186, v96, v190
	v_sub_f32_e32 v97, v97, v192
	v_mul_f32_e32 v97, v97, v193
	v_fma_f32 v97, v187, v97, v191
	v_cvt_pk_bf16_f32 v100, v94, v95
	v_cvt_pk_bf16_f32 v101, v96, v97
	s_nop 1
	v_permlane16_swap_b32 v98, v100
	v_permlane16_swap_b32 v99, v101
	ds_read_b128 v[184:187], v136 offset:192
	ds_read_b128 v[188:191], v136 offset:4288
	s_waitcnt lgkmcnt(2)
	v_sub_f32_e32 v90, v90, v192
	v_mul_f32_e32 v90, v90, v193
	v_fma_f32 v90, v176, v90, v180
	v_sub_f32_e32 v91, v91, v192
	v_mul_f32_e32 v91, v91, v193
	v_fma_f32 v91, v177, v91, v181
	v_sub_f32_e32 v92, v92, v192
	v_mul_f32_e32 v92, v92, v193
	v_fma_f32 v92, v178, v92, v182
	v_sub_f32_e32 v93, v93, v192
	v_mul_f32_e32 v93, v93, v193
	v_fma_f32 v93, v179, v93, v183
	v_cvt_pk_bf16_f32 v90, v90, v91
	v_cvt_pk_bf16_f32 v91, v92, v93
	ds_read_b128 v[176:179], v136 offset:256
	ds_read_b128 v[180:183], v136 offset:4352
	s_waitcnt lgkmcnt(2)
	v_sub_f32_e32 v86, v86, v192
	v_mul_f32_e32 v86, v86, v193
	v_fma_f32 v86, v184, v86, v188
	v_sub_f32_e32 v87, v87, v192
	v_mul_f32_e32 v87, v87, v193
	v_fma_f32 v87, v185, v87, v189
	v_sub_f32_e32 v88, v88, v192
	v_mul_f32_e32 v88, v88, v193
	v_fma_f32 v88, v186, v88, v190
	v_sub_f32_e32 v89, v89, v192
	v_mul_f32_e32 v89, v89, v193
	v_fma_f32 v89, v187, v89, v191
	v_cvt_pk_bf16_f32 v92, v86, v87
	v_cvt_pk_bf16_f32 v93, v88, v89
	s_nop 1
	v_permlane16_swap_b32 v90, v92
	v_permlane16_swap_b32 v91, v93
	ds_read_b128 v[184:187], v136 offset:320
	ds_read_b128 v[188:191], v136 offset:4416
	s_waitcnt lgkmcnt(2)
	v_sub_f32_e32 v82, v82, v192
	v_mul_f32_e32 v82, v82, v193
	v_fma_f32 v82, v176, v82, v180
	v_sub_f32_e32 v83, v83, v192
	v_mul_f32_e32 v83, v83, v193
	v_fma_f32 v83, v177, v83, v181
	v_sub_f32_e32 v84, v84, v192
	v_mul_f32_e32 v84, v84, v193
	v_fma_f32 v84, v178, v84, v182
	v_sub_f32_e32 v85, v85, v192
	v_mul_f32_e32 v85, v85, v193
	v_fma_f32 v85, v179, v85, v183
	v_cvt_pk_bf16_f32 v82, v82, v83
	v_cvt_pk_bf16_f32 v83, v84, v85
	ds_read_b128 v[176:179], v136 offset:384
	ds_read_b128 v[180:183], v136 offset:4480
	s_waitcnt lgkmcnt(2)
	v_sub_f32_e32 v78, v78, v192
	v_mul_f32_e32 v78, v78, v193
	v_fma_f32 v78, v184, v78, v188
	v_sub_f32_e32 v79, v79, v192
	v_mul_f32_e32 v79, v79, v193
	v_fma_f32 v79, v185, v79, v189
	v_sub_f32_e32 v80, v80, v192
	v_mul_f32_e32 v80, v80, v193
	v_fma_f32 v80, v186, v80, v190
	v_sub_f32_e32 v81, v81, v192
	v_mul_f32_e32 v81, v81, v193
	v_fma_f32 v81, v187, v81, v191
	v_cvt_pk_bf16_f32 v84, v78, v79
	v_cvt_pk_bf16_f32 v85, v80, v81
	s_nop 1
	v_permlane16_swap_b32 v82, v84
	v_permlane16_swap_b32 v83, v85
	ds_read_b128 v[184:187], v136 offset:448
	ds_read_b128 v[188:191], v136 offset:4544
	s_waitcnt lgkmcnt(2)
	v_sub_f32_e32 v74, v74, v192
	v_mul_f32_e32 v74, v74, v193
	v_fma_f32 v74, v176, v74, v180
	v_sub_f32_e32 v75, v75, v192
	v_mul_f32_e32 v75, v75, v193
	v_fma_f32 v75, v177, v75, v181
	v_sub_f32_e32 v76, v76, v192
	v_mul_f32_e32 v76, v76, v193
	v_fma_f32 v76, v178, v76, v182
	v_sub_f32_e32 v77, v77, v192
	v_mul_f32_e32 v77, v77, v193
	v_fma_f32 v77, v179, v77, v183
	v_cvt_pk_bf16_f32 v74, v74, v75
	v_cvt_pk_bf16_f32 v75, v76, v77
	s_waitcnt lgkmcnt(0)
	v_sub_f32_e32 v70, v70, v192
	v_mul_f32_e32 v70, v70, v193
	v_fma_f32 v70, v184, v70, v188
	v_sub_f32_e32 v71, v71, v192
	v_mul_f32_e32 v71, v71, v193
	v_fma_f32 v71, v185, v71, v189
	v_sub_f32_e32 v72, v72, v192
	v_mul_f32_e32 v72, v72, v193
	v_fma_f32 v72, v186, v72, v190
	v_sub_f32_e32 v73, v73, v192
	v_mul_f32_e32 v73, v73, v193
	v_fma_f32 v73, v187, v73, v191
	v_cvt_pk_bf16_f32 v76, v70, v71
	v_cvt_pk_bf16_f32 v77, v72, v73
	s_nop 1
	v_permlane16_swap_b32 v74, v76
	v_permlane16_swap_b32 v75, v77
	s_waitcnt vmcnt(8) lgkmcnt(0)
	s_barrier
; DI float bf2f(unsigned b) { return __uint_as_float(b << 16); }
; DI void unit_O(const Params& p, char* lds, int l, int tile, int glu_tiles, int tile_b) {
;     ...
;         float s2[2], ss2[2];
; #pragma unroll
;         for (int mh = 0; mh < 2; ++mh) {
;             const int mt = half * 2 + mh, rl = mh * 16 + l15;
;             float s = 0.f, ss = 0.f;
; #pragma unroll
;             for (int nt = 0; nt < 8; ++nt) {
;                 f32x4 xr;
;                 if (l == 0) {
;                     const int chunk = wid * 32 + nt * 4 + quad;
;                     xr = *(const f32x4*)(XR + rl * 4096 + ((chunk ^ l15) << 4));
;                 } else {
;                     const u32x2 hb = *(const u32x2*)(XR + ((wid * 4 + (nt >> 1)) * 32 + rl) * 64 + (nt & 1) * 32 + quad * 8);
;                     xr = (f32x4){bf2f(hb[0] & 0xffffu), bf2f(hb[0] >> 16), bf2f(hb[1] & 0xffffu), bf2f(hb[1] >> 16)};
;                 }
; #pragma unroll
;                 for (int i = 0; i < 4; ++i) { const float v = acc[mt][nt][i] + DN_ALPHA * xr[i]; acc[mt][nt][i] = v; s += v; ss += v * v; }
;             }
;             s2[mh] = s; ss2[mh] = ss;
;         }
; #pragma unroll
;         for (int mh = 0; mh < 2; ++mh) { s2[mh] += __shfl_xor(s2[mh], 16); ss2[mh] += __shfl_xor(ss2[mh], 16); }
; #pragma unroll
;         for (int mh = 0; mh < 2; ++mh) { s2[mh] += __shfl_xor(s2[mh], 32); ss2[mh] += __shfl_xor(ss2[mh], 32); }
;         if (quad == 0) {
; #pragma unroll
;             for (int mh = 0; mh < 2; ++mh) *(f32x2*)&red[((mh * 16 + l15) * 8 + wid) * 2] = (f32x2){s2[mh], ss2[mh]};
;         }
;         __syncthreads();
;         if (half == 0) issue_x(1);
; #pragma unroll
;         for (int mh = 0; mh < 2; ++mh) {
;             const int mt = half * 2 + mh, rl = mh * 16 + l15, row = mt * 16 + l15;
;             float s = 0.f, ss = 0.f;
; #pragma unroll
;             for (int w = 0; w < 4; ++w) { const f32x4 v = *(const f32x4*)&red[rl * 16 + 4 * w]; s += v[0] + v[2]; ss += v[1] + v[3]; }
;             const float mu = s * (1.f / 1024.f);
;             const float var = ss * (1.f / 1024.f) - mu * mu;
;             const float rs = rsqrtf(var + LN_EPS);
	ds_read_b128 v[144:147], v204
	ds_read_b128 v[148:151], v205
	ds_read_b128 v[152:155], v206
	ds_read_b128 v[156:159], v207
	ds_read_b128 v[160:163], v204 offset:256
	ds_read_b128 v[164:167], v205 offset:256
	ds_read_b128 v[168:171], v206 offset:256
	ds_read_b128 v[172:175], v207 offset:256
	s_waitcnt lgkmcnt(7)
	v_fmac_f32_e32 v126, s58, v144
	v_fmac_f32_e32 v127, s58, v145
	v_fmac_f32_e32 v128, s58, v146
	v_fmac_f32_e32 v129, s58, v147
	v_mov_b32_e32 v196, v126
	v_mul_f32_e32 v197, v126, v126
	v_mov_b32_e32 v130, v127
	v_mul_f32_e32 v142, v127, v127
	v_add_f32_e32 v196, v196, v128
	v_fmac_f32_e32 v197, v128, v128
	v_add_f32_e32 v130, v130, v129
	v_fmac_f32_e32 v142, v129, v129
	s_waitcnt lgkmcnt(6)
	v_fmac_f32_e32 v122, s58, v148
	v_fmac_f32_e32 v123, s58, v149
	v_fmac_f32_e32 v124, s58, v150
	v_fmac_f32_e32 v125, s58, v151
	v_add_f32_e32 v196, v196, v122
	v_fmac_f32_e32 v197, v122, v122
	v_add_f32_e32 v130, v130, v123
	v_fmac_f32_e32 v142, v123, v123
	v_add_f32_e32 v196, v196, v124
	v_fmac_f32_e32 v197, v124, v124
	v_add_f32_e32 v130, v130, v125
	v_fmac_f32_e32 v142, v125, v125
	s_waitcnt lgkmcnt(5)
	v_fmac_f32_e32 v118, s58, v152
	v_fmac_f32_e32 v119, s58, v153
	v_fmac_f32_e32 v120, s58, v154
	v_fmac_f32_e32 v121, s58, v155
	v_add_f32_e32 v196, v196, v118
	v_fmac_f32_e32 v197, v118, v118
	v_add_f32_e32 v130, v130, v119
	v_fmac_f32_e32 v142, v119, v119
	v_add_f32_e32 v196, v196, v120
	v_fmac_f32_e32 v197, v120, v120
	v_add_f32_e32 v130, v130, v121
	v_fmac_f32_e32 v142, v121, v121
	s_waitcnt lgkmcnt(4)
	v_fmac_f32_e32 v114, s58, v156
	v_fmac_f32_e32 v115, s58, v157
	v_fmac_f32_e32 v116, s58, v158
	v_fmac_f32_e32 v117, s58, v159
	v_add_f32_e32 v196, v196, v114
	v_fmac_f32_e32 v197, v114, v114
	v_add_f32_e32 v130, v130, v115
	v_fmac_f32_e32 v142, v115, v115
	v_add_f32_e32 v196, v196, v116
	v_fmac_f32_e32 v197, v116, v116
	v_add_f32_e32 v130, v130, v117
	v_fmac_f32_e32 v142, v117, v117
	s_waitcnt lgkmcnt(3)
	v_fmac_f32_e32 v110, s58, v160
	v_fmac_f32_e32 v111, s58, v161
	v_fmac_f32_e32 v112, s58, v162
	v_fmac_f32_e32 v113, s58, v163
	v_add_f32_e32 v196, v196, v110
	v_fmac_f32_e32 v197, v110, v110
	v_add_f32_e32 v130, v130, v111
	v_fmac_f32_e32 v142, v111, v111
	v_add_f32_e32 v196, v196, v112
	v_fmac_f32_e32 v197, v112, v112
	v_add_f32_e32 v130, v130, v113
	v_fmac_f32_e32 v142, v113, v113
	s_waitcnt lgkmcnt(2)
	v_fmac_f32_e32 v106, s58, v164
	v_fmac_f32_e32 v107, s58, v165
	v_fmac_f32_e32 v108, s58, v166
	v_fmac_f32_e32 v109, s58, v167
	v_add_f32_e32 v196, v196, v106
	v_fmac_f32_e32 v197, v106, v106
	v_add_f32_e32 v130, v130, v107
	v_fmac_f32_e32 v142, v107, v107
	v_add_f32_e32 v196, v196, v108
	v_fmac_f32_e32 v197, v108, v108
	v_add_f32_e32 v130, v130, v109
	v_fmac_f32_e32 v142, v109, v109
	s_waitcnt lgkmcnt(1)
	v_fmac_f32_e32 v102, s58, v168
	v_fmac_f32_e32 v103, s58, v169
	v_fmac_f32_e32 v104, s58, v170
	v_fmac_f32_e32 v105, s58, v171
	v_add_f32_e32 v196, v196, v102
	v_fmac_f32_e32 v197, v102, v102
	v_add_f32_e32 v130, v130, v103
	v_fmac_f32_e32 v142, v103, v103
	v_add_f32_e32 v196, v196, v104
	v_fmac_f32_e32 v197, v104, v104
	v_add_f32_e32 v130, v130, v105
	v_fmac_f32_e32 v142, v105, v105
	s_waitcnt lgkmcnt(0)
	v_fmac_f32_e32 v66, s58, v172
	v_fmac_f32_e32 v67, s58, v173
	v_fmac_f32_e32 v68, s58, v174
	v_fmac_f32_e32 v69, s58, v175
	v_add_f32_e32 v196, v196, v66
	v_fmac_f32_e32 v197, v66, v66
	v_add_f32_e32 v130, v130, v67
	v_fmac_f32_e32 v142, v67, v67
	v_add_f32_e32 v196, v196, v68
	v_fmac_f32_e32 v197, v68, v68
	v_add_f32_e32 v130, v130, v69
	v_fmac_f32_e32 v142, v69, v69
	v_add_f32_e32 v196, v196, v130
	v_add_f32_e32 v197, v197, v142
	v_mov_b32_e32 v198, v196
	v_mov_b32_e32 v199, v197
	s_nop 1
	v_permlane16_swap_b32 v198, v196
	v_permlane16_swap_b32 v199, v197
	v_add_f32_e32 v196, v196, v198
	v_add_f32_e32 v197, v197, v199
	v_mov_b32_e32 v198, v196
	v_mov_b32_e32 v199, v197
	s_nop 1
	v_permlane32_swap_b32 v198, v196
	v_permlane32_swap_b32 v199, v197
	v_add_f32_e32 v196, v196, v198
	v_add_f32_e32 v197, v197, v199
	s_mov_b64 exec, 0xffff
	ds_write_b64 v134, v[196:197]
	s_mov_b64 exec, -1
	s_waitcnt lgkmcnt(0)
	s_barrier
	s_add_u32 s92, s96, 0x30000
	s_addc_u32 s93, s97, 0
	s_add_u32 s40, s91, 0x10000
	s_mov_b32 m0, s40
	s_nop 0
	global_load_lds_dwordx4 v208, s[92:93]
	global_load_lds_dwordx4 v208, s[92:93] offset:1024
	global_load_lds_dwordx4 v208, s[92:93] offset:2048
	global_load_lds_dwordx4 v208, s[92:93] offset:3072
	s_add_u32 s92, s96, 0x31000
	s_addc_u32 s93, s97, 0
	s_add_u32 s40, s91, 0x11000
	s_mov_b32 m0, s40
	s_nop 0
	global_load_lds_dwordx4 v209, s[92:93]
	global_load_lds_dwordx4 v209, s[92:93] offset:1024
	global_load_lds_dwordx4 v209, s[92:93] offset:2048
	global_load_lds_dwordx4 v209, s[92:93] offset:3072
	ds_read_b128 v[160:163], v135 offset:0
	ds_read_b128 v[164:167], v135 offset:16
	ds_read_b128 v[168:171], v135 offset:32
	ds_read_b128 v[172:175], v135 offset:48
	s_waitcnt lgkmcnt(0)
	v_add_f32_e32 v160, v160, v162
	v_add_f32_e32 v161, v161, v163
	v_add_f32_e32 v164, v164, v166
	v_add_f32_e32 v165, v165, v167
	v_add_f32_e32 v168, v168, v170
	v_add_f32_e32 v169, v169, v171
	v_add_f32_e32 v172, v172, v174
	v_add_f32_e32 v173, v173, v175
	v_add_f32_e32 v160, v160, v164
	v_add_f32_e32 v161, v161, v165
	v_add_f32_e32 v168, v168, v172
	v_add_f32_e32 v169, v169, v173
	v_add_f32_e32 v160, v160, v168
	v_add_f32_e32 v161, v161, v169
	v_mul_f32_e32 v192, 0x3a800000, v160
	v_mul_f32_e32 v193, 0x3a800000, v161
	v_fma_f32 v193, -v192, v192, v193
	v_add_f32_e32 v193, 0x3727c5ac, v193
	v_rsq_f32_e32 v193, v193
	s_nop 0
	ds_read_b128 v[176:179], v136
	ds_read_b128 v[180:183], v136 offset:4096
	ds_read_b128 v[184:187], v136 offset:64
	ds_read_b128 v[188:191], v136 offset:4160
	s_waitcnt lgkmcnt(2)
; DI unsigned pk2(float lo, float hi) { const f32x2 v = {lo, hi}; const bf16x2_t b = __builtin_convertvector(v, bf16x2_t); return __builtin_bit_cast(unsigned, b); }
; DI size_t xb_off(int tok, int col) { return ((size_t)(((tok >> 7) * 32 + (col >> 5)) * 128 + (tok & 127))) * 32 + (col & 31); }
; DI void unit_O(const Params& p, char* lds, int l, int tile, int glu_tiles, int tile_b) {
;     ...
;             float* orow = xo + (r0 + row) * 1024 + wid * 128 + quad * 4;
;             bf16_t* brow = xbo + xb_off((int)r0 + row, wid * 128) + quad * 4;
;             const float* gp = GB + wid * 128 + quad * 4;
; #pragma unroll
;             for (int nt = 0; nt < 8; ++nt) {
;                 const f32x4 g = *(const f32x4*)(gp + nt * 16), bb = *(const f32x4*)(gp + 1024 + nt * 16);
;                 f32x4 o;
; #pragma unroll
;                 for (int i = 0; i < 4; ++i) o[i] = (acc[mt][nt][i] - mu) * rs * g[i] + bb[i];
;                 if (l == 0) *(u32x2*)(brow + (nt >> 1) * 4096 + (nt & 1) * 16) = (u32x2){pk2(o[0], o[1]), pk2(o[2], o[3])};
	v_sub_f32_e32 v126, v126, v192
	v_mul_f32_e32 v126, v126, v193
	v_fma_f32 v126, v176, v126, v180
	v_sub_f32_e32 v127, v127, v192
	v_mul_f32_e32 v127, v127, v193
	v_fma_f32 v127, v177, v127, v181
	v_sub_f32_e32 v128, v128, v192
	v_mul_f32_e32 v128, v128, v193
	v_fma_f32 v128, v178, v128, v182
	v_sub_f32_e32 v129, v129, v192
	v_mul_f32_e32 v129, v129, v193
	v_fma_f32 v129, v179, v129, v183
	v_cvt_pk_bf16_f32 v126, v126, v127
	v_cvt_pk_bf16_f32 v127, v128, v129
	ds_read_b128 v[176:179], v136 offset:128
	ds_read_b128 v[180:183], v136 offset:4224
	s_waitcnt lgkmcnt(2)
	v_sub_f32_e32 v122, v122, v192
	v_mul_f32_e32 v122, v122, v193
	v_fma_f32 v122, v184, v122, v188
	v_sub_f32_e32 v123, v123, v192
	v_mul_f32_e32 v123, v123, v193
	v_fma_f32 v123, v185, v123, v189
	v_sub_f32_e32 v124, v124, v192
	v_mul_f32_e32 v124, v124, v193
	v_fma_f32 v124, v186, v124, v190
	v_sub_f32_e32 v125, v125, v192
	v_mul_f32_e32 v125, v125, v193
	v_fma_f32 v125, v187, v125, v191
	v_cvt_pk_bf16_f32 v128, v122, v123
	v_cvt_pk_bf16_f32 v129, v124, v125
	s_nop 1
	v_permlane16_swap_b32 v126, v128
	v_permlane16_swap_b32 v127, v129
	ds_read_b128 v[184:187], v136 offset:192
	ds_read_b128 v[188:191], v136 offset:4288
	s_waitcnt lgkmcnt(2)
	v_sub_f32_e32 v118, v118, v192
	v_mul_f32_e32 v118, v118, v193
	v_fma_f32 v118, v176, v118, v180
	v_sub_f32_e32 v119, v119, v192
	v_mul_f32_e32 v119, v119, v193
	v_fma_f32 v119, v177, v119, v181
	v_sub_f32_e32 v120, v120, v192
	v_mul_f32_e32 v120, v120, v193
	v_fma_f32 v120, v178, v120, v182
	v_sub_f32_e32 v121, v121, v192
	v_mul_f32_e32 v121, v121, v193
	v_fma_f32 v121, v179, v121, v183
	v_cvt_pk_bf16_f32 v118, v118, v119
	v_cvt_pk_bf16_f32 v119, v120, v121
	ds_read_b128 v[176:179], v136 offset:256
	ds_read_b128 v[180:183], v136 offset:4352
	s_waitcnt lgkmcnt(2)
	v_sub_f32_e32 v114, v114, v192
	v_mul_f32_e32 v114, v114, v193
	v_fma_f32 v114, v184, v114, v188
	v_sub_f32_e32 v115, v115, v192
	v_mul_f32_e32 v115, v115, v193
	v_fma_f32 v115, v185, v115, v189
	v_sub_f32_e32 v116, v116, v192
	v_mul_f32_e32 v116, v116, v193
	v_fma_f32 v116, v186, v116, v190
	v_sub_f32_e32 v117, v117, v192
	v_mul_f32_e32 v117, v117, v193
	v_fma_f32 v117, v187, v117, v191
	v_cvt_pk_bf16_f32 v120, v114, v115
	v_cvt_pk_bf16_f32 v121, v116, v117
	s_nop 1
	v_permlane16_swap_b32 v118, v120
	v_permlane16_swap_b32 v119, v121
	ds_read_b128 v[184:187], v136 offset:320
	ds_read_b128 v[188:191], v136 offset:4416
	s_waitcnt lgkmcnt(2)
	v_sub_f32_e32 v110, v110, v192
	v_mul_f32_e32 v110, v110, v193
	v_fma_f32 v110, v176, v110, v180
	v_sub_f32_e32 v111, v111, v192
	v_mul_f32_e32 v111, v111, v193
	v_fma_f32 v111, v177, v111, v181
	v_sub_f32_e32 v112, v112, v192
	v_mul_f32_e32 v112, v112, v193
	v_fma_f32 v112, v178, v112, v182
	v_sub_f32_e32 v113, v113, v192
	v_mul_f32_e32 v113, v113, v193
	v_fma_f32 v113, v179, v113, v183
	v_cvt_pk_bf16_f32 v110, v110, v111
	v_cvt_pk_bf16_f32 v111, v112, v113
	ds_read_b128 v[176:179], v136 offset:384
	ds_read_b128 v[180:183], v136 offset:4480
	s_waitcnt lgkmcnt(2)
	v_sub_f32_e32 v106, v106, v192
	v_mul_f32_e32 v106, v106, v193
	v_fma_f32 v106, v184, v106, v188
	v_sub_f32_e32 v107, v107, v192
	v_mul_f32_e32 v107, v107, v193
	v_fma_f32 v107, v185, v107, v189
	v_sub_f32_e32 v108, v108, v192
	v_mul_f32_e32 v108, v108, v193
	v_fma_f32 v108, v186, v108, v190
	v_sub_f32_e32 v109, v109, v192
	v_mul_f32_e32 v109, v109, v193
	v_fma_f32 v109, v187, v109, v191
	v_cvt_pk_bf16_f32 v112, v106, v107
	v_cvt_pk_bf16_f32 v113, v108, v109
	s_nop 1
	v_permlane16_swap_b32 v110, v112
	v_permlane16_swap_b32 v111, v113
	ds_read_b128 v[184:187], v136 offset:448
	ds_read_b128 v[188:191], v136 offset:4544
	s_waitcnt lgkmcnt(2)
	v_sub_f32_e32 v102, v102, v192
	v_mul_f32_e32 v102, v102, v193
	v_fma_f32 v102, v176, v102, v180
	v_sub_f32_e32 v103, v103, v192
	v_mul_f32_e32 v103, v103, v193
	v_fma_f32 v103, v177, v103, v181
	v_sub_f32_e32 v104, v104, v192
	v_mul_f32_e32 v104, v104, v193
	v_fma_f32 v104, v178, v104, v182
	v_sub_f32_e32 v105, v105, v192
	v_mul_f32_e32 v105, v105, v193
	v_fma_f32 v105, v179, v105, v183
	v_cvt_pk_bf16_f32 v102, v102, v103
	v_cvt_pk_bf16_f32 v103, v104, v105
	s_waitcnt lgkmcnt(0)
	v_sub_f32_e32 v66, v66, v192
	v_mul_f32_e32 v66, v66, v193
	v_fma_f32 v66, v184, v66, v188
	v_sub_f32_e32 v67, v67, v192
	v_mul_f32_e32 v67, v67, v193
	v_fma_f32 v67, v185, v67, v189
	v_sub_f32_e32 v68, v68, v192
	v_mul_f32_e32 v68, v68, v193
	v_fma_f32 v68, v186, v68, v190
	v_sub_f32_e32 v69, v69, v192
	v_mul_f32_e32 v69, v69, v193
	v_fma_f32 v69, v187, v69, v191
	v_cvt_pk_bf16_f32 v104, v66, v67
	v_cvt_pk_bf16_f32 v105, v68, v69
	s_nop 1
	v_permlane16_swap_b32 v102, v104
	v_permlane16_swap_b32 v103, v105
	s_waitcnt vmcnt(8) lgkmcnt(0)
	s_barrier
; DI void unit_O(const Params& p, char* lds, int l, int tile, int glu_tiles, int tile_b) {
;     ...
;         float s2[2], ss2[2];
; #pragma unroll
;         for (int mh = 0; mh < 2; ++mh) {
;             const int mt = half * 2 + mh, rl = mh * 16 + l15;
;             float s = 0.f, ss = 0.f;
; #pragma unroll
;             for (int nt = 0; nt < 8; ++nt) {
;                 f32x4 xr;
;                 if (l == 0) {
;                     const int chunk = wid * 32 + nt * 4 + quad;
;                     xr = *(const f32x4*)(XR + rl * 4096 + ((chunk ^ l15) << 4));
;                 } else {
;                     const u32x2 hb = *(const u32x2*)(XR + ((wid * 4 + (nt >> 1)) * 32 + rl) * 64 + (nt & 1) * 32 + quad * 8);
;                     xr = (f32x4){bf2f(hb[0] & 0xffffu), bf2f(hb[0] >> 16), bf2f(hb[1] & 0xffffu), bf2f(hb[1] >> 16)};
;                 }
; #pragma unroll
;                 for (int i = 0; i < 4; ++i) { const float v = acc[mt][nt][i] + DN_ALPHA * xr[i]; acc[mt][nt][i] = v; s += v; ss += v * v; }
;             }
;             s2[mh] = s; ss2[mh] = ss;
;         }
; #pragma unroll
;         for (int mh = 0; mh < 2; ++mh) { s2[mh] += __shfl_xor(s2[mh], 16); ss2[mh] += __shfl_xor(ss2[mh], 16); }
; #pragma unroll
;         for (int mh = 0; mh < 2; ++mh) { s2[mh] += __shfl_xor(s2[mh], 32); ss2[mh] += __shfl_xor(ss2[mh], 32); }
;         if (quad == 0) {
; #pragma unroll
;             for (int mh = 0; mh < 2; ++mh) *(f32x2*)&red[((mh * 16 + l15) * 8 + wid) * 2] = (f32x2){s2[mh], ss2[mh]};
;         }
;         __syncthreads();
;         if (half == 0) issue_x(1);
; #pragma unroll
;         for (int mh = 0; mh < 2; ++mh) {
;             const int mt = half * 2 + mh, rl = mh * 16 + l15, row = mt * 16 + l15;
;             float s = 0.f, ss = 0.f;
; #pragma unroll
;             for (int w = 0; w < 4; ++w) { const f32x4 v = *(const f32x4*)&red[rl * 16 + 4 * w]; s += v[0] + v[2]; ss += v[1] + v[3]; }
;             const float mu = s * (1.f / 1024.f);
;             const float var = ss * (1.f / 1024.f) - mu * mu;
;             const float rs = rsqrtf(var + LN_EPS);
;             float* orow = xo + (r0 + row) * 1024 + wid * 128 + quad * 4;
;             bf16_t* brow = xbo + xb_off((int)r0 + row, wid * 128) + quad * 4;
;             const float* gp = GB + wid * 128 + quad * 4;
; #pragma unroll
;             for (int nt = 0; nt < 8; ++nt) {
	ds_read_b128 v[144:147], v200
	ds_read_b128 v[148:151], v201
	ds_read_b128 v[152:155], v202
	ds_read_b128 v[156:159], v203
	ds_read_b128 v[160:163], v200 offset:256
	ds_read_b128 v[164:167], v201 offset:256
	ds_read_b128 v[168:171], v202 offset:256
	ds_read_b128 v[172:175], v203 offset:256
	s_waitcnt lgkmcnt(7)
	v_fmac_f32_e32 v34, s58, v144
	v_fmac_f32_e32 v35, s58, v145
	v_fmac_f32_e32 v36, s58, v146
	v_fmac_f32_e32 v37, s58, v147
	v_mov_b32_e32 v196, v34
	v_mul_f32_e32 v197, v34, v34
	v_mov_b32_e32 v130, v35
	v_mul_f32_e32 v142, v35, v35
	v_add_f32_e32 v196, v196, v36
	v_fmac_f32_e32 v197, v36, v36
	v_add_f32_e32 v130, v130, v37
	v_fmac_f32_e32 v142, v37, v37
	s_waitcnt lgkmcnt(6)
	v_fmac_f32_e32 v30, s58, v148
	v_fmac_f32_e32 v31, s58, v149
	v_fmac_f32_e32 v32, s58, v150
	v_fmac_f32_e32 v33, s58, v151
	v_add_f32_e32 v196, v196, v30
	v_fmac_f32_e32 v197, v30, v30
	v_add_f32_e32 v130, v130, v31
	v_fmac_f32_e32 v142, v31, v31
	v_add_f32_e32 v196, v196, v32
	v_fmac_f32_e32 v197, v32, v32
	v_add_f32_e32 v130, v130, v33
	v_fmac_f32_e32 v142, v33, v33
	s_waitcnt lgkmcnt(5)
	v_fmac_f32_e32 v26, s58, v152
	v_fmac_f32_e32 v27, s58, v153
	v_fmac_f32_e32 v28, s58, v154
	v_fmac_f32_e32 v29, s58, v155
	v_add_f32_e32 v196, v196, v26
	v_fmac_f32_e32 v197, v26, v26
	v_add_f32_e32 v130, v130, v27
	v_fmac_f32_e32 v142, v27, v27
	v_add_f32_e32 v196, v196, v28
	v_fmac_f32_e32 v197, v28, v28
	v_add_f32_e32 v130, v130, v29
	v_fmac_f32_e32 v142, v29, v29
	s_waitcnt lgkmcnt(4)
	v_fmac_f32_e32 v22, s58, v156
	v_fmac_f32_e32 v23, s58, v157
	v_fmac_f32_e32 v24, s58, v158
	v_fmac_f32_e32 v25, s58, v159
	v_add_f32_e32 v196, v196, v22
	v_fmac_f32_e32 v197, v22, v22
	v_add_f32_e32 v130, v130, v23
	v_fmac_f32_e32 v142, v23, v23
	v_add_f32_e32 v196, v196, v24
	v_fmac_f32_e32 v197, v24, v24
	v_add_f32_e32 v130, v130, v25
	v_fmac_f32_e32 v142, v25, v25
	s_waitcnt lgkmcnt(3)
	v_fmac_f32_e32 v18, s58, v160
	v_fmac_f32_e32 v19, s58, v161
	v_fmac_f32_e32 v20, s58, v162
	v_fmac_f32_e32 v21, s58, v163
	v_add_f32_e32 v196, v196, v18
	v_fmac_f32_e32 v197, v18, v18
	v_add_f32_e32 v130, v130, v19
	v_fmac_f32_e32 v142, v19, v19
	v_add_f32_e32 v196, v196, v20
	v_fmac_f32_e32 v197, v20, v20
	v_add_f32_e32 v130, v130, v21
	v_fmac_f32_e32 v142, v21, v21
	s_waitcnt lgkmcnt(2)
	v_fmac_f32_e32 v14, s58, v164
	v_fmac_f32_e32 v15, s58, v165
	v_fmac_f32_e32 v16, s58, v166
	v_fmac_f32_e32 v17, s58, v167
	v_add_f32_e32 v196, v196, v14
	v_fmac_f32_e32 v197, v14, v14
	v_add_f32_e32 v130, v130, v15
	v_fmac_f32_e32 v142, v15, v15
	v_add_f32_e32 v196, v196, v16
	v_fmac_f32_e32 v197, v16, v16
	v_add_f32_e32 v130, v130, v17
	v_fmac_f32_e32 v142, v17, v17
	s_waitcnt lgkmcnt(1)
	v_fmac_f32_e32 v10, s58, v168
	v_fmac_f32_e32 v11, s58, v169
	v_fmac_f32_e32 v12, s58, v170
	v_fmac_f32_e32 v13, s58, v171
	v_add_f32_e32 v196, v196, v10
	v_fmac_f32_e32 v197, v10, v10
	v_add_f32_e32 v130, v130, v11
	v_fmac_f32_e32 v142, v11, v11
	v_add_f32_e32 v196, v196, v12
	v_fmac_f32_e32 v197, v12, v12
	v_add_f32_e32 v130, v130, v13
	v_fmac_f32_e32 v142, v13, v13
	s_waitcnt lgkmcnt(0)
	v_fmac_f32_e32 v6, s58, v172
	v_fmac_f32_e32 v7, s58, v173
	v_fmac_f32_e32 v8, s58, v174
	v_fmac_f32_e32 v9, s58, v175
	v_add_f32_e32 v196, v196, v6
	v_fmac_f32_e32 v197, v6, v6
	v_add_f32_e32 v130, v130, v7
	v_fmac_f32_e32 v142, v7, v7
	v_add_f32_e32 v196, v196, v8
	v_fmac_f32_e32 v197, v8, v8
	v_add_f32_e32 v130, v130, v9
	v_fmac_f32_e32 v142, v9, v9
	v_add_f32_e32 v196, v196, v130
	v_add_f32_e32 v197, v197, v142
	v_mov_b32_e32 v198, v196
	v_mov_b32_e32 v199, v197
	s_nop 1
	v_permlane16_swap_b32 v198, v196
	v_permlane16_swap_b32 v199, v197
	v_add_f32_e32 v196, v196, v198
	v_add_f32_e32 v197, v197, v199
	v_mov_b32_e32 v198, v196
	v_mov_b32_e32 v199, v197
	s_nop 1
	v_permlane32_swap_b32 v198, v196
	v_permlane32_swap_b32 v199, v197
	v_add_f32_e32 v196, v196, v198
	v_add_f32_e32 v197, v197, v199
	s_mov_b64 exec, 0xffff
	ds_write_b64 v134, v[196:197]
	s_mov_b64 exec, -1
	s_waitcnt lgkmcnt(0)
	s_barrier
	ds_read_b128 v[160:163], v135 offset:0
	ds_read_b128 v[164:167], v135 offset:16
	ds_read_b128 v[168:171], v135 offset:32
	ds_read_b128 v[172:175], v135 offset:48
	s_waitcnt lgkmcnt(0)
	v_add_f32_e32 v160, v160, v162
	v_add_f32_e32 v161, v161, v163
	v_add_f32_e32 v164, v164, v166
	v_add_f32_e32 v165, v165, v167
	v_add_f32_e32 v168, v168, v170
	v_add_f32_e32 v169, v169, v171
	v_add_f32_e32 v172, v172, v174
	v_add_f32_e32 v173, v173, v175
	v_add_f32_e32 v160, v160, v164
	v_add_f32_e32 v161, v161, v165
	v_add_f32_e32 v168, v168, v172
	v_add_f32_e32 v169, v169, v173
	v_add_f32_e32 v160, v160, v168
	v_add_f32_e32 v161, v161, v169
	v_mul_f32_e32 v192, 0x3a800000, v160
	v_mul_f32_e32 v193, 0x3a800000, v161
	v_fma_f32 v193, -v192, v192, v193
	v_add_f32_e32 v193, 0x3727c5ac, v193
	v_rsq_f32_e32 v193, v193
	s_nop 0
	ds_read_b128 v[176:179], v136
	ds_read_b128 v[180:183], v136 offset:4096
	ds_read_b128 v[184:187], v136 offset:64
	ds_read_b128 v[188:191], v136 offset:4160
	s_waitcnt lgkmcnt(2)
	v_sub_f32_e32 v34, v34, v192
	v_mul_f32_e32 v34, v34, v193
	v_fma_f32 v34, v176, v34, v180
	v_sub_f32_e32 v35, v35, v192
	v_mul_f32_e32 v35, v35, v193
	v_fma_f32 v35, v177, v35, v181
	v_sub_f32_e32 v36, v36, v192
	v_mul_f32_e32 v36, v36, v193
	v_fma_f32 v36, v178, v36, v182
	v_sub_f32_e32 v37, v37, v192
	v_mul_f32_e32 v37, v37, v193
	v_fma_f32 v37, v179, v37, v183
	v_cvt_pk_bf16_f32 v34, v34, v35
	v_cvt_pk_bf16_f32 v35, v36, v37
	ds_read_b128 v[176:179], v136 offset:128
	ds_read_b128 v[180:183], v136 offset:4224
	s_waitcnt lgkmcnt(2)
; DI unsigned pk2(float lo, float hi) { const f32x2 v = {lo, hi}; const bf16x2_t b = __builtin_convertvector(v, bf16x2_t); return __builtin_bit_cast(unsigned, b); }
; DI float bf2f(unsigned b) { return __uint_as_float(b << 16); }
; DI size_t xb_off(int tok, int col) { return ((size_t)(((tok >> 7) * 32 + (col >> 5)) * 128 + (tok & 127))) * 32 + (col & 31); }
; DI void unit_O(const Params& p, char* lds, int l, int tile, int glu_tiles, int tile_b) {
;     ...
;         float s2[2], ss2[2];
; #pragma unroll
;         for (int mh = 0; mh < 2; ++mh) {
;             const int mt = half * 2 + mh, rl = mh * 16 + l15;
;             float s = 0.f, ss = 0.f;
; #pragma unroll
;             for (int nt = 0; nt < 8; ++nt) {
;                 f32x4 xr;
;                 if (l == 0) {
;                     const int chunk = wid * 32 + nt * 4 + quad;
;                     xr = *(const f32x4*)(XR + rl * 4096 + ((chunk ^ l15) << 4));
;                 } else {
;                     const u32x2 hb = *(const u32x2*)(XR + ((wid * 4 + (nt >> 1)) * 32 + rl) * 64 + (nt & 1) * 32 + quad * 8);
;                     xr = (f32x4){bf2f(hb[0] & 0xffffu), bf2f(hb[0] >> 16), bf2f(hb[1] & 0xffffu), bf2f(hb[1] >> 16)};
;                 }
; #pragma unroll
;                 for (int i = 0; i < 4; ++i) { const float v = acc[mt][nt][i] + DN_ALPHA * xr[i]; acc[mt][nt][i] = v; s += v; ss += v * v; }
;             }
;             s2[mh] = s; ss2[mh] = ss;
;         }
;     ...
;             float* orow = xo + (r0 + row) * 1024 + wid * 128 + quad * 4;
;             bf16_t* brow = xbo + xb_off((int)r0 + row, wid * 128) + quad * 4;
;             const float* gp = GB + wid * 128 + quad * 4;
; #pragma unroll
;             for (int nt = 0; nt < 8; ++nt) {
;                 const f32x4 g = *(const f32x4*)(gp + nt * 16), bb = *(const f32x4*)(gp + 1024 + nt * 16);
;                 f32x4 o;
; #pragma unroll
;                 for (int i = 0; i < 4; ++i) o[i] = (acc[mt][nt][i] - mu) * rs * g[i] + bb[i];
;                 if (l == 0) *(u32x2*)(brow + (nt >> 1) * 4096 + (nt & 1) * 16) = (u32x2){pk2(o[0], o[1]), pk2(o[2], o[3])};
	v_sub_f32_e32 v30, v30, v192
	v_mul_f32_e32 v30, v30, v193
	v_fma_f32 v30, v184, v30, v188
	v_sub_f32_e32 v31, v31, v192
	v_mul_f32_e32 v31, v31, v193
	v_fma_f32 v31, v185, v31, v189
	v_sub_f32_e32 v32, v32, v192
	v_mul_f32_e32 v32, v32, v193
	v_fma_f32 v32, v186, v32, v190
	v_sub_f32_e32 v33, v33, v192
	v_mul_f32_e32 v33, v33, v193
	v_fma_f32 v33, v187, v33, v191
	v_cvt_pk_bf16_f32 v36, v30, v31
	v_cvt_pk_bf16_f32 v37, v32, v33
	s_nop 1
	v_permlane16_swap_b32 v34, v36
	v_permlane16_swap_b32 v35, v37
	ds_read_b128 v[184:187], v136 offset:192
	ds_read_b128 v[188:191], v136 offset:4288
	s_waitcnt lgkmcnt(2)
	v_sub_f32_e32 v26, v26, v192
	v_mul_f32_e32 v26, v26, v193
	v_fma_f32 v26, v176, v26, v180
	v_sub_f32_e32 v27, v27, v192
	v_mul_f32_e32 v27, v27, v193
	v_fma_f32 v27, v177, v27, v181
	v_sub_f32_e32 v28, v28, v192
	v_mul_f32_e32 v28, v28, v193
	v_fma_f32 v28, v178, v28, v182
	v_sub_f32_e32 v29, v29, v192
	v_mul_f32_e32 v29, v29, v193
	v_fma_f32 v29, v179, v29, v183
	v_cvt_pk_bf16_f32 v26, v26, v27
	v_cvt_pk_bf16_f32 v27, v28, v29
	ds_read_b128 v[176:179], v136 offset:256
	ds_read_b128 v[180:183], v136 offset:4352
	s_waitcnt lgkmcnt(2)
	v_sub_f32_e32 v22, v22, v192
	v_mul_f32_e32 v22, v22, v193
	v_fma_f32 v22, v184, v22, v188
	v_sub_f32_e32 v23, v23, v192
	v_mul_f32_e32 v23, v23, v193
	v_fma_f32 v23, v185, v23, v189
	v_sub_f32_e32 v24, v24, v192
	v_mul_f32_e32 v24, v24, v193
	v_fma_f32 v24, v186, v24, v190
	v_sub_f32_e32 v25, v25, v192
	v_mul_f32_e32 v25, v25, v193
	v_fma_f32 v25, v187, v25, v191
	v_cvt_pk_bf16_f32 v28, v22, v23
	v_cvt_pk_bf16_f32 v29, v24, v25
	s_nop 1
	v_permlane16_swap_b32 v26, v28
	v_permlane16_swap_b32 v27, v29
	ds_read_b128 v[184:187], v136 offset:320
	ds_read_b128 v[188:191], v136 offset:4416
	s_waitcnt lgkmcnt(2)
	v_sub_f32_e32 v18, v18, v192
	v_mul_f32_e32 v18, v18, v193
	v_fma_f32 v18, v176, v18, v180
	v_sub_f32_e32 v19, v19, v192
	v_mul_f32_e32 v19, v19, v193
	v_fma_f32 v19, v177, v19, v181
	v_sub_f32_e32 v20, v20, v192
	v_mul_f32_e32 v20, v20, v193
	v_fma_f32 v20, v178, v20, v182
	v_sub_f32_e32 v21, v21, v192
	v_mul_f32_e32 v21, v21, v193
	v_fma_f32 v21, v179, v21, v183
	v_cvt_pk_bf16_f32 v18, v18, v19
	v_cvt_pk_bf16_f32 v19, v20, v21
	ds_read_b128 v[176:179], v136 offset:384
	ds_read_b128 v[180:183], v136 offset:4480
	s_waitcnt lgkmcnt(2)
	v_sub_f32_e32 v14, v14, v192
	v_mul_f32_e32 v14, v14, v193
	v_fma_f32 v14, v184, v14, v188
	v_sub_f32_e32 v15, v15, v192
	v_mul_f32_e32 v15, v15, v193
	v_fma_f32 v15, v185, v15, v189
	v_sub_f32_e32 v16, v16, v192
	v_mul_f32_e32 v16, v16, v193
	v_fma_f32 v16, v186, v16, v190
	v_sub_f32_e32 v17, v17, v192
	v_mul_f32_e32 v17, v17, v193
	v_fma_f32 v17, v187, v17, v191
	v_cvt_pk_bf16_f32 v20, v14, v15
	v_cvt_pk_bf16_f32 v21, v16, v17
	s_nop 1
	v_permlane16_swap_b32 v18, v20
	v_permlane16_swap_b32 v19, v21
	ds_read_b128 v[184:187], v136 offset:448
	ds_read_b128 v[188:191], v136 offset:4544
	s_waitcnt lgkmcnt(2)
	v_sub_f32_e32 v10, v10, v192
	v_mul_f32_e32 v10, v10, v193
	v_fma_f32 v10, v176, v10, v180
	v_sub_f32_e32 v11, v11, v192
	v_mul_f32_e32 v11, v11, v193
	v_fma_f32 v11, v177, v11, v181
	v_sub_f32_e32 v12, v12, v192
	v_mul_f32_e32 v12, v12, v193
	v_fma_f32 v12, v178, v12, v182
	v_sub_f32_e32 v13, v13, v192
	v_mul_f32_e32 v13, v13, v193
	v_fma_f32 v13, v179, v13, v183
	v_cvt_pk_bf16_f32 v10, v10, v11
	v_cvt_pk_bf16_f32 v11, v12, v13
	s_waitcnt lgkmcnt(0)
	v_sub_f32_e32 v6, v6, v192
	v_mul_f32_e32 v6, v6, v193
	v_fma_f32 v6, v184, v6, v188
	v_sub_f32_e32 v7, v7, v192
	v_mul_f32_e32 v7, v7, v193
	v_fma_f32 v7, v185, v7, v189
	v_sub_f32_e32 v8, v8, v192
	v_mul_f32_e32 v8, v8, v193
	v_fma_f32 v8, v186, v8, v190
	v_sub_f32_e32 v9, v9, v192
	v_mul_f32_e32 v9, v9, v193
	v_fma_f32 v9, v187, v9, v191
	v_cvt_pk_bf16_f32 v12, v6, v7
	v_cvt_pk_bf16_f32 v13, v8, v9
	s_nop 1
	v_permlane16_swap_b32 v10, v12
	v_permlane16_swap_b32 v11, v13
	s_waitcnt vmcnt(0) lgkmcnt(0)
	s_barrier
	ds_read_b128 v[144:147], v204
	ds_read_b128 v[148:151], v205
	ds_read_b128 v[152:155], v206
	ds_read_b128 v[156:159], v207
	ds_read_b128 v[160:163], v204 offset:256
	ds_read_b128 v[164:167], v205 offset:256
	ds_read_b128 v[168:171], v206 offset:256
	ds_read_b128 v[172:175], v207 offset:256
	s_waitcnt lgkmcnt(7)
	v_fmac_f32_e32 v62, s58, v144
	v_fmac_f32_e32 v63, s58, v145
	v_fmac_f32_e32 v64, s58, v146
	v_fmac_f32_e32 v65, s58, v147
	v_mov_b32_e32 v196, v62
	v_mul_f32_e32 v197, v62, v62
	v_mov_b32_e32 v130, v63
	v_mul_f32_e32 v142, v63, v63
	v_add_f32_e32 v196, v196, v64
	v_fmac_f32_e32 v197, v64, v64
	v_add_f32_e32 v130, v130, v65
	v_fmac_f32_e32 v142, v65, v65
	s_waitcnt lgkmcnt(6)
	v_fmac_f32_e32 v58, s58, v148
	v_fmac_f32_e32 v59, s58, v149
	v_fmac_f32_e32 v60, s58, v150
	v_fmac_f32_e32 v61, s58, v151
	v_add_f32_e32 v196, v196, v58
	v_fmac_f32_e32 v197, v58, v58
	v_add_f32_e32 v130, v130, v59
	v_fmac_f32_e32 v142, v59, v59
	v_add_f32_e32 v196, v196, v60
	v_fmac_f32_e32 v197, v60, v60
	v_add_f32_e32 v130, v130, v61
	v_fmac_f32_e32 v142, v61, v61
	s_waitcnt lgkmcnt(5)
	v_fmac_f32_e32 v54, s58, v152
	v_fmac_f32_e32 v55, s58, v153
	v_fmac_f32_e32 v56, s58, v154
	v_fmac_f32_e32 v57, s58, v155
	v_add_f32_e32 v196, v196, v54
	v_fmac_f32_e32 v197, v54, v54
	v_add_f32_e32 v130, v130, v55
	v_fmac_f32_e32 v142, v55, v55
	v_add_f32_e32 v196, v196, v56
	v_fmac_f32_e32 v197, v56, v56
	v_add_f32_e32 v130, v130, v57
	v_fmac_f32_e32 v142, v57, v57
	s_waitcnt lgkmcnt(4)
	v_fmac_f32_e32 v50, s58, v156
	v_fmac_f32_e32 v51, s58, v157
	v_fmac_f32_e32 v52, s58, v158
	v_fmac_f32_e32 v53, s58, v159
	v_add_f32_e32 v196, v196, v50
	v_fmac_f32_e32 v197, v50, v50
	v_add_f32_e32 v130, v130, v51
	v_fmac_f32_e32 v142, v51, v51
	v_add_f32_e32 v196, v196, v52
	v_fmac_f32_e32 v197, v52, v52
	v_add_f32_e32 v130, v130, v53
	v_fmac_f32_e32 v142, v53, v53
	s_waitcnt lgkmcnt(3)
; DI void unit_O(const Params& p, char* lds, int l, int tile, int glu_tiles, int tile_b) {
;     ...
;         float s2[2], ss2[2];
; #pragma unroll
;         for (int mh = 0; mh < 2; ++mh) {
;             const int mt = half * 2 + mh, rl = mh * 16 + l15;
;             float s = 0.f, ss = 0.f;
; #pragma unroll
;             for (int nt = 0; nt < 8; ++nt) {
;                 f32x4 xr;
;                 if (l == 0) {
;                     const int chunk = wid * 32 + nt * 4 + quad;
;                     xr = *(const f32x4*)(XR + rl * 4096 + ((chunk ^ l15) << 4));
;                 } else {
;                     const u32x2 hb = *(const u32x2*)(XR + ((wid * 4 + (nt >> 1)) * 32 + rl) * 64 + (nt & 1) * 32 + quad * 8);
;                     xr = (f32x4){bf2f(hb[0] & 0xffffu), bf2f(hb[0] >> 16), bf2f(hb[1] & 0xffffu), bf2f(hb[1] >> 16)};
;                 }
; #pragma unroll
;                 for (int i = 0; i < 4; ++i) { const float v = acc[mt][nt][i] + DN_ALPHA * xr[i]; acc[mt][nt][i] = v; s += v; ss += v * v; }
;             }
;             s2[mh] = s; ss2[mh] = ss;
;         }
; #pragma unroll
;         for (int mh = 0; mh < 2; ++mh) { s2[mh] += __shfl_xor(s2[mh], 16); ss2[mh] += __shfl_xor(ss2[mh], 16); }
; #pragma unroll
;         for (int mh = 0; mh < 2; ++mh) { s2[mh] += __shfl_xor(s2[mh], 32); ss2[mh] += __shfl_xor(ss2[mh], 32); }
;         if (quad == 0) {
; #pragma unroll
;             for (int mh = 0; mh < 2; ++mh) *(f32x2*)&red[((mh * 16 + l15) * 8 + wid) * 2] = (f32x2){s2[mh], ss2[mh]};
;         }
;         __syncthreads();
;         if (half == 0) issue_x(1);
; #pragma unroll
;         for (int mh = 0; mh < 2; ++mh) {
;             const int mt = half * 2 + mh, rl = mh * 16 + l15, row = mt * 16 + l15;
;             float s = 0.f, ss = 0.f;
; #pragma unroll
;             for (int w = 0; w < 4; ++w) { const f32x4 v = *(const f32x4*)&red[rl * 16 + 4 * w]; s += v[0] + v[2]; ss += v[1] + v[3]; }
;             const float mu = s * (1.f / 1024.f);
;             const float var = ss * (1.f / 1024.f) - mu * mu;
;             const float rs = rsqrtf(var + LN_EPS);
;             float* orow = xo + (r0 + row) * 1024 + wid * 128 + quad * 4;
;             bf16_t* brow = xbo + xb_off((int)r0 + row, wid * 128) + quad * 4;
;             const float* gp = GB + wid * 128 + quad * 4;
; #pragma unroll
;             for (int nt = 0; nt < 8; ++nt) {
	v_fmac_f32_e32 v46, s58, v160
	v_fmac_f32_e32 v47, s58, v161
	v_fmac_f32_e32 v48, s58, v162
	v_fmac_f32_e32 v49, s58, v163
	v_add_f32_e32 v196, v196, v46
	v_fmac_f32_e32 v197, v46, v46
	v_add_f32_e32 v130, v130, v47
	v_fmac_f32_e32 v142, v47, v47
	v_add_f32_e32 v196, v196, v48
	v_fmac_f32_e32 v197, v48, v48
	v_add_f32_e32 v130, v130, v49
	v_fmac_f32_e32 v142, v49, v49
	s_waitcnt lgkmcnt(2)
	v_fmac_f32_e32 v42, s58, v164
	v_fmac_f32_e32 v43, s58, v165
	v_fmac_f32_e32 v44, s58, v166
	v_fmac_f32_e32 v45, s58, v167
	v_add_f32_e32 v196, v196, v42
	v_fmac_f32_e32 v197, v42, v42
	v_add_f32_e32 v130, v130, v43
	v_fmac_f32_e32 v142, v43, v43
	v_add_f32_e32 v196, v196, v44
	v_fmac_f32_e32 v197, v44, v44
	v_add_f32_e32 v130, v130, v45
	v_fmac_f32_e32 v142, v45, v45
	s_waitcnt lgkmcnt(1)
	v_fmac_f32_e32 v38, s58, v168
	v_fmac_f32_e32 v39, s58, v169
	v_fmac_f32_e32 v40, s58, v170
	v_fmac_f32_e32 v41, s58, v171
	v_add_f32_e32 v196, v196, v38
	v_fmac_f32_e32 v197, v38, v38
	v_add_f32_e32 v130, v130, v39
	v_fmac_f32_e32 v142, v39, v39
	v_add_f32_e32 v196, v196, v40
	v_fmac_f32_e32 v197, v40, v40
	v_add_f32_e32 v130, v130, v41
	v_fmac_f32_e32 v142, v41, v41
	s_waitcnt lgkmcnt(0)
	v_fmac_f32_e32 v2, s58, v172
	v_fmac_f32_e32 v3, s58, v173
	v_fmac_f32_e32 v4, s58, v174
	v_fmac_f32_e32 v5, s58, v175
	v_add_f32_e32 v196, v196, v2
	v_fmac_f32_e32 v197, v2, v2
	v_add_f32_e32 v130, v130, v3
	v_fmac_f32_e32 v142, v3, v3
	v_add_f32_e32 v196, v196, v4
	v_fmac_f32_e32 v197, v4, v4
	v_add_f32_e32 v130, v130, v5
	v_fmac_f32_e32 v142, v5, v5
	v_add_f32_e32 v196, v196, v130
	v_add_f32_e32 v197, v197, v142
	v_mov_b32_e32 v198, v196
	v_mov_b32_e32 v199, v197
	s_nop 1
	v_permlane16_swap_b32 v198, v196
	v_permlane16_swap_b32 v199, v197
	v_add_f32_e32 v196, v196, v198
	v_add_f32_e32 v197, v197, v199
	v_mov_b32_e32 v198, v196
	v_mov_b32_e32 v199, v197
	s_nop 1
	v_permlane32_swap_b32 v198, v196
	v_permlane32_swap_b32 v199, v197
	v_add_f32_e32 v196, v196, v198
	v_add_f32_e32 v197, v197, v199
	s_mov_b64 exec, 0xffff
	ds_write_b64 v134, v[196:197]
	s_mov_b64 exec, -1
	s_waitcnt lgkmcnt(0)
	s_barrier
	ds_read_b128 v[160:163], v135 offset:0
	ds_read_b128 v[164:167], v135 offset:16
	ds_read_b128 v[168:171], v135 offset:32
	ds_read_b128 v[172:175], v135 offset:48
	s_waitcnt lgkmcnt(0)
	v_add_f32_e32 v160, v160, v162
	v_add_f32_e32 v161, v161, v163
	v_add_f32_e32 v164, v164, v166
	v_add_f32_e32 v165, v165, v167
	v_add_f32_e32 v168, v168, v170
	v_add_f32_e32 v169, v169, v171
	v_add_f32_e32 v172, v172, v174
	v_add_f32_e32 v173, v173, v175
	v_add_f32_e32 v160, v160, v164
	v_add_f32_e32 v161, v161, v165
	v_add_f32_e32 v168, v168, v172
	v_add_f32_e32 v169, v169, v173
	v_add_f32_e32 v160, v160, v168
	v_add_f32_e32 v161, v161, v169
	v_mul_f32_e32 v192, 0x3a800000, v160
	v_mul_f32_e32 v193, 0x3a800000, v161
	v_fma_f32 v193, -v192, v192, v193
	v_add_f32_e32 v193, 0x3727c5ac, v193
	v_rsq_f32_e32 v193, v193
	s_nop 0
	ds_read_b128 v[176:179], v136
	ds_read_b128 v[180:183], v136 offset:4096
	ds_read_b128 v[184:187], v136 offset:64
	ds_read_b128 v[188:191], v136 offset:4160
	s_waitcnt lgkmcnt(2)
	v_sub_f32_e32 v62, v62, v192
	v_mul_f32_e32 v62, v62, v193
	v_fma_f32 v62, v176, v62, v180
	v_sub_f32_e32 v63, v63, v192
	v_mul_f32_e32 v63, v63, v193
	v_fma_f32 v63, v177, v63, v181
	v_sub_f32_e32 v64, v64, v192
	v_mul_f32_e32 v64, v64, v193
	v_fma_f32 v64, v178, v64, v182
	v_sub_f32_e32 v65, v65, v192
	v_mul_f32_e32 v65, v65, v193
	v_fma_f32 v65, v179, v65, v183
	v_cvt_pk_bf16_f32 v62, v62, v63
	v_cvt_pk_bf16_f32 v63, v64, v65
	ds_read_b128 v[176:179], v136 offset:128
	ds_read_b128 v[180:183], v136 offset:4224
	s_waitcnt lgkmcnt(2)
	v_sub_f32_e32 v58, v58, v192
	v_mul_f32_e32 v58, v58, v193
	v_fma_f32 v58, v184, v58, v188
	v_sub_f32_e32 v59, v59, v192
	v_mul_f32_e32 v59, v59, v193
	v_fma_f32 v59, v185, v59, v189
	v_sub_f32_e32 v60, v60, v192
	v_mul_f32_e32 v60, v60, v193
	v_fma_f32 v60, v186, v60, v190
	v_sub_f32_e32 v61, v61, v192
	v_mul_f32_e32 v61, v61, v193
	v_fma_f32 v61, v187, v61, v191
	v_cvt_pk_bf16_f32 v64, v58, v59
	v_cvt_pk_bf16_f32 v65, v60, v61
	s_nop 1
	v_permlane16_swap_b32 v62, v64
	v_permlane16_swap_b32 v63, v65
	ds_read_b128 v[184:187], v136 offset:192
	ds_read_b128 v[188:191], v136 offset:4288
	s_waitcnt lgkmcnt(2)
	v_sub_f32_e32 v54, v54, v192
	v_mul_f32_e32 v54, v54, v193
	v_fma_f32 v54, v176, v54, v180
	v_sub_f32_e32 v55, v55, v192
	v_mul_f32_e32 v55, v55, v193
	v_fma_f32 v55, v177, v55, v181
	v_sub_f32_e32 v56, v56, v192
	v_mul_f32_e32 v56, v56, v193
	v_fma_f32 v56, v178, v56, v182
	v_sub_f32_e32 v57, v57, v192
	v_mul_f32_e32 v57, v57, v193
	v_fma_f32 v57, v179, v57, v183
	v_cvt_pk_bf16_f32 v54, v54, v55
	v_cvt_pk_bf16_f32 v55, v56, v57
	ds_read_b128 v[176:179], v136 offset:256
	ds_read_b128 v[180:183], v136 offset:4352
	s_waitcnt lgkmcnt(2)
	v_sub_f32_e32 v50, v50, v192
	v_mul_f32_e32 v50, v50, v193
	v_fma_f32 v50, v184, v50, v188
	v_sub_f32_e32 v51, v51, v192
	v_mul_f32_e32 v51, v51, v193
	v_fma_f32 v51, v185, v51, v189
	v_sub_f32_e32 v52, v52, v192
	v_mul_f32_e32 v52, v52, v193
	v_fma_f32 v52, v186, v52, v190
	v_sub_f32_e32 v53, v53, v192
	v_mul_f32_e32 v53, v53, v193
	v_fma_f32 v53, v187, v53, v191
	v_cvt_pk_bf16_f32 v56, v50, v51
	v_cvt_pk_bf16_f32 v57, v52, v53
	s_nop 1
	v_permlane16_swap_b32 v54, v56
	v_permlane16_swap_b32 v55, v57
	ds_read_b128 v[184:187], v136 offset:320
	ds_read_b128 v[188:191], v136 offset:4416
	s_waitcnt lgkmcnt(2)
; DI unsigned pk2(float lo, float hi) { const f32x2 v = {lo, hi}; const bf16x2_t b = __builtin_convertvector(v, bf16x2_t); return __builtin_bit_cast(unsigned, b); }
; DI size_t xb_off(int tok, int col) { return ((size_t)(((tok >> 7) * 32 + (col >> 5)) * 128 + (tok & 127))) * 32 + (col & 31); }
; DI void unit_O(const Params& p, char* lds, int l, int tile, int glu_tiles, int tile_b) {
;     ...
;     auto issue_x = [&](int half) {
;         if (l == 0) {
; #pragma unroll 1
;             for (int i = 0; i < 16; ++i) {
;                 const int pc = (wid * 16 + i + xrot) & 127, row = pc >> 2, phys = (pc & 3) * 64 + lane, logical = phys ^ (row & 15);
;                 __builtin_amdgcn_global_load_lds((const unsigned*)(xres + (r0 + half * 32 + row) * 1024 + logical * 4), (unsigned*)(XR + pc * 1024 + lane * 16), 16, 0, 0);
;             }
;         } else {
; #pragma unroll 1
;             for (int i = 0; i < 8; ++i) {
;                 const int pc = (wid * 8 + i + (xrot >> 1)) & 63, kt = pc >> 1, sub = pc & 1;
;                 __builtin_amdgcn_global_load_lds((const unsigned*)(xbres + ((size_t)kt * 128 + half * 32) * 32 + sub * 512 + lane * 8), (unsigned*)(XR + pc * 1024 + lane * 16), 16, 0, 0);
;             }
;         }
;     ...
;             float* orow = xo + (r0 + row) * 1024 + wid * 128 + quad * 4;
;             bf16_t* brow = xbo + xb_off((int)r0 + row, wid * 128) + quad * 4;
;             const float* gp = GB + wid * 128 + quad * 4;
; #pragma unroll
;             for (int nt = 0; nt < 8; ++nt) {
;                 const f32x4 g = *(const f32x4*)(gp + nt * 16), bb = *(const f32x4*)(gp + 1024 + nt * 16);
;                 f32x4 o;
; #pragma unroll
;                 for (int i = 0; i < 4; ++i) o[i] = (acc[mt][nt][i] - mu) * rs * g[i] + bb[i];
;                 if (l == 0) *(u32x2*)(brow + (nt >> 1) * 4096 + (nt & 1) * 16) = (u32x2){pk2(o[0], o[1]), pk2(o[2], o[3])};
	v_sub_f32_e32 v46, v46, v192
	v_mul_f32_e32 v46, v46, v193
	v_fma_f32 v46, v176, v46, v180
	v_sub_f32_e32 v47, v47, v192
	v_mul_f32_e32 v47, v47, v193
	v_fma_f32 v47, v177, v47, v181
	v_sub_f32_e32 v48, v48, v192
	v_mul_f32_e32 v48, v48, v193
	v_fma_f32 v48, v178, v48, v182
	v_sub_f32_e32 v49, v49, v192
	v_mul_f32_e32 v49, v49, v193
	v_fma_f32 v49, v179, v49, v183
	v_cvt_pk_bf16_f32 v46, v46, v47
	v_cvt_pk_bf16_f32 v47, v48, v49
	ds_read_b128 v[176:179], v136 offset:384
	ds_read_b128 v[180:183], v136 offset:4480
	s_waitcnt lgkmcnt(2)
	v_sub_f32_e32 v42, v42, v192
	v_mul_f32_e32 v42, v42, v193
	v_fma_f32 v42, v184, v42, v188
	v_sub_f32_e32 v43, v43, v192
	v_mul_f32_e32 v43, v43, v193
	v_fma_f32 v43, v185, v43, v189
	v_sub_f32_e32 v44, v44, v192
	v_mul_f32_e32 v44, v44, v193
	v_fma_f32 v44, v186, v44, v190
	v_sub_f32_e32 v45, v45, v192
	v_mul_f32_e32 v45, v45, v193
	v_fma_f32 v45, v187, v45, v191
	v_cvt_pk_bf16_f32 v48, v42, v43
	v_cvt_pk_bf16_f32 v49, v44, v45
	s_nop 1
	v_permlane16_swap_b32 v46, v48
	v_permlane16_swap_b32 v47, v49
	ds_read_b128 v[184:187], v136 offset:448
	ds_read_b128 v[188:191], v136 offset:4544
	s_waitcnt lgkmcnt(2)
	v_sub_f32_e32 v38, v38, v192
	v_mul_f32_e32 v38, v38, v193
	v_fma_f32 v38, v176, v38, v180
	v_sub_f32_e32 v39, v39, v192
	v_mul_f32_e32 v39, v39, v193
	v_fma_f32 v39, v177, v39, v181
	v_sub_f32_e32 v40, v40, v192
	v_mul_f32_e32 v40, v40, v193
	v_fma_f32 v40, v178, v40, v182
	v_sub_f32_e32 v41, v41, v192
	v_mul_f32_e32 v41, v41, v193
	v_fma_f32 v41, v179, v41, v183
	v_cvt_pk_bf16_f32 v38, v38, v39
	v_cvt_pk_bf16_f32 v39, v40, v41
	s_waitcnt lgkmcnt(0)
	v_sub_f32_e32 v2, v2, v192
	v_mul_f32_e32 v2, v2, v193
	v_fma_f32 v2, v184, v2, v188
	v_sub_f32_e32 v3, v3, v192
	v_mul_f32_e32 v3, v3, v193
	v_fma_f32 v3, v185, v3, v189
	v_sub_f32_e32 v4, v4, v192
	v_mul_f32_e32 v4, v4, v193
	v_fma_f32 v4, v186, v4, v190
	v_sub_f32_e32 v5, v5, v192
	v_mul_f32_e32 v5, v5, v193
	v_fma_f32 v5, v187, v5, v191
	v_cvt_pk_bf16_f32 v40, v2, v3
	v_cvt_pk_bf16_f32 v41, v4, v5
	s_nop 1
	v_permlane16_swap_b32 v38, v40
	v_permlane16_swap_b32 v39, v41
	s_add_u32 s94, s78, 0x0
	s_addc_u32 s95, s79, 0
	global_store_dwordx4 v137, v[98:101], s[94:95]
	s_add_u32 s94, s94, 0x2000
	s_addc_u32 s95, s95, 0
	global_store_dwordx4 v137, v[90:93], s[94:95]
	s_add_u32 s94, s94, 0x2000
	s_addc_u32 s95, s95, 0
	global_store_dwordx4 v137, v[82:85], s[94:95]
	s_add_u32 s94, s94, 0x2000
	s_addc_u32 s95, s95, 0
	global_store_dwordx4 v137, v[74:77], s[94:95]
	s_add_u32 s94, s78, 0x400
	s_addc_u32 s95, s79, 0
	global_store_dwordx4 v137, v[126:129], s[94:95]
	s_add_u32 s94, s94, 0x2000
	s_addc_u32 s95, s95, 0
	global_store_dwordx4 v137, v[118:121], s[94:95]
	s_add_u32 s94, s94, 0x2000
	s_addc_u32 s95, s95, 0
	global_store_dwordx4 v137, v[110:113], s[94:95]
	s_add_u32 s94, s94, 0x2000
	s_addc_u32 s95, s95, 0
	global_store_dwordx4 v137, v[102:105], s[94:95]
	s_add_u32 s94, s78, 0x800
	s_addc_u32 s95, s79, 0
	global_store_dwordx4 v137, v[34:37], s[94:95]
	s_add_u32 s94, s94, 0x2000
	s_addc_u32 s95, s95, 0
	global_store_dwordx4 v137, v[26:29], s[94:95]
	s_add_u32 s94, s94, 0x2000
	s_addc_u32 s95, s95, 0
	global_store_dwordx4 v137, v[18:21], s[94:95]
	s_add_u32 s94, s94, 0x2000
	s_addc_u32 s95, s95, 0
	global_store_dwordx4 v137, v[10:13], s[94:95]
	s_add_u32 s94, s78, 0xc00
	s_addc_u32 s95, s79, 0
	global_store_dwordx4 v137, v[62:65], s[94:95]
	s_add_u32 s94, s94, 0x2000
	s_addc_u32 s95, s95, 0
	global_store_dwordx4 v137, v[54:57], s[94:95]
	s_add_u32 s94, s94, 0x2000
	s_addc_u32 s95, s95, 0
	global_store_dwordx4 v137, v[46:49], s[94:95]
	s_add_u32 s94, s94, 0x2000
	s_addc_u32 s95, s95, 0
	global_store_dwordx4 v137, v[38:41], s[94:95]
	s_branch .Le1_done
.Le1_l1:
	s_lshr_b32 s40, s34, 1
	s_lshl_b32 s40, s40, 18
	s_and_b32 s94, s34, 1
	s_lshl_b32 s94, s94, 12
	s_add_u32 s40, s40, s94
	s_lshl_b32 s91, s90, 12
	s_lshl_b32 s94, s90, 15
	s_add_u32 s96, s56, s40
	s_addc_u32 s97, s57, 0
	s_add_u32 s96, s96, s94
	s_addc_u32 s97, s97, 0
	v_lshlrev_b32_e32 v208, 4, v141
	v_lshlrev_b32_e32 v133, 12, v140
	v_lshl_add_u32 v133, v138, 6, v133
	v_lshl_add_u32 v133, v139, 3, v133
	v_lshlrev_b32_e32 v137, 12, v138
	v_lshl_add_u32 v137, v140, 9, v137
	v_lshl_add_u32 v137, v139, 4, v137
	s_lshl_b32 s40, s34, 18
	s_add_u32 s78, s16, s40
	s_addc_u32 s79, s17, 0
	s_add_u32 s92, s96, 0x0
	s_addc_u32 s93, s97, 0
	s_add_u32 s40, s91, 0x0
	s_mov_b32 m0, s40
	s_nop 0
	global_load_lds_dwordx4 v208, s[92:93]
	s_add_u32 s92, s92, 0x2000
	s_addc_u32 s93, s93, 0
	s_add_u32 m0, m0, 0x400
	s_nop 0
	global_load_lds_dwordx4 v208, s[92:93]
	s_add_u32 s92, s92, 0x2000
	s_addc_u32 s93, s93, 0
	s_add_u32 m0, m0, 0x400
	s_nop 0
	global_load_lds_dwordx4 v208, s[92:93]
	s_add_u32 s92, s92, 0x2000
	s_addc_u32 s93, s93, 0
	s_add_u32 m0, m0, 0x400
	s_nop 0
	global_load_lds_dwordx4 v208, s[92:93]
	s_add_u32 s92, s96, 0x400
	s_addc_u32 s93, s97, 0
	s_add_u32 s40, s91, 0x8000
	s_mov_b32 m0, s40
	s_nop 0
	global_load_lds_dwordx4 v208, s[92:93]
	s_add_u32 s92, s92, 0x2000
	s_addc_u32 s93, s93, 0
	s_add_u32 m0, m0, 0x400
	s_nop 0
	global_load_lds_dwordx4 v208, s[92:93]
	s_add_u32 s92, s92, 0x2000
	s_addc_u32 s93, s93, 0
	s_add_u32 m0, m0, 0x400
	s_nop 0
	global_load_lds_dwordx4 v208, s[92:93]
	s_add_u32 s92, s92, 0x2000
	s_addc_u32 s93, s93, 0
	s_add_u32 m0, m0, 0x400
	s_nop 0
	global_load_lds_dwordx4 v208, s[92:93]
	s_waitcnt vmcnt(8)
	ds_write_b128 v143, v[176:179]
	s_waitcnt vmcnt(4) lgkmcnt(0)
	s_barrier
; DI float bf2f(unsigned b) { return __uint_as_float(b << 16); }
; DI void unit_O(const Params& p, char* lds, int l, int tile, int glu_tiles, int tile_b) {
;     ...
;         float s2[2], ss2[2];
; #pragma unroll
;         for (int mh = 0; mh < 2; ++mh) {
;             const int mt = half * 2 + mh, rl = mh * 16 + l15;
;             float s = 0.f, ss = 0.f;
; #pragma unroll
;             for (int nt = 0; nt < 8; ++nt) {
;                 f32x4 xr;
;                 if (l == 0) {
;                     const int chunk = wid * 32 + nt * 4 + quad;
;                     xr = *(const f32x4*)(XR + rl * 4096 + ((chunk ^ l15) << 4));
;                 } else {
;                     const u32x2 hb = *(const u32x2*)(XR + ((wid * 4 + (nt >> 1)) * 32 + rl) * 64 + (nt & 1) * 32 + quad * 8);
;                     xr = (f32x4){bf2f(hb[0] & 0xffffu), bf2f(hb[0] >> 16), bf2f(hb[1] & 0xffffu), bf2f(hb[1] >> 16)};
;                 }
; #pragma unroll
;                 for (int i = 0; i < 4; ++i) { const float v = acc[mt][nt][i] + DN_ALPHA * xr[i]; acc[mt][nt][i] = v; s += v; ss += v * v; }
;             }
;             s2[mh] = s; ss2[mh] = ss;
;         }
; #pragma unroll
;         for (int mh = 0; mh < 2; ++mh) { s2[mh] += __shfl_xor(s2[mh], 16); ss2[mh] += __shfl_xor(ss2[mh], 16); }
; #pragma unroll
;         for (int mh = 0; mh < 2; ++mh) { s2[mh] += __shfl_xor(s2[mh], 32); ss2[mh] += __shfl_xor(ss2[mh], 32); }
;         if (quad == 0) {
; #pragma unroll
;             for (int mh = 0; mh < 2; ++mh) *(f32x2*)&red[((mh * 16 + l15) * 8 + wid) * 2] = (f32x2){s2[mh], ss2[mh]};
;         }
;         __syncthreads();
	ds_read_b64 v[180:181], v133 offset:0
	ds_read_b64 v[182:183], v133 offset:32
	ds_read_b64 v[184:185], v133 offset:1024
	ds_read_b64 v[186:187], v133 offset:1056
	ds_read_b64 v[188:189], v133 offset:2048
	ds_read_b64 v[190:191], v133 offset:2080
	ds_read_b64 v[192:193], v133 offset:3072
	ds_read_b64 v[194:195], v133 offset:3104
	s_waitcnt lgkmcnt(7)
	v_lshlrev_b32_e32 v144, 16, v180
	v_and_b32_e32 v145, 0xffff0000, v180
	v_lshlrev_b32_e32 v146, 16, v181
	v_and_b32_e32 v147, 0xffff0000, v181
	v_fmac_f32_e32 v98, s58, v144
	v_fmac_f32_e32 v99, s58, v145
	v_fmac_f32_e32 v100, s58, v146
	v_fmac_f32_e32 v101, s58, v147
	v_mov_b32_e32 v196, v98
	v_mul_f32_e32 v197, v98, v98
	v_mov_b32_e32 v130, v99
	v_mul_f32_e32 v142, v99, v99
	v_add_f32_e32 v196, v196, v100
	v_fmac_f32_e32 v197, v100, v100
	v_add_f32_e32 v130, v130, v101
	v_fmac_f32_e32 v142, v101, v101
	s_waitcnt lgkmcnt(6)
	v_lshlrev_b32_e32 v148, 16, v182
	v_and_b32_e32 v149, 0xffff0000, v182
	v_lshlrev_b32_e32 v150, 16, v183
	v_and_b32_e32 v151, 0xffff0000, v183
	v_fmac_f32_e32 v94, s58, v148
	v_fmac_f32_e32 v95, s58, v149
	v_fmac_f32_e32 v96, s58, v150
	v_fmac_f32_e32 v97, s58, v151
	v_add_f32_e32 v196, v196, v94
	v_fmac_f32_e32 v197, v94, v94
	v_add_f32_e32 v130, v130, v95
	v_fmac_f32_e32 v142, v95, v95
	v_add_f32_e32 v196, v196, v96
	v_fmac_f32_e32 v197, v96, v96
	v_add_f32_e32 v130, v130, v97
	v_fmac_f32_e32 v142, v97, v97
	s_waitcnt lgkmcnt(5)
	v_lshlrev_b32_e32 v152, 16, v184
	v_and_b32_e32 v153, 0xffff0000, v184
	v_lshlrev_b32_e32 v154, 16, v185
	v_and_b32_e32 v155, 0xffff0000, v185
	v_fmac_f32_e32 v90, s58, v152
	v_fmac_f32_e32 v91, s58, v153
	v_fmac_f32_e32 v92, s58, v154
	v_fmac_f32_e32 v93, s58, v155
	v_add_f32_e32 v196, v196, v90
	v_fmac_f32_e32 v197, v90, v90
	v_add_f32_e32 v130, v130, v91
	v_fmac_f32_e32 v142, v91, v91
	v_add_f32_e32 v196, v196, v92
	v_fmac_f32_e32 v197, v92, v92
	v_add_f32_e32 v130, v130, v93
	v_fmac_f32_e32 v142, v93, v93
	s_waitcnt lgkmcnt(4)
	v_lshlrev_b32_e32 v156, 16, v186
	v_and_b32_e32 v157, 0xffff0000, v186
	v_lshlrev_b32_e32 v158, 16, v187
	v_and_b32_e32 v159, 0xffff0000, v187
	v_fmac_f32_e32 v86, s58, v156
	v_fmac_f32_e32 v87, s58, v157
	v_fmac_f32_e32 v88, s58, v158
	v_fmac_f32_e32 v89, s58, v159
	v_add_f32_e32 v196, v196, v86
	v_fmac_f32_e32 v197, v86, v86
	v_add_f32_e32 v130, v130, v87
	v_fmac_f32_e32 v142, v87, v87
	v_add_f32_e32 v196, v196, v88
	v_fmac_f32_e32 v197, v88, v88
	v_add_f32_e32 v130, v130, v89
	v_fmac_f32_e32 v142, v89, v89
	s_waitcnt lgkmcnt(3)
	v_lshlrev_b32_e32 v160, 16, v188
	v_and_b32_e32 v161, 0xffff0000, v188
	v_lshlrev_b32_e32 v162, 16, v189
	v_and_b32_e32 v163, 0xffff0000, v189
	v_fmac_f32_e32 v82, s58, v160
	v_fmac_f32_e32 v83, s58, v161
	v_fmac_f32_e32 v84, s58, v162
	v_fmac_f32_e32 v85, s58, v163
	v_add_f32_e32 v196, v196, v82
	v_fmac_f32_e32 v197, v82, v82
	v_add_f32_e32 v130, v130, v83
	v_fmac_f32_e32 v142, v83, v83
	v_add_f32_e32 v196, v196, v84
	v_fmac_f32_e32 v197, v84, v84
	v_add_f32_e32 v130, v130, v85
	v_fmac_f32_e32 v142, v85, v85
	s_waitcnt lgkmcnt(2)
	v_lshlrev_b32_e32 v164, 16, v190
	v_and_b32_e32 v165, 0xffff0000, v190
	v_lshlrev_b32_e32 v166, 16, v191
	v_and_b32_e32 v167, 0xffff0000, v191
	v_fmac_f32_e32 v78, s58, v164
	v_fmac_f32_e32 v79, s58, v165
	v_fmac_f32_e32 v80, s58, v166
	v_fmac_f32_e32 v81, s58, v167
	v_add_f32_e32 v196, v196, v78
	v_fmac_f32_e32 v197, v78, v78
	v_add_f32_e32 v130, v130, v79
	v_fmac_f32_e32 v142, v79, v79
	v_add_f32_e32 v196, v196, v80
	v_fmac_f32_e32 v197, v80, v80
	v_add_f32_e32 v130, v130, v81
	v_fmac_f32_e32 v142, v81, v81
	s_waitcnt lgkmcnt(1)
	v_lshlrev_b32_e32 v168, 16, v192
	v_and_b32_e32 v169, 0xffff0000, v192
	v_lshlrev_b32_e32 v170, 16, v193
	v_and_b32_e32 v171, 0xffff0000, v193
	v_fmac_f32_e32 v74, s58, v168
	v_fmac_f32_e32 v75, s58, v169
	v_fmac_f32_e32 v76, s58, v170
	v_fmac_f32_e32 v77, s58, v171
	v_add_f32_e32 v196, v196, v74
	v_fmac_f32_e32 v197, v74, v74
	v_add_f32_e32 v130, v130, v75
	v_fmac_f32_e32 v142, v75, v75
	v_add_f32_e32 v196, v196, v76
	v_fmac_f32_e32 v197, v76, v76
	v_add_f32_e32 v130, v130, v77
	v_fmac_f32_e32 v142, v77, v77
	s_waitcnt lgkmcnt(0)
	v_lshlrev_b32_e32 v172, 16, v194
	v_and_b32_e32 v173, 0xffff0000, v194
	v_lshlrev_b32_e32 v174, 16, v195
	v_and_b32_e32 v175, 0xffff0000, v195
	v_fmac_f32_e32 v70, s58, v172
	v_fmac_f32_e32 v71, s58, v173
	v_fmac_f32_e32 v72, s58, v174
	v_fmac_f32_e32 v73, s58, v175
	v_add_f32_e32 v196, v196, v70
	v_fmac_f32_e32 v197, v70, v70
	v_add_f32_e32 v130, v130, v71
	v_fmac_f32_e32 v142, v71, v71
	v_add_f32_e32 v196, v196, v72
	v_fmac_f32_e32 v197, v72, v72
	v_add_f32_e32 v130, v130, v73
	v_fmac_f32_e32 v142, v73, v73
	v_add_f32_e32 v196, v196, v130
	v_add_f32_e32 v197, v197, v142
	v_mov_b32_e32 v198, v196
	v_mov_b32_e32 v199, v197
	s_nop 1
	v_permlane16_swap_b32 v198, v196
	v_permlane16_swap_b32 v199, v197
	v_add_f32_e32 v196, v196, v198
	v_add_f32_e32 v197, v197, v199
	v_mov_b32_e32 v198, v196
	v_mov_b32_e32 v199, v197
	s_nop 1
	v_permlane32_swap_b32 v198, v196
	v_permlane32_swap_b32 v199, v197
	v_add_f32_e32 v196, v196, v198
	v_add_f32_e32 v197, v197, v199
	s_mov_b64 exec, 0xffff
	ds_write_b64 v134, v[196:197]
	s_mov_b64 exec, -1
	s_waitcnt lgkmcnt(0)
	s_barrier
; DI unsigned pk2(float lo, float hi) { const f32x2 v = {lo, hi}; const bf16x2_t b = __builtin_convertvector(v, bf16x2_t); return __builtin_bit_cast(unsigned, b); }
; DI size_t xb_off(int tok, int col) { return ((size_t)(((tok >> 7) * 32 + (col >> 5)) * 128 + (tok & 127))) * 32 + (col & 31); }
; DI void unit_O(const Params& p, char* lds, int l, int tile, int glu_tiles, int tile_b) {
;     ...
;         if (half == 0) issue_x(1);
; #pragma unroll
;         for (int mh = 0; mh < 2; ++mh) {
;             const int mt = half * 2 + mh, rl = mh * 16 + l15, row = mt * 16 + l15;
;             float s = 0.f, ss = 0.f;
; #pragma unroll
;             for (int w = 0; w < 4; ++w) { const f32x4 v = *(const f32x4*)&red[rl * 16 + 4 * w]; s += v[0] + v[2]; ss += v[1] + v[3]; }
;             const float mu = s * (1.f / 1024.f);
;             const float var = ss * (1.f / 1024.f) - mu * mu;
;             const float rs = rsqrtf(var + LN_EPS);
;             float* orow = xo + (r0 + row) * 1024 + wid * 128 + quad * 4;
;             bf16_t* brow = xbo + xb_off((int)r0 + row, wid * 128) + quad * 4;
;             const float* gp = GB + wid * 128 + quad * 4;
; #pragma unroll
;             for (int nt = 0; nt < 8; ++nt) {
;                 const f32x4 g = *(const f32x4*)(gp + nt * 16), bb = *(const f32x4*)(gp + 1024 + nt * 16);
;                 f32x4 o;
; #pragma unroll
;                 for (int i = 0; i < 4; ++i) o[i] = (acc[mt][nt][i] - mu) * rs * g[i] + bb[i];
;                 if (l == 0) *(u32x2*)(brow + (nt >> 1) * 4096 + (nt & 1) * 16) = (u32x2){pk2(o[0], o[1]), pk2(o[2], o[3])};
;                 else *(f32x4*)(orow + nt * 16) = o;
	s_add_u32 s92, s96, 0x800
	s_addc_u32 s93, s97, 0
	s_add_u32 s40, s91, 0x0
	s_mov_b32 m0, s40
	s_nop 0
	global_load_lds_dwordx4 v208, s[92:93]
	s_add_u32 s92, s92, 0x2000
	s_addc_u32 s93, s93, 0
	s_add_u32 m0, m0, 0x400
	s_nop 0
	global_load_lds_dwordx4 v208, s[92:93]
	s_add_u32 s92, s92, 0x2000
	s_addc_u32 s93, s93, 0
	s_add_u32 m0, m0, 0x400
	s_nop 0
	global_load_lds_dwordx4 v208, s[92:93]
	s_add_u32 s92, s92, 0x2000
	s_addc_u32 s93, s93, 0
	s_add_u32 m0, m0, 0x400
	s_nop 0
	global_load_lds_dwordx4 v208, s[92:93]
	ds_read_b128 v[160:163], v135 offset:0
	ds_read_b128 v[164:167], v135 offset:16
	ds_read_b128 v[168:171], v135 offset:32
	ds_read_b128 v[172:175], v135 offset:48
	s_waitcnt lgkmcnt(0)
	v_add_f32_e32 v160, v160, v162
	v_add_f32_e32 v161, v161, v163
	v_add_f32_e32 v164, v164, v166
	v_add_f32_e32 v165, v165, v167
	v_add_f32_e32 v168, v168, v170
	v_add_f32_e32 v169, v169, v171
	v_add_f32_e32 v172, v172, v174
	v_add_f32_e32 v173, v173, v175
	v_add_f32_e32 v160, v160, v164
	v_add_f32_e32 v161, v161, v165
	v_add_f32_e32 v168, v168, v172
	v_add_f32_e32 v169, v169, v173
	v_add_f32_e32 v160, v160, v168
	v_add_f32_e32 v161, v161, v169
	v_mul_f32_e32 v192, 0x3a800000, v160
	v_mul_f32_e32 v193, 0x3a800000, v161
	v_fma_f32 v193, -v192, v192, v193
	v_add_f32_e32 v193, 0x3727c5ac, v193
	v_rsq_f32_e32 v193, v193
	s_nop 0
	ds_read_b128 v[176:179], v136
	ds_read_b128 v[180:183], v136 offset:4096
	ds_read_b128 v[184:187], v136 offset:64
	ds_read_b128 v[188:191], v136 offset:4160
	s_waitcnt lgkmcnt(2)
	v_sub_f32_e32 v98, v98, v192
	v_mul_f32_e32 v98, v98, v193
	v_fma_f32 v98, v176, v98, v180
	v_sub_f32_e32 v99, v99, v192
	v_mul_f32_e32 v99, v99, v193
	v_fma_f32 v99, v177, v99, v181
	v_sub_f32_e32 v100, v100, v192
	v_mul_f32_e32 v100, v100, v193
	v_fma_f32 v100, v178, v100, v182
	v_sub_f32_e32 v101, v101, v192
	v_mul_f32_e32 v101, v101, v193
	v_fma_f32 v101, v179, v101, v183
	ds_read_b128 v[176:179], v136 offset:128
	ds_read_b128 v[180:183], v136 offset:4224
	s_waitcnt lgkmcnt(2)
	v_sub_f32_e32 v94, v94, v192
	v_mul_f32_e32 v94, v94, v193
	v_fma_f32 v94, v184, v94, v188
	v_sub_f32_e32 v95, v95, v192
	v_mul_f32_e32 v95, v95, v193
	v_fma_f32 v95, v185, v95, v189
	v_sub_f32_e32 v96, v96, v192
	v_mul_f32_e32 v96, v96, v193
	v_fma_f32 v96, v186, v96, v190
	v_sub_f32_e32 v97, v97, v192
	v_mul_f32_e32 v97, v97, v193
	v_fma_f32 v97, v187, v97, v191
	ds_read_b128 v[184:187], v136 offset:192
	ds_read_b128 v[188:191], v136 offset:4288
	s_waitcnt lgkmcnt(2)
	v_sub_f32_e32 v90, v90, v192
	v_mul_f32_e32 v90, v90, v193
	v_fma_f32 v90, v176, v90, v180
	v_sub_f32_e32 v91, v91, v192
	v_mul_f32_e32 v91, v91, v193
	v_fma_f32 v91, v177, v91, v181
	v_sub_f32_e32 v92, v92, v192
	v_mul_f32_e32 v92, v92, v193
	v_fma_f32 v92, v178, v92, v182
	v_sub_f32_e32 v93, v93, v192
	v_mul_f32_e32 v93, v93, v193
	v_fma_f32 v93, v179, v93, v183
	ds_read_b128 v[176:179], v136 offset:256
	ds_read_b128 v[180:183], v136 offset:4352
	s_waitcnt lgkmcnt(2)
	v_sub_f32_e32 v86, v86, v192
	v_mul_f32_e32 v86, v86, v193
	v_fma_f32 v86, v184, v86, v188
	v_sub_f32_e32 v87, v87, v192
	v_mul_f32_e32 v87, v87, v193
	v_fma_f32 v87, v185, v87, v189
	v_sub_f32_e32 v88, v88, v192
	v_mul_f32_e32 v88, v88, v193
	v_fma_f32 v88, v186, v88, v190
	v_sub_f32_e32 v89, v89, v192
	v_mul_f32_e32 v89, v89, v193
	v_fma_f32 v89, v187, v89, v191
	ds_read_b128 v[184:187], v136 offset:320
	ds_read_b128 v[188:191], v136 offset:4416
	s_waitcnt lgkmcnt(2)
	v_sub_f32_e32 v82, v82, v192
	v_mul_f32_e32 v82, v82, v193
	v_fma_f32 v82, v176, v82, v180
	v_sub_f32_e32 v83, v83, v192
	v_mul_f32_e32 v83, v83, v193
	v_fma_f32 v83, v177, v83, v181
	v_sub_f32_e32 v84, v84, v192
	v_mul_f32_e32 v84, v84, v193
	v_fma_f32 v84, v178, v84, v182
	v_sub_f32_e32 v85, v85, v192
	v_mul_f32_e32 v85, v85, v193
	v_fma_f32 v85, v179, v85, v183
	ds_read_b128 v[176:179], v136 offset:384
	ds_read_b128 v[180:183], v136 offset:4480
	s_waitcnt lgkmcnt(2)
	v_sub_f32_e32 v78, v78, v192
	v_mul_f32_e32 v78, v78, v193
	v_fma_f32 v78, v184, v78, v188
	v_sub_f32_e32 v79, v79, v192
	v_mul_f32_e32 v79, v79, v193
	v_fma_f32 v79, v185, v79, v189
	v_sub_f32_e32 v80, v80, v192
	v_mul_f32_e32 v80, v80, v193
	v_fma_f32 v80, v186, v80, v190
	v_sub_f32_e32 v81, v81, v192
	v_mul_f32_e32 v81, v81, v193
	v_fma_f32 v81, v187, v81, v191
	ds_read_b128 v[184:187], v136 offset:448
	ds_read_b128 v[188:191], v136 offset:4544
	s_waitcnt lgkmcnt(2)
	v_sub_f32_e32 v74, v74, v192
	v_mul_f32_e32 v74, v74, v193
	v_fma_f32 v74, v176, v74, v180
	v_sub_f32_e32 v75, v75, v192
	v_mul_f32_e32 v75, v75, v193
	v_fma_f32 v75, v177, v75, v181
	v_sub_f32_e32 v76, v76, v192
	v_mul_f32_e32 v76, v76, v193
	v_fma_f32 v76, v178, v76, v182
	v_sub_f32_e32 v77, v77, v192
	v_mul_f32_e32 v77, v77, v193
	v_fma_f32 v77, v179, v77, v183
	s_waitcnt lgkmcnt(0)
	v_sub_f32_e32 v70, v70, v192
	v_mul_f32_e32 v70, v70, v193
	v_fma_f32 v70, v184, v70, v188
	v_sub_f32_e32 v71, v71, v192
	v_mul_f32_e32 v71, v71, v193
	v_fma_f32 v71, v185, v71, v189
	v_sub_f32_e32 v72, v72, v192
	v_mul_f32_e32 v72, v72, v193
	v_fma_f32 v72, v186, v72, v190
	v_sub_f32_e32 v73, v73, v192
	v_mul_f32_e32 v73, v73, v193
	v_fma_f32 v73, v187, v73, v191
	s_waitcnt vmcnt(4) lgkmcnt(0)
	s_barrier
; DI float bf2f(unsigned b) { return __uint_as_float(b << 16); }
; DI void unit_O(const Params& p, char* lds, int l, int tile, int glu_tiles, int tile_b) {
;     ...
;         float s2[2], ss2[2];
; #pragma unroll
;         for (int mh = 0; mh < 2; ++mh) {
;             const int mt = half * 2 + mh, rl = mh * 16 + l15;
;             float s = 0.f, ss = 0.f;
; #pragma unroll
;             for (int nt = 0; nt < 8; ++nt) {
;                 f32x4 xr;
;                 if (l == 0) {
;                     const int chunk = wid * 32 + nt * 4 + quad;
;                     xr = *(const f32x4*)(XR + rl * 4096 + ((chunk ^ l15) << 4));
;                 } else {
;                     const u32x2 hb = *(const u32x2*)(XR + ((wid * 4 + (nt >> 1)) * 32 + rl) * 64 + (nt & 1) * 32 + quad * 8);
;                     xr = (f32x4){bf2f(hb[0] & 0xffffu), bf2f(hb[0] >> 16), bf2f(hb[1] & 0xffffu), bf2f(hb[1] >> 16)};
;                 }
; #pragma unroll
;                 for (int i = 0; i < 4; ++i) { const float v = acc[mt][nt][i] + DN_ALPHA * xr[i]; acc[mt][nt][i] = v; s += v; ss += v * v; }
;             }
;             s2[mh] = s; ss2[mh] = ss;
;         }
; #pragma unroll
;         for (int mh = 0; mh < 2; ++mh) { s2[mh] += __shfl_xor(s2[mh], 16); ss2[mh] += __shfl_xor(ss2[mh], 16); }
; #pragma unroll
;         for (int mh = 0; mh < 2; ++mh) { s2[mh] += __shfl_xor(s2[mh], 32); ss2[mh] += __shfl_xor(ss2[mh], 32); }
;         if (quad == 0) {
; #pragma unroll
;             for (int mh = 0; mh < 2; ++mh) *(f32x2*)&red[((mh * 16 + l15) * 8 + wid) * 2] = (f32x2){s2[mh], ss2[mh]};
;         }
;         __syncthreads();
	ds_read_b64 v[180:181], v133 offset:32768
	ds_read_b64 v[182:183], v133 offset:32800
	ds_read_b64 v[184:185], v133 offset:33792
	ds_read_b64 v[186:187], v133 offset:33824
	ds_read_b64 v[188:189], v133 offset:34816
	ds_read_b64 v[190:191], v133 offset:34848
	ds_read_b64 v[192:193], v133 offset:35840
	ds_read_b64 v[194:195], v133 offset:35872
	s_waitcnt lgkmcnt(7)
	v_lshlrev_b32_e32 v144, 16, v180
	v_and_b32_e32 v145, 0xffff0000, v180
	v_lshlrev_b32_e32 v146, 16, v181
	v_and_b32_e32 v147, 0xffff0000, v181
	v_fmac_f32_e32 v126, s58, v144
	v_fmac_f32_e32 v127, s58, v145
	v_fmac_f32_e32 v128, s58, v146
	v_fmac_f32_e32 v129, s58, v147
	v_mov_b32_e32 v196, v126
	v_mul_f32_e32 v197, v126, v126
	v_mov_b32_e32 v130, v127
	v_mul_f32_e32 v142, v127, v127
	v_add_f32_e32 v196, v196, v128
	v_fmac_f32_e32 v197, v128, v128
	v_add_f32_e32 v130, v130, v129
	v_fmac_f32_e32 v142, v129, v129
	s_waitcnt lgkmcnt(6)
	v_lshlrev_b32_e32 v148, 16, v182
	v_and_b32_e32 v149, 0xffff0000, v182
	v_lshlrev_b32_e32 v150, 16, v183
	v_and_b32_e32 v151, 0xffff0000, v183
	v_fmac_f32_e32 v122, s58, v148
	v_fmac_f32_e32 v123, s58, v149
	v_fmac_f32_e32 v124, s58, v150
	v_fmac_f32_e32 v125, s58, v151
	v_add_f32_e32 v196, v196, v122
	v_fmac_f32_e32 v197, v122, v122
	v_add_f32_e32 v130, v130, v123
	v_fmac_f32_e32 v142, v123, v123
	v_add_f32_e32 v196, v196, v124
	v_fmac_f32_e32 v197, v124, v124
	v_add_f32_e32 v130, v130, v125
	v_fmac_f32_e32 v142, v125, v125
	s_waitcnt lgkmcnt(5)
	v_lshlrev_b32_e32 v152, 16, v184
	v_and_b32_e32 v153, 0xffff0000, v184
	v_lshlrev_b32_e32 v154, 16, v185
	v_and_b32_e32 v155, 0xffff0000, v185
	v_fmac_f32_e32 v118, s58, v152
	v_fmac_f32_e32 v119, s58, v153
	v_fmac_f32_e32 v120, s58, v154
	v_fmac_f32_e32 v121, s58, v155
	v_add_f32_e32 v196, v196, v118
	v_fmac_f32_e32 v197, v118, v118
	v_add_f32_e32 v130, v130, v119
	v_fmac_f32_e32 v142, v119, v119
	v_add_f32_e32 v196, v196, v120
	v_fmac_f32_e32 v197, v120, v120
	v_add_f32_e32 v130, v130, v121
	v_fmac_f32_e32 v142, v121, v121
	s_waitcnt lgkmcnt(4)
	v_lshlrev_b32_e32 v156, 16, v186
	v_and_b32_e32 v157, 0xffff0000, v186
	v_lshlrev_b32_e32 v158, 16, v187
	v_and_b32_e32 v159, 0xffff0000, v187
	v_fmac_f32_e32 v114, s58, v156
	v_fmac_f32_e32 v115, s58, v157
	v_fmac_f32_e32 v116, s58, v158
	v_fmac_f32_e32 v117, s58, v159
	v_add_f32_e32 v196, v196, v114
	v_fmac_f32_e32 v197, v114, v114
	v_add_f32_e32 v130, v130, v115
	v_fmac_f32_e32 v142, v115, v115
	v_add_f32_e32 v196, v196, v116
	v_fmac_f32_e32 v197, v116, v116
	v_add_f32_e32 v130, v130, v117
	v_fmac_f32_e32 v142, v117, v117
	s_waitcnt lgkmcnt(3)
	v_lshlrev_b32_e32 v160, 16, v188
	v_and_b32_e32 v161, 0xffff0000, v188
	v_lshlrev_b32_e32 v162, 16, v189
	v_and_b32_e32 v163, 0xffff0000, v189
	v_fmac_f32_e32 v110, s58, v160
	v_fmac_f32_e32 v111, s58, v161
	v_fmac_f32_e32 v112, s58, v162
	v_fmac_f32_e32 v113, s58, v163
	v_add_f32_e32 v196, v196, v110
	v_fmac_f32_e32 v197, v110, v110
	v_add_f32_e32 v130, v130, v111
	v_fmac_f32_e32 v142, v111, v111
	v_add_f32_e32 v196, v196, v112
	v_fmac_f32_e32 v197, v112, v112
	v_add_f32_e32 v130, v130, v113
	v_fmac_f32_e32 v142, v113, v113
	s_waitcnt lgkmcnt(2)
	v_lshlrev_b32_e32 v164, 16, v190
	v_and_b32_e32 v165, 0xffff0000, v190
	v_lshlrev_b32_e32 v166, 16, v191
	v_and_b32_e32 v167, 0xffff0000, v191
	v_fmac_f32_e32 v106, s58, v164
	v_fmac_f32_e32 v107, s58, v165
	v_fmac_f32_e32 v108, s58, v166
	v_fmac_f32_e32 v109, s58, v167
	v_add_f32_e32 v196, v196, v106
	v_fmac_f32_e32 v197, v106, v106
	v_add_f32_e32 v130, v130, v107
	v_fmac_f32_e32 v142, v107, v107
	v_add_f32_e32 v196, v196, v108
	v_fmac_f32_e32 v197, v108, v108
	v_add_f32_e32 v130, v130, v109
	v_fmac_f32_e32 v142, v109, v109
	s_waitcnt lgkmcnt(1)
	v_lshlrev_b32_e32 v168, 16, v192
	v_and_b32_e32 v169, 0xffff0000, v192
	v_lshlrev_b32_e32 v170, 16, v193
	v_and_b32_e32 v171, 0xffff0000, v193
	v_fmac_f32_e32 v102, s58, v168
	v_fmac_f32_e32 v103, s58, v169
	v_fmac_f32_e32 v104, s58, v170
	v_fmac_f32_e32 v105, s58, v171
	v_add_f32_e32 v196, v196, v102
	v_fmac_f32_e32 v197, v102, v102
	v_add_f32_e32 v130, v130, v103
	v_fmac_f32_e32 v142, v103, v103
	v_add_f32_e32 v196, v196, v104
	v_fmac_f32_e32 v197, v104, v104
	v_add_f32_e32 v130, v130, v105
	v_fmac_f32_e32 v142, v105, v105
	s_waitcnt lgkmcnt(0)
	v_lshlrev_b32_e32 v172, 16, v194
	v_and_b32_e32 v173, 0xffff0000, v194
	v_lshlrev_b32_e32 v174, 16, v195
	v_and_b32_e32 v175, 0xffff0000, v195
	v_fmac_f32_e32 v66, s58, v172
	v_fmac_f32_e32 v67, s58, v173
	v_fmac_f32_e32 v68, s58, v174
	v_fmac_f32_e32 v69, s58, v175
	v_add_f32_e32 v196, v196, v66
	v_fmac_f32_e32 v197, v66, v66
	v_add_f32_e32 v130, v130, v67
	v_fmac_f32_e32 v142, v67, v67
	v_add_f32_e32 v196, v196, v68
	v_fmac_f32_e32 v197, v68, v68
	v_add_f32_e32 v130, v130, v69
	v_fmac_f32_e32 v142, v69, v69
	v_add_f32_e32 v196, v196, v130
	v_add_f32_e32 v197, v197, v142
	v_mov_b32_e32 v198, v196
	v_mov_b32_e32 v199, v197
	s_nop 1
	v_permlane16_swap_b32 v198, v196
	v_permlane16_swap_b32 v199, v197
	v_add_f32_e32 v196, v196, v198
	v_add_f32_e32 v197, v197, v199
	v_mov_b32_e32 v198, v196
	v_mov_b32_e32 v199, v197
	s_nop 1
	v_permlane32_swap_b32 v198, v196
	v_permlane32_swap_b32 v199, v197
	v_add_f32_e32 v196, v196, v198
	v_add_f32_e32 v197, v197, v199
	s_mov_b64 exec, 0xffff
	ds_write_b64 v134, v[196:197]
	s_mov_b64 exec, -1
	s_waitcnt lgkmcnt(0)
	s_barrier
; DI unsigned pk2(float lo, float hi) { const f32x2 v = {lo, hi}; const bf16x2_t b = __builtin_convertvector(v, bf16x2_t); return __builtin_bit_cast(unsigned, b); }
; DI size_t xb_off(int tok, int col) { return ((size_t)(((tok >> 7) * 32 + (col >> 5)) * 128 + (tok & 127))) * 32 + (col & 31); }
; DI void unit_O(const Params& p, char* lds, int l, int tile, int glu_tiles, int tile_b) {
;     ...
;         if (half == 0) issue_x(1);
; #pragma unroll
;         for (int mh = 0; mh < 2; ++mh) {
;             const int mt = half * 2 + mh, rl = mh * 16 + l15, row = mt * 16 + l15;
;             float s = 0.f, ss = 0.f;
; #pragma unroll
;             for (int w = 0; w < 4; ++w) { const f32x4 v = *(const f32x4*)&red[rl * 16 + 4 * w]; s += v[0] + v[2]; ss += v[1] + v[3]; }
;             const float mu = s * (1.f / 1024.f);
;             const float var = ss * (1.f / 1024.f) - mu * mu;
;             const float rs = rsqrtf(var + LN_EPS);
;             float* orow = xo + (r0 + row) * 1024 + wid * 128 + quad * 4;
;             bf16_t* brow = xbo + xb_off((int)r0 + row, wid * 128) + quad * 4;
;             const float* gp = GB + wid * 128 + quad * 4;
; #pragma unroll
;             for (int nt = 0; nt < 8; ++nt) {
;                 const f32x4 g = *(const f32x4*)(gp + nt * 16), bb = *(const f32x4*)(gp + 1024 + nt * 16);
;                 f32x4 o;
; #pragma unroll
;                 for (int i = 0; i < 4; ++i) o[i] = (acc[mt][nt][i] - mu) * rs * g[i] + bb[i];
;                 if (l == 0) *(u32x2*)(brow + (nt >> 1) * 4096 + (nt & 1) * 16) = (u32x2){pk2(o[0], o[1]), pk2(o[2], o[3])};
;                 else *(f32x4*)(orow + nt * 16) = o;
	s_add_u32 s92, s96, 0xc00
	s_addc_u32 s93, s97, 0
	s_add_u32 s40, s91, 0x8000
	s_mov_b32 m0, s40
	s_nop 0
	global_load_lds_dwordx4 v208, s[92:93]
	s_add_u32 s92, s92, 0x2000
	s_addc_u32 s93, s93, 0
	s_add_u32 m0, m0, 0x400
	s_nop 0
	global_load_lds_dwordx4 v208, s[92:93]
	s_add_u32 s92, s92, 0x2000
	s_addc_u32 s93, s93, 0
	s_add_u32 m0, m0, 0x400
	s_nop 0
	global_load_lds_dwordx4 v208, s[92:93]
	s_add_u32 s92, s92, 0x2000
	s_addc_u32 s93, s93, 0
	s_add_u32 m0, m0, 0x400
	s_nop 0
	global_load_lds_dwordx4 v208, s[92:93]
	ds_read_b128 v[160:163], v135 offset:0
	ds_read_b128 v[164:167], v135 offset:16
	ds_read_b128 v[168:171], v135 offset:32
	ds_read_b128 v[172:175], v135 offset:48
	s_waitcnt lgkmcnt(0)
	v_add_f32_e32 v160, v160, v162
	v_add_f32_e32 v161, v161, v163
	v_add_f32_e32 v164, v164, v166
	v_add_f32_e32 v165, v165, v167
	v_add_f32_e32 v168, v168, v170
	v_add_f32_e32 v169, v169, v171
	v_add_f32_e32 v172, v172, v174
	v_add_f32_e32 v173, v173, v175
	v_add_f32_e32 v160, v160, v164
	v_add_f32_e32 v161, v161, v165
	v_add_f32_e32 v168, v168, v172
	v_add_f32_e32 v169, v169, v173
	v_add_f32_e32 v160, v160, v168
	v_add_f32_e32 v161, v161, v169
	v_mul_f32_e32 v192, 0x3a800000, v160
	v_mul_f32_e32 v193, 0x3a800000, v161
	v_fma_f32 v193, -v192, v192, v193
	v_add_f32_e32 v193, 0x3727c5ac, v193
	v_rsq_f32_e32 v193, v193
	s_nop 0
	ds_read_b128 v[176:179], v136
	ds_read_b128 v[180:183], v136 offset:4096
	ds_read_b128 v[184:187], v136 offset:64
	ds_read_b128 v[188:191], v136 offset:4160
	s_waitcnt lgkmcnt(2)
	v_sub_f32_e32 v126, v126, v192
	v_mul_f32_e32 v126, v126, v193
	v_fma_f32 v126, v176, v126, v180
	v_sub_f32_e32 v127, v127, v192
	v_mul_f32_e32 v127, v127, v193
	v_fma_f32 v127, v177, v127, v181
	v_sub_f32_e32 v128, v128, v192
	v_mul_f32_e32 v128, v128, v193
	v_fma_f32 v128, v178, v128, v182
	v_sub_f32_e32 v129, v129, v192
	v_mul_f32_e32 v129, v129, v193
	v_fma_f32 v129, v179, v129, v183
	ds_read_b128 v[176:179], v136 offset:128
	ds_read_b128 v[180:183], v136 offset:4224
	s_waitcnt lgkmcnt(2)
	v_sub_f32_e32 v122, v122, v192
	v_mul_f32_e32 v122, v122, v193
	v_fma_f32 v122, v184, v122, v188
	v_sub_f32_e32 v123, v123, v192
	v_mul_f32_e32 v123, v123, v193
	v_fma_f32 v123, v185, v123, v189
	v_sub_f32_e32 v124, v124, v192
	v_mul_f32_e32 v124, v124, v193
	v_fma_f32 v124, v186, v124, v190
	v_sub_f32_e32 v125, v125, v192
	v_mul_f32_e32 v125, v125, v193
	v_fma_f32 v125, v187, v125, v191
	ds_read_b128 v[184:187], v136 offset:192
	ds_read_b128 v[188:191], v136 offset:4288
	s_waitcnt lgkmcnt(2)
	v_sub_f32_e32 v118, v118, v192
	v_mul_f32_e32 v118, v118, v193
	v_fma_f32 v118, v176, v118, v180
	v_sub_f32_e32 v119, v119, v192
	v_mul_f32_e32 v119, v119, v193
	v_fma_f32 v119, v177, v119, v181
	v_sub_f32_e32 v120, v120, v192
	v_mul_f32_e32 v120, v120, v193
	v_fma_f32 v120, v178, v120, v182
	v_sub_f32_e32 v121, v121, v192
	v_mul_f32_e32 v121, v121, v193
	v_fma_f32 v121, v179, v121, v183
	ds_read_b128 v[176:179], v136 offset:256
	ds_read_b128 v[180:183], v136 offset:4352
	s_waitcnt lgkmcnt(2)
	v_sub_f32_e32 v114, v114, v192
	v_mul_f32_e32 v114, v114, v193
	v_fma_f32 v114, v184, v114, v188
	v_sub_f32_e32 v115, v115, v192
	v_mul_f32_e32 v115, v115, v193
	v_fma_f32 v115, v185, v115, v189
	v_sub_f32_e32 v116, v116, v192
	v_mul_f32_e32 v116, v116, v193
	v_fma_f32 v116, v186, v116, v190
	v_sub_f32_e32 v117, v117, v192
	v_mul_f32_e32 v117, v117, v193
	v_fma_f32 v117, v187, v117, v191
	ds_read_b128 v[184:187], v136 offset:320
	ds_read_b128 v[188:191], v136 offset:4416
	s_waitcnt lgkmcnt(2)
	v_sub_f32_e32 v110, v110, v192
	v_mul_f32_e32 v110, v110, v193
	v_fma_f32 v110, v176, v110, v180
	v_sub_f32_e32 v111, v111, v192
	v_mul_f32_e32 v111, v111, v193
	v_fma_f32 v111, v177, v111, v181
	v_sub_f32_e32 v112, v112, v192
	v_mul_f32_e32 v112, v112, v193
	v_fma_f32 v112, v178, v112, v182
	v_sub_f32_e32 v113, v113, v192
	v_mul_f32_e32 v113, v113, v193
	v_fma_f32 v113, v179, v113, v183
	ds_read_b128 v[176:179], v136 offset:384
	ds_read_b128 v[180:183], v136 offset:4480
	s_waitcnt lgkmcnt(2)
	v_sub_f32_e32 v106, v106, v192
	v_mul_f32_e32 v106, v106, v193
	v_fma_f32 v106, v184, v106, v188
	v_sub_f32_e32 v107, v107, v192
	v_mul_f32_e32 v107, v107, v193
	v_fma_f32 v107, v185, v107, v189
	v_sub_f32_e32 v108, v108, v192
	v_mul_f32_e32 v108, v108, v193
	v_fma_f32 v108, v186, v108, v190
	v_sub_f32_e32 v109, v109, v192
	v_mul_f32_e32 v109, v109, v193
	v_fma_f32 v109, v187, v109, v191
	ds_read_b128 v[184:187], v136 offset:448
	ds_read_b128 v[188:191], v136 offset:4544
	s_waitcnt lgkmcnt(2)
	v_sub_f32_e32 v102, v102, v192
	v_mul_f32_e32 v102, v102, v193
	v_fma_f32 v102, v176, v102, v180
	v_sub_f32_e32 v103, v103, v192
	v_mul_f32_e32 v103, v103, v193
	v_fma_f32 v103, v177, v103, v181
	v_sub_f32_e32 v104, v104, v192
	v_mul_f32_e32 v104, v104, v193
	v_fma_f32 v104, v178, v104, v182
	v_sub_f32_e32 v105, v105, v192
	v_mul_f32_e32 v105, v105, v193
	v_fma_f32 v105, v179, v105, v183
	s_waitcnt lgkmcnt(0)
	v_sub_f32_e32 v66, v66, v192
	v_mul_f32_e32 v66, v66, v193
	v_fma_f32 v66, v184, v66, v188
	v_sub_f32_e32 v67, v67, v192
	v_mul_f32_e32 v67, v67, v193
	v_fma_f32 v67, v185, v67, v189
	v_sub_f32_e32 v68, v68, v192
	v_mul_f32_e32 v68, v68, v193
	v_fma_f32 v68, v186, v68, v190
	v_sub_f32_e32 v69, v69, v192
	v_mul_f32_e32 v69, v69, v193
	v_fma_f32 v69, v187, v69, v191
	s_waitcnt vmcnt(4) lgkmcnt(0)
	s_barrier
; DI float bf2f(unsigned b) { return __uint_as_float(b << 16); }
; DI void unit_O(const Params& p, char* lds, int l, int tile, int glu_tiles, int tile_b) {
;     ...
;         float s2[2], ss2[2];
; #pragma unroll
;         for (int mh = 0; mh < 2; ++mh) {
;             const int mt = half * 2 + mh, rl = mh * 16 + l15;
;             float s = 0.f, ss = 0.f;
; #pragma unroll
;             for (int nt = 0; nt < 8; ++nt) {
;                 f32x4 xr;
;                 if (l == 0) {
;                     const int chunk = wid * 32 + nt * 4 + quad;
;                     xr = *(const f32x4*)(XR + rl * 4096 + ((chunk ^ l15) << 4));
;                 } else {
;                     const u32x2 hb = *(const u32x2*)(XR + ((wid * 4 + (nt >> 1)) * 32 + rl) * 64 + (nt & 1) * 32 + quad * 8);
;                     xr = (f32x4){bf2f(hb[0] & 0xffffu), bf2f(hb[0] >> 16), bf2f(hb[1] & 0xffffu), bf2f(hb[1] >> 16)};
;                 }
; #pragma unroll
;                 for (int i = 0; i < 4; ++i) { const float v = acc[mt][nt][i] + DN_ALPHA * xr[i]; acc[mt][nt][i] = v; s += v; ss += v * v; }
;             }
;             s2[mh] = s; ss2[mh] = ss;
;         }
; #pragma unroll
;         for (int mh = 0; mh < 2; ++mh) { s2[mh] += __shfl_xor(s2[mh], 16); ss2[mh] += __shfl_xor(ss2[mh], 16); }
; #pragma unroll
;         for (int mh = 0; mh < 2; ++mh) { s2[mh] += __shfl_xor(s2[mh], 32); ss2[mh] += __shfl_xor(ss2[mh], 32); }
;         if (quad == 0) {
; #pragma unroll
;             for (int mh = 0; mh < 2; ++mh) *(f32x2*)&red[((mh * 16 + l15) * 8 + wid) * 2] = (f32x2){s2[mh], ss2[mh]};
;         }
;         __syncthreads();
	ds_read_b64 v[180:181], v133 offset:0
	ds_read_b64 v[182:183], v133 offset:32
	ds_read_b64 v[184:185], v133 offset:1024
	ds_read_b64 v[186:187], v133 offset:1056
	ds_read_b64 v[188:189], v133 offset:2048
	ds_read_b64 v[190:191], v133 offset:2080
	ds_read_b64 v[192:193], v133 offset:3072
	ds_read_b64 v[194:195], v133 offset:3104
	s_waitcnt lgkmcnt(7)
	v_lshlrev_b32_e32 v144, 16, v180
	v_and_b32_e32 v145, 0xffff0000, v180
	v_lshlrev_b32_e32 v146, 16, v181
	v_and_b32_e32 v147, 0xffff0000, v181
	v_fmac_f32_e32 v34, s58, v144
	v_fmac_f32_e32 v35, s58, v145
	v_fmac_f32_e32 v36, s58, v146
	v_fmac_f32_e32 v37, s58, v147
	v_mov_b32_e32 v196, v34
	v_mul_f32_e32 v197, v34, v34
	v_mov_b32_e32 v130, v35
	v_mul_f32_e32 v142, v35, v35
	v_add_f32_e32 v196, v196, v36
	v_fmac_f32_e32 v197, v36, v36
	v_add_f32_e32 v130, v130, v37
	v_fmac_f32_e32 v142, v37, v37
	s_waitcnt lgkmcnt(6)
	v_lshlrev_b32_e32 v148, 16, v182
	v_and_b32_e32 v149, 0xffff0000, v182
	v_lshlrev_b32_e32 v150, 16, v183
	v_and_b32_e32 v151, 0xffff0000, v183
	v_fmac_f32_e32 v30, s58, v148
	v_fmac_f32_e32 v31, s58, v149
	v_fmac_f32_e32 v32, s58, v150
	v_fmac_f32_e32 v33, s58, v151
	v_add_f32_e32 v196, v196, v30
	v_fmac_f32_e32 v197, v30, v30
	v_add_f32_e32 v130, v130, v31
	v_fmac_f32_e32 v142, v31, v31
	v_add_f32_e32 v196, v196, v32
	v_fmac_f32_e32 v197, v32, v32
	v_add_f32_e32 v130, v130, v33
	v_fmac_f32_e32 v142, v33, v33
	s_waitcnt lgkmcnt(5)
	v_lshlrev_b32_e32 v152, 16, v184
	v_and_b32_e32 v153, 0xffff0000, v184
	v_lshlrev_b32_e32 v154, 16, v185
	v_and_b32_e32 v155, 0xffff0000, v185
	v_fmac_f32_e32 v26, s58, v152
	v_fmac_f32_e32 v27, s58, v153
	v_fmac_f32_e32 v28, s58, v154
	v_fmac_f32_e32 v29, s58, v155
	v_add_f32_e32 v196, v196, v26
	v_fmac_f32_e32 v197, v26, v26
	v_add_f32_e32 v130, v130, v27
	v_fmac_f32_e32 v142, v27, v27
	v_add_f32_e32 v196, v196, v28
	v_fmac_f32_e32 v197, v28, v28
	v_add_f32_e32 v130, v130, v29
	v_fmac_f32_e32 v142, v29, v29
	s_waitcnt lgkmcnt(4)
	v_lshlrev_b32_e32 v156, 16, v186
	v_and_b32_e32 v157, 0xffff0000, v186
	v_lshlrev_b32_e32 v158, 16, v187
	v_and_b32_e32 v159, 0xffff0000, v187
	v_fmac_f32_e32 v22, s58, v156
	v_fmac_f32_e32 v23, s58, v157
	v_fmac_f32_e32 v24, s58, v158
	v_fmac_f32_e32 v25, s58, v159
	v_add_f32_e32 v196, v196, v22
	v_fmac_f32_e32 v197, v22, v22
	v_add_f32_e32 v130, v130, v23
	v_fmac_f32_e32 v142, v23, v23
	v_add_f32_e32 v196, v196, v24
	v_fmac_f32_e32 v197, v24, v24
	v_add_f32_e32 v130, v130, v25
	v_fmac_f32_e32 v142, v25, v25
	s_waitcnt lgkmcnt(3)
	v_lshlrev_b32_e32 v160, 16, v188
	v_and_b32_e32 v161, 0xffff0000, v188
	v_lshlrev_b32_e32 v162, 16, v189
	v_and_b32_e32 v163, 0xffff0000, v189
	v_fmac_f32_e32 v18, s58, v160
	v_fmac_f32_e32 v19, s58, v161
	v_fmac_f32_e32 v20, s58, v162
	v_fmac_f32_e32 v21, s58, v163
	v_add_f32_e32 v196, v196, v18
	v_fmac_f32_e32 v197, v18, v18
	v_add_f32_e32 v130, v130, v19
	v_fmac_f32_e32 v142, v19, v19
	v_add_f32_e32 v196, v196, v20
	v_fmac_f32_e32 v197, v20, v20
	v_add_f32_e32 v130, v130, v21
	v_fmac_f32_e32 v142, v21, v21
	s_waitcnt lgkmcnt(2)
	v_lshlrev_b32_e32 v164, 16, v190
	v_and_b32_e32 v165, 0xffff0000, v190
	v_lshlrev_b32_e32 v166, 16, v191
	v_and_b32_e32 v167, 0xffff0000, v191
	v_fmac_f32_e32 v14, s58, v164
	v_fmac_f32_e32 v15, s58, v165
	v_fmac_f32_e32 v16, s58, v166
	v_fmac_f32_e32 v17, s58, v167
	v_add_f32_e32 v196, v196, v14
	v_fmac_f32_e32 v197, v14, v14
	v_add_f32_e32 v130, v130, v15
	v_fmac_f32_e32 v142, v15, v15
	v_add_f32_e32 v196, v196, v16
	v_fmac_f32_e32 v197, v16, v16
	v_add_f32_e32 v130, v130, v17
	v_fmac_f32_e32 v142, v17, v17
	s_waitcnt lgkmcnt(1)
	v_lshlrev_b32_e32 v168, 16, v192
	v_and_b32_e32 v169, 0xffff0000, v192
	v_lshlrev_b32_e32 v170, 16, v193
	v_and_b32_e32 v171, 0xffff0000, v193
	v_fmac_f32_e32 v10, s58, v168
	v_fmac_f32_e32 v11, s58, v169
	v_fmac_f32_e32 v12, s58, v170
	v_fmac_f32_e32 v13, s58, v171
	v_add_f32_e32 v196, v196, v10
	v_fmac_f32_e32 v197, v10, v10
	v_add_f32_e32 v130, v130, v11
	v_fmac_f32_e32 v142, v11, v11
	v_add_f32_e32 v196, v196, v12
	v_fmac_f32_e32 v197, v12, v12
	v_add_f32_e32 v130, v130, v13
	v_fmac_f32_e32 v142, v13, v13
	s_waitcnt lgkmcnt(0)
	v_lshlrev_b32_e32 v172, 16, v194
	v_and_b32_e32 v173, 0xffff0000, v194
	v_lshlrev_b32_e32 v174, 16, v195
	v_and_b32_e32 v175, 0xffff0000, v195
	v_fmac_f32_e32 v6, s58, v172
	v_fmac_f32_e32 v7, s58, v173
	v_fmac_f32_e32 v8, s58, v174
	v_fmac_f32_e32 v9, s58, v175
	v_add_f32_e32 v196, v196, v6
	v_fmac_f32_e32 v197, v6, v6
	v_add_f32_e32 v130, v130, v7
	v_fmac_f32_e32 v142, v7, v7
	v_add_f32_e32 v196, v196, v8
	v_fmac_f32_e32 v197, v8, v8
	v_add_f32_e32 v130, v130, v9
	v_fmac_f32_e32 v142, v9, v9
	v_add_f32_e32 v196, v196, v130
	v_add_f32_e32 v197, v197, v142
	v_mov_b32_e32 v198, v196
	v_mov_b32_e32 v199, v197
	s_nop 1
	v_permlane16_swap_b32 v198, v196
	v_permlane16_swap_b32 v199, v197
	v_add_f32_e32 v196, v196, v198
	v_add_f32_e32 v197, v197, v199
	v_mov_b32_e32 v198, v196
	v_mov_b32_e32 v199, v197
	s_nop 1
	v_permlane32_swap_b32 v198, v196
	v_permlane32_swap_b32 v199, v197
	v_add_f32_e32 v196, v196, v198
	v_add_f32_e32 v197, v197, v199
	s_mov_b64 exec, 0xffff
	ds_write_b64 v134, v[196:197]
	s_mov_b64 exec, -1
	s_waitcnt lgkmcnt(0)
	s_barrier
; DI unsigned pk2(float lo, float hi) { const f32x2 v = {lo, hi}; const bf16x2_t b = __builtin_convertvector(v, bf16x2_t); return __builtin_bit_cast(unsigned, b); }
; DI size_t xb_off(int tok, int col) { return ((size_t)(((tok >> 7) * 32 + (col >> 5)) * 128 + (tok & 127))) * 32 + (col & 31); }
; DI void unit_O(const Params& p, char* lds, int l, int tile, int glu_tiles, int tile_b) {
;     ...
; #pragma unroll
;         for (int mh = 0; mh < 2; ++mh) {
;             const int mt = half * 2 + mh, rl = mh * 16 + l15, row = mt * 16 + l15;
;             float s = 0.f, ss = 0.f;
; #pragma unroll
;             for (int w = 0; w < 4; ++w) { const f32x4 v = *(const f32x4*)&red[rl * 16 + 4 * w]; s += v[0] + v[2]; ss += v[1] + v[3]; }
;             const float mu = s * (1.f / 1024.f);
;             const float var = ss * (1.f / 1024.f) - mu * mu;
;             const float rs = rsqrtf(var + LN_EPS);
;             float* orow = xo + (r0 + row) * 1024 + wid * 128 + quad * 4;
;             bf16_t* brow = xbo + xb_off((int)r0 + row, wid * 128) + quad * 4;
;             const float* gp = GB + wid * 128 + quad * 4;
; #pragma unroll
;             for (int nt = 0; nt < 8; ++nt) {
;                 const f32x4 g = *(const f32x4*)(gp + nt * 16), bb = *(const f32x4*)(gp + 1024 + nt * 16);
;                 f32x4 o;
; #pragma unroll
;                 for (int i = 0; i < 4; ++i) o[i] = (acc[mt][nt][i] - mu) * rs * g[i] + bb[i];
;                 if (l == 0) *(u32x2*)(brow + (nt >> 1) * 4096 + (nt & 1) * 16) = (u32x2){pk2(o[0], o[1]), pk2(o[2], o[3])};
;                 else *(f32x4*)(orow + nt * 16) = o;
;             }
;         }
	ds_read_b128 v[160:163], v135 offset:0
	ds_read_b128 v[164:167], v135 offset:16
	ds_read_b128 v[168:171], v135 offset:32
	ds_read_b128 v[172:175], v135 offset:48
	s_waitcnt lgkmcnt(0)
	v_add_f32_e32 v160, v160, v162
	v_add_f32_e32 v161, v161, v163
	v_add_f32_e32 v164, v164, v166
	v_add_f32_e32 v165, v165, v167
	v_add_f32_e32 v168, v168, v170
	v_add_f32_e32 v169, v169, v171
	v_add_f32_e32 v172, v172, v174
	v_add_f32_e32 v173, v173, v175
	v_add_f32_e32 v160, v160, v164
	v_add_f32_e32 v161, v161, v165
	v_add_f32_e32 v168, v168, v172
	v_add_f32_e32 v169, v169, v173
	v_add_f32_e32 v160, v160, v168
	v_add_f32_e32 v161, v161, v169
	v_mul_f32_e32 v192, 0x3a800000, v160
	v_mul_f32_e32 v193, 0x3a800000, v161
	v_fma_f32 v193, -v192, v192, v193
	v_add_f32_e32 v193, 0x3727c5ac, v193
	v_rsq_f32_e32 v193, v193
	s_nop 0
	ds_read_b128 v[176:179], v136
	ds_read_b128 v[180:183], v136 offset:4096
	ds_read_b128 v[184:187], v136 offset:64
	ds_read_b128 v[188:191], v136 offset:4160
	s_waitcnt lgkmcnt(2)
	v_sub_f32_e32 v34, v34, v192
	v_mul_f32_e32 v34, v34, v193
	v_fma_f32 v34, v176, v34, v180
	v_sub_f32_e32 v35, v35, v192
	v_mul_f32_e32 v35, v35, v193
	v_fma_f32 v35, v177, v35, v181
	v_sub_f32_e32 v36, v36, v192
	v_mul_f32_e32 v36, v36, v193
	v_fma_f32 v36, v178, v36, v182
	v_sub_f32_e32 v37, v37, v192
	v_mul_f32_e32 v37, v37, v193
	v_fma_f32 v37, v179, v37, v183
	ds_read_b128 v[176:179], v136 offset:128
	ds_read_b128 v[180:183], v136 offset:4224
	s_waitcnt lgkmcnt(2)
	v_sub_f32_e32 v30, v30, v192
	v_mul_f32_e32 v30, v30, v193
	v_fma_f32 v30, v184, v30, v188
	v_sub_f32_e32 v31, v31, v192
	v_mul_f32_e32 v31, v31, v193
	v_fma_f32 v31, v185, v31, v189
	v_sub_f32_e32 v32, v32, v192
	v_mul_f32_e32 v32, v32, v193
	v_fma_f32 v32, v186, v32, v190
	v_sub_f32_e32 v33, v33, v192
	v_mul_f32_e32 v33, v33, v193
	v_fma_f32 v33, v187, v33, v191
	ds_read_b128 v[184:187], v136 offset:192
	ds_read_b128 v[188:191], v136 offset:4288
	s_waitcnt lgkmcnt(2)
	v_sub_f32_e32 v26, v26, v192
	v_mul_f32_e32 v26, v26, v193
	v_fma_f32 v26, v176, v26, v180
	v_sub_f32_e32 v27, v27, v192
	v_mul_f32_e32 v27, v27, v193
	v_fma_f32 v27, v177, v27, v181
	v_sub_f32_e32 v28, v28, v192
	v_mul_f32_e32 v28, v28, v193
	v_fma_f32 v28, v178, v28, v182
	v_sub_f32_e32 v29, v29, v192
	v_mul_f32_e32 v29, v29, v193
	v_fma_f32 v29, v179, v29, v183
	ds_read_b128 v[176:179], v136 offset:256
	ds_read_b128 v[180:183], v136 offset:4352
	s_waitcnt lgkmcnt(2)
	v_sub_f32_e32 v22, v22, v192
	v_mul_f32_e32 v22, v22, v193
	v_fma_f32 v22, v184, v22, v188
	v_sub_f32_e32 v23, v23, v192
	v_mul_f32_e32 v23, v23, v193
	v_fma_f32 v23, v185, v23, v189
	v_sub_f32_e32 v24, v24, v192
	v_mul_f32_e32 v24, v24, v193
	v_fma_f32 v24, v186, v24, v190
	v_sub_f32_e32 v25, v25, v192
	v_mul_f32_e32 v25, v25, v193
	v_fma_f32 v25, v187, v25, v191
	ds_read_b128 v[184:187], v136 offset:320
	ds_read_b128 v[188:191], v136 offset:4416
	s_waitcnt lgkmcnt(2)
	v_sub_f32_e32 v18, v18, v192
	v_mul_f32_e32 v18, v18, v193
	v_fma_f32 v18, v176, v18, v180
	v_sub_f32_e32 v19, v19, v192
	v_mul_f32_e32 v19, v19, v193
	v_fma_f32 v19, v177, v19, v181
	v_sub_f32_e32 v20, v20, v192
	v_mul_f32_e32 v20, v20, v193
	v_fma_f32 v20, v178, v20, v182
	v_sub_f32_e32 v21, v21, v192
	v_mul_f32_e32 v21, v21, v193
	v_fma_f32 v21, v179, v21, v183
	ds_read_b128 v[176:179], v136 offset:384
	ds_read_b128 v[180:183], v136 offset:4480
	s_waitcnt lgkmcnt(2)
	v_sub_f32_e32 v14, v14, v192
	v_mul_f32_e32 v14, v14, v193
	v_fma_f32 v14, v184, v14, v188
	v_sub_f32_e32 v15, v15, v192
	v_mul_f32_e32 v15, v15, v193
	v_fma_f32 v15, v185, v15, v189
	v_sub_f32_e32 v16, v16, v192
	v_mul_f32_e32 v16, v16, v193
	v_fma_f32 v16, v186, v16, v190
	v_sub_f32_e32 v17, v17, v192
	v_mul_f32_e32 v17, v17, v193
	v_fma_f32 v17, v187, v17, v191
	ds_read_b128 v[184:187], v136 offset:448
	ds_read_b128 v[188:191], v136 offset:4544
	s_waitcnt lgkmcnt(2)
	v_sub_f32_e32 v10, v10, v192
	v_mul_f32_e32 v10, v10, v193
	v_fma_f32 v10, v176, v10, v180
	v_sub_f32_e32 v11, v11, v192
	v_mul_f32_e32 v11, v11, v193
	v_fma_f32 v11, v177, v11, v181
	v_sub_f32_e32 v12, v12, v192
	v_mul_f32_e32 v12, v12, v193
	v_fma_f32 v12, v178, v12, v182
	v_sub_f32_e32 v13, v13, v192
	v_mul_f32_e32 v13, v13, v193
	v_fma_f32 v13, v179, v13, v183
	s_waitcnt lgkmcnt(0)
	v_sub_f32_e32 v6, v6, v192
	v_mul_f32_e32 v6, v6, v193
	v_fma_f32 v6, v184, v6, v188
	v_sub_f32_e32 v7, v7, v192
	v_mul_f32_e32 v7, v7, v193
	v_fma_f32 v7, v185, v7, v189
	v_sub_f32_e32 v8, v8, v192
	v_mul_f32_e32 v8, v8, v193
	v_fma_f32 v8, v186, v8, v190
	v_sub_f32_e32 v9, v9, v192
	v_mul_f32_e32 v9, v9, v193
	v_fma_f32 v9, v187, v9, v191
	s_waitcnt vmcnt(0) lgkmcnt(0)
	s_barrier
; DI float bf2f(unsigned b) { return __uint_as_float(b << 16); }
; DI void unit_O(const Params& p, char* lds, int l, int tile, int glu_tiles, int tile_b) {
;     ...
;         float s2[2], ss2[2];
; #pragma unroll
;         for (int mh = 0; mh < 2; ++mh) {
;             const int mt = half * 2 + mh, rl = mh * 16 + l15;
;             float s = 0.f, ss = 0.f;
; #pragma unroll
;             for (int nt = 0; nt < 8; ++nt) {
;                 f32x4 xr;
;                 if (l == 0) {
;                     const int chunk = wid * 32 + nt * 4 + quad;
;                     xr = *(const f32x4*)(XR + rl * 4096 + ((chunk ^ l15) << 4));
;                 } else {
;                     const u32x2 hb = *(const u32x2*)(XR + ((wid * 4 + (nt >> 1)) * 32 + rl) * 64 + (nt & 1) * 32 + quad * 8);
;                     xr = (f32x4){bf2f(hb[0] & 0xffffu), bf2f(hb[0] >> 16), bf2f(hb[1] & 0xffffu), bf2f(hb[1] >> 16)};
;                 }
; #pragma unroll
;                 for (int i = 0; i < 4; ++i) { const float v = acc[mt][nt][i] + DN_ALPHA * xr[i]; acc[mt][nt][i] = v; s += v; ss += v * v; }
;             }
;             s2[mh] = s; ss2[mh] = ss;
;         }
; #pragma unroll
;         for (int mh = 0; mh < 2; ++mh) { s2[mh] += __shfl_xor(s2[mh], 16); ss2[mh] += __shfl_xor(ss2[mh], 16); }
; #pragma unroll
;         for (int mh = 0; mh < 2; ++mh) { s2[mh] += __shfl_xor(s2[mh], 32); ss2[mh] += __shfl_xor(ss2[mh], 32); }
;         if (quad == 0) {
; #pragma unroll
;             for (int mh = 0; mh < 2; ++mh) *(f32x2*)&red[((mh * 16 + l15) * 8 + wid) * 2] = (f32x2){s2[mh], ss2[mh]};
;         }
;         __syncthreads();
	ds_read_b64 v[180:181], v133 offset:32768
	ds_read_b64 v[182:183], v133 offset:32800
	ds_read_b64 v[184:185], v133 offset:33792
	ds_read_b64 v[186:187], v133 offset:33824
	ds_read_b64 v[188:189], v133 offset:34816
	ds_read_b64 v[190:191], v133 offset:34848
	ds_read_b64 v[192:193], v133 offset:35840
	ds_read_b64 v[194:195], v133 offset:35872
	s_waitcnt lgkmcnt(7)
	v_lshlrev_b32_e32 v144, 16, v180
	v_and_b32_e32 v145, 0xffff0000, v180
	v_lshlrev_b32_e32 v146, 16, v181
	v_and_b32_e32 v147, 0xffff0000, v181
	v_fmac_f32_e32 v62, s58, v144
	v_fmac_f32_e32 v63, s58, v145
	v_fmac_f32_e32 v64, s58, v146
	v_fmac_f32_e32 v65, s58, v147
	v_mov_b32_e32 v196, v62
	v_mul_f32_e32 v197, v62, v62
	v_mov_b32_e32 v130, v63
	v_mul_f32_e32 v142, v63, v63
	v_add_f32_e32 v196, v196, v64
	v_fmac_f32_e32 v197, v64, v64
	v_add_f32_e32 v130, v130, v65
	v_fmac_f32_e32 v142, v65, v65
	s_waitcnt lgkmcnt(6)
	v_lshlrev_b32_e32 v148, 16, v182
	v_and_b32_e32 v149, 0xffff0000, v182
	v_lshlrev_b32_e32 v150, 16, v183
	v_and_b32_e32 v151, 0xffff0000, v183
	v_fmac_f32_e32 v58, s58, v148
	v_fmac_f32_e32 v59, s58, v149
	v_fmac_f32_e32 v60, s58, v150
	v_fmac_f32_e32 v61, s58, v151
	v_add_f32_e32 v196, v196, v58
	v_fmac_f32_e32 v197, v58, v58
	v_add_f32_e32 v130, v130, v59
	v_fmac_f32_e32 v142, v59, v59
	v_add_f32_e32 v196, v196, v60
	v_fmac_f32_e32 v197, v60, v60
	v_add_f32_e32 v130, v130, v61
	v_fmac_f32_e32 v142, v61, v61
	s_waitcnt lgkmcnt(5)
	v_lshlrev_b32_e32 v152, 16, v184
	v_and_b32_e32 v153, 0xffff0000, v184
	v_lshlrev_b32_e32 v154, 16, v185
	v_and_b32_e32 v155, 0xffff0000, v185
	v_fmac_f32_e32 v54, s58, v152
	v_fmac_f32_e32 v55, s58, v153
	v_fmac_f32_e32 v56, s58, v154
	v_fmac_f32_e32 v57, s58, v155
	v_add_f32_e32 v196, v196, v54
	v_fmac_f32_e32 v197, v54, v54
	v_add_f32_e32 v130, v130, v55
	v_fmac_f32_e32 v142, v55, v55
	v_add_f32_e32 v196, v196, v56
	v_fmac_f32_e32 v197, v56, v56
	v_add_f32_e32 v130, v130, v57
	v_fmac_f32_e32 v142, v57, v57
	s_waitcnt lgkmcnt(4)
	v_lshlrev_b32_e32 v156, 16, v186
	v_and_b32_e32 v157, 0xffff0000, v186
	v_lshlrev_b32_e32 v158, 16, v187
	v_and_b32_e32 v159, 0xffff0000, v187
	v_fmac_f32_e32 v50, s58, v156
	v_fmac_f32_e32 v51, s58, v157
	v_fmac_f32_e32 v52, s58, v158
	v_fmac_f32_e32 v53, s58, v159
	v_add_f32_e32 v196, v196, v50
	v_fmac_f32_e32 v197, v50, v50
	v_add_f32_e32 v130, v130, v51
	v_fmac_f32_e32 v142, v51, v51
	v_add_f32_e32 v196, v196, v52
	v_fmac_f32_e32 v197, v52, v52
	v_add_f32_e32 v130, v130, v53
	v_fmac_f32_e32 v142, v53, v53
	s_waitcnt lgkmcnt(3)
	v_lshlrev_b32_e32 v160, 16, v188
	v_and_b32_e32 v161, 0xffff0000, v188
	v_lshlrev_b32_e32 v162, 16, v189
	v_and_b32_e32 v163, 0xffff0000, v189
	v_fmac_f32_e32 v46, s58, v160
	v_fmac_f32_e32 v47, s58, v161
	v_fmac_f32_e32 v48, s58, v162
	v_fmac_f32_e32 v49, s58, v163
	v_add_f32_e32 v196, v196, v46
	v_fmac_f32_e32 v197, v46, v46
	v_add_f32_e32 v130, v130, v47
	v_fmac_f32_e32 v142, v47, v47
	v_add_f32_e32 v196, v196, v48
	v_fmac_f32_e32 v197, v48, v48
	v_add_f32_e32 v130, v130, v49
	v_fmac_f32_e32 v142, v49, v49
	s_waitcnt lgkmcnt(2)
	v_lshlrev_b32_e32 v164, 16, v190
	v_and_b32_e32 v165, 0xffff0000, v190
	v_lshlrev_b32_e32 v166, 16, v191
	v_and_b32_e32 v167, 0xffff0000, v191
	v_fmac_f32_e32 v42, s58, v164
	v_fmac_f32_e32 v43, s58, v165
	v_fmac_f32_e32 v44, s58, v166
	v_fmac_f32_e32 v45, s58, v167
	v_add_f32_e32 v196, v196, v42
	v_fmac_f32_e32 v197, v42, v42
	v_add_f32_e32 v130, v130, v43
	v_fmac_f32_e32 v142, v43, v43
	v_add_f32_e32 v196, v196, v44
	v_fmac_f32_e32 v197, v44, v44
	v_add_f32_e32 v130, v130, v45
	v_fmac_f32_e32 v142, v45, v45
	s_waitcnt lgkmcnt(1)
	v_lshlrev_b32_e32 v168, 16, v192
	v_and_b32_e32 v169, 0xffff0000, v192
	v_lshlrev_b32_e32 v170, 16, v193
	v_and_b32_e32 v171, 0xffff0000, v193
	v_fmac_f32_e32 v38, s58, v168
	v_fmac_f32_e32 v39, s58, v169
	v_fmac_f32_e32 v40, s58, v170
	v_fmac_f32_e32 v41, s58, v171
	v_add_f32_e32 v196, v196, v38
	v_fmac_f32_e32 v197, v38, v38
	v_add_f32_e32 v130, v130, v39
	v_fmac_f32_e32 v142, v39, v39
	v_add_f32_e32 v196, v196, v40
	v_fmac_f32_e32 v197, v40, v40
	v_add_f32_e32 v130, v130, v41
	v_fmac_f32_e32 v142, v41, v41
	s_waitcnt lgkmcnt(0)
	v_lshlrev_b32_e32 v172, 16, v194
	v_and_b32_e32 v173, 0xffff0000, v194
	v_lshlrev_b32_e32 v174, 16, v195
	v_and_b32_e32 v175, 0xffff0000, v195
	v_fmac_f32_e32 v2, s58, v172
	v_fmac_f32_e32 v3, s58, v173
	v_fmac_f32_e32 v4, s58, v174
	v_fmac_f32_e32 v5, s58, v175
	v_add_f32_e32 v196, v196, v2
	v_fmac_f32_e32 v197, v2, v2
	v_add_f32_e32 v130, v130, v3
	v_fmac_f32_e32 v142, v3, v3
	v_add_f32_e32 v196, v196, v4
	v_fmac_f32_e32 v197, v4, v4
	v_add_f32_e32 v130, v130, v5
	v_fmac_f32_e32 v142, v5, v5
	v_add_f32_e32 v196, v196, v130
	v_add_f32_e32 v197, v197, v142
	v_mov_b32_e32 v198, v196
	v_mov_b32_e32 v199, v197
	s_nop 1
	v_permlane16_swap_b32 v198, v196
	v_permlane16_swap_b32 v199, v197
	v_add_f32_e32 v196, v196, v198
	v_add_f32_e32 v197, v197, v199
	v_mov_b32_e32 v198, v196
	v_mov_b32_e32 v199, v197
	s_nop 1
	v_permlane32_swap_b32 v198, v196
	v_permlane32_swap_b32 v199, v197
	v_add_f32_e32 v196, v196, v198
	v_add_f32_e32 v197, v197, v199
	s_mov_b64 exec, 0xffff
	ds_write_b64 v134, v[196:197]
	s_mov_b64 exec, -1
	s_waitcnt lgkmcnt(0)
	s_barrier
; DI unsigned pk2(float lo, float hi) { const f32x2 v = {lo, hi}; const bf16x2_t b = __builtin_convertvector(v, bf16x2_t); return __builtin_bit_cast(unsigned, b); }
; DI size_t xb_off(int tok, int col) { return ((size_t)(((tok >> 7) * 32 + (col >> 5)) * 128 + (tok & 127))) * 32 + (col & 31); }
; DI void unit_O(const Params& p, char* lds, int l, int tile, int glu_tiles, int tile_b) {
;     ...
; #pragma unroll
;         for (int mh = 0; mh < 2; ++mh) {
;             const int mt = half * 2 + mh, rl = mh * 16 + l15, row = mt * 16 + l15;
;             float s = 0.f, ss = 0.f;
; #pragma unroll
;             for (int w = 0; w < 4; ++w) { const f32x4 v = *(const f32x4*)&red[rl * 16 + 4 * w]; s += v[0] + v[2]; ss += v[1] + v[3]; }
;             const float mu = s * (1.f / 1024.f);
;             const float var = ss * (1.f / 1024.f) - mu * mu;
;             const float rs = rsqrtf(var + LN_EPS);
;             float* orow = xo + (r0 + row) * 1024 + wid * 128 + quad * 4;
;             bf16_t* brow = xbo + xb_off((int)r0 + row, wid * 128) + quad * 4;
;             const float* gp = GB + wid * 128 + quad * 4;
; #pragma unroll
;             for (int nt = 0; nt < 8; ++nt) {
;                 const f32x4 g = *(const f32x4*)(gp + nt * 16), bb = *(const f32x4*)(gp + 1024 + nt * 16);
;                 f32x4 o;
; #pragma unroll
;                 for (int i = 0; i < 4; ++i) o[i] = (acc[mt][nt][i] - mu) * rs * g[i] + bb[i];
;                 if (l == 0) *(u32x2*)(brow + (nt >> 1) * 4096 + (nt & 1) * 16) = (u32x2){pk2(o[0], o[1]), pk2(o[2], o[3])};
;                 else *(f32x4*)(orow + nt * 16) = o;
;             }
;         }
	ds_read_b128 v[160:163], v135 offset:0
	ds_read_b128 v[164:167], v135 offset:16
	ds_read_b128 v[168:171], v135 offset:32
	ds_read_b128 v[172:175], v135 offset:48
	s_waitcnt lgkmcnt(0)
	v_add_f32_e32 v160, v160, v162
	v_add_f32_e32 v161, v161, v163
	v_add_f32_e32 v164, v164, v166
	v_add_f32_e32 v165, v165, v167
	v_add_f32_e32 v168, v168, v170
	v_add_f32_e32 v169, v169, v171
	v_add_f32_e32 v172, v172, v174
	v_add_f32_e32 v173, v173, v175
	v_add_f32_e32 v160, v160, v164
	v_add_f32_e32 v161, v161, v165
	v_add_f32_e32 v168, v168, v172
	v_add_f32_e32 v169, v169, v173
	v_add_f32_e32 v160, v160, v168
	v_add_f32_e32 v161, v161, v169
	v_mul_f32_e32 v192, 0x3a800000, v160
	v_mul_f32_e32 v193, 0x3a800000, v161
	v_fma_f32 v193, -v192, v192, v193
	v_add_f32_e32 v193, 0x3727c5ac, v193
	v_rsq_f32_e32 v193, v193
	s_nop 0
	ds_read_b128 v[176:179], v136
	ds_read_b128 v[180:183], v136 offset:4096
	ds_read_b128 v[184:187], v136 offset:64
	ds_read_b128 v[188:191], v136 offset:4160
	s_waitcnt lgkmcnt(2)
	v_sub_f32_e32 v62, v62, v192
	v_mul_f32_e32 v62, v62, v193
	v_fma_f32 v62, v176, v62, v180
	v_sub_f32_e32 v63, v63, v192
	v_mul_f32_e32 v63, v63, v193
	v_fma_f32 v63, v177, v63, v181
	v_sub_f32_e32 v64, v64, v192
	v_mul_f32_e32 v64, v64, v193
	v_fma_f32 v64, v178, v64, v182
	v_sub_f32_e32 v65, v65, v192
	v_mul_f32_e32 v65, v65, v193
	v_fma_f32 v65, v179, v65, v183
	ds_read_b128 v[176:179], v136 offset:128
	ds_read_b128 v[180:183], v136 offset:4224
	s_waitcnt lgkmcnt(2)
	v_sub_f32_e32 v58, v58, v192
	v_mul_f32_e32 v58, v58, v193
	v_fma_f32 v58, v184, v58, v188
	v_sub_f32_e32 v59, v59, v192
	v_mul_f32_e32 v59, v59, v193
	v_fma_f32 v59, v185, v59, v189
	v_sub_f32_e32 v60, v60, v192
	v_mul_f32_e32 v60, v60, v193
	v_fma_f32 v60, v186, v60, v190
	v_sub_f32_e32 v61, v61, v192
	v_mul_f32_e32 v61, v61, v193
	v_fma_f32 v61, v187, v61, v191
	ds_read_b128 v[184:187], v136 offset:192
	ds_read_b128 v[188:191], v136 offset:4288
	s_waitcnt lgkmcnt(2)
	v_sub_f32_e32 v54, v54, v192
	v_mul_f32_e32 v54, v54, v193
	v_fma_f32 v54, v176, v54, v180
	v_sub_f32_e32 v55, v55, v192
	v_mul_f32_e32 v55, v55, v193
	v_fma_f32 v55, v177, v55, v181
	v_sub_f32_e32 v56, v56, v192
	v_mul_f32_e32 v56, v56, v193
	v_fma_f32 v56, v178, v56, v182
	v_sub_f32_e32 v57, v57, v192
	v_mul_f32_e32 v57, v57, v193
	v_fma_f32 v57, v179, v57, v183
	ds_read_b128 v[176:179], v136 offset:256
	ds_read_b128 v[180:183], v136 offset:4352
	s_waitcnt lgkmcnt(2)
	v_sub_f32_e32 v50, v50, v192
	v_mul_f32_e32 v50, v50, v193
	v_fma_f32 v50, v184, v50, v188
	v_sub_f32_e32 v51, v51, v192
	v_mul_f32_e32 v51, v51, v193
	v_fma_f32 v51, v185, v51, v189
	v_sub_f32_e32 v52, v52, v192
	v_mul_f32_e32 v52, v52, v193
	v_fma_f32 v52, v186, v52, v190
	v_sub_f32_e32 v53, v53, v192
	v_mul_f32_e32 v53, v53, v193
	v_fma_f32 v53, v187, v53, v191
	ds_read_b128 v[184:187], v136 offset:320
	ds_read_b128 v[188:191], v136 offset:4416
	s_waitcnt lgkmcnt(2)
	v_sub_f32_e32 v46, v46, v192
	v_mul_f32_e32 v46, v46, v193
	v_fma_f32 v46, v176, v46, v180
	v_sub_f32_e32 v47, v47, v192
	v_mul_f32_e32 v47, v47, v193
	v_fma_f32 v47, v177, v47, v181
	v_sub_f32_e32 v48, v48, v192
	v_mul_f32_e32 v48, v48, v193
	v_fma_f32 v48, v178, v48, v182
	v_sub_f32_e32 v49, v49, v192
	v_mul_f32_e32 v49, v49, v193
	v_fma_f32 v49, v179, v49, v183
	ds_read_b128 v[176:179], v136 offset:384
	ds_read_b128 v[180:183], v136 offset:4480
	s_waitcnt lgkmcnt(2)
	v_sub_f32_e32 v42, v42, v192
	v_mul_f32_e32 v42, v42, v193
	v_fma_f32 v42, v184, v42, v188
	v_sub_f32_e32 v43, v43, v192
	v_mul_f32_e32 v43, v43, v193
	v_fma_f32 v43, v185, v43, v189
	v_sub_f32_e32 v44, v44, v192
	v_mul_f32_e32 v44, v44, v193
	v_fma_f32 v44, v186, v44, v190
	v_sub_f32_e32 v45, v45, v192
	v_mul_f32_e32 v45, v45, v193
	v_fma_f32 v45, v187, v45, v191
	ds_read_b128 v[184:187], v136 offset:448
	ds_read_b128 v[188:191], v136 offset:4544
	s_waitcnt lgkmcnt(2)
	v_sub_f32_e32 v38, v38, v192
	v_mul_f32_e32 v38, v38, v193
	v_fma_f32 v38, v176, v38, v180
	v_sub_f32_e32 v39, v39, v192
	v_mul_f32_e32 v39, v39, v193
	v_fma_f32 v39, v177, v39, v181
	v_sub_f32_e32 v40, v40, v192
	v_mul_f32_e32 v40, v40, v193
	v_fma_f32 v40, v178, v40, v182
	v_sub_f32_e32 v41, v41, v192
	v_mul_f32_e32 v41, v41, v193
	v_fma_f32 v41, v179, v41, v183
	s_waitcnt lgkmcnt(0)
	v_sub_f32_e32 v2, v2, v192
	v_mul_f32_e32 v2, v2, v193
	v_fma_f32 v2, v184, v2, v188
	v_sub_f32_e32 v3, v3, v192
	v_mul_f32_e32 v3, v3, v193
	v_fma_f32 v3, v185, v3, v189
	v_sub_f32_e32 v4, v4, v192
	v_mul_f32_e32 v4, v4, v193
	v_fma_f32 v4, v186, v4, v190
	v_sub_f32_e32 v5, v5, v192
	v_mul_f32_e32 v5, v5, v193
	v_fma_f32 v5, v187, v5, v191
	s_add_u32 s94, s78, 0x0
	s_addc_u32 s95, s79, 0
	global_store_dwordx4 v137, v[98:101], s[94:95]
	global_store_dwordx4 v137, v[94:97], s[94:95] offset:64
	global_store_dwordx4 v137, v[90:93], s[94:95] offset:128
	global_store_dwordx4 v137, v[86:89], s[94:95] offset:192
	global_store_dwordx4 v137, v[82:85], s[94:95] offset:256
	global_store_dwordx4 v137, v[78:81], s[94:95] offset:320
	global_store_dwordx4 v137, v[74:77], s[94:95] offset:384
	global_store_dwordx4 v137, v[70:73], s[94:95] offset:448
	s_add_u32 s94, s78, 0x10000
	s_addc_u32 s95, s79, 0
	global_store_dwordx4 v137, v[126:129], s[94:95]
	global_store_dwordx4 v137, v[122:125], s[94:95] offset:64
	global_store_dwordx4 v137, v[118:121], s[94:95] offset:128
	global_store_dwordx4 v137, v[114:117], s[94:95] offset:192
	global_store_dwordx4 v137, v[110:113], s[94:95] offset:256
	global_store_dwordx4 v137, v[106:109], s[94:95] offset:320
	global_store_dwordx4 v137, v[102:105], s[94:95] offset:384
	global_store_dwordx4 v137, v[66:69], s[94:95] offset:448
	s_add_u32 s94, s78, 0x20000
	s_addc_u32 s95, s79, 0
	global_store_dwordx4 v137, v[34:37], s[94:95]
	global_store_dwordx4 v137, v[30:33], s[94:95] offset:64
	global_store_dwordx4 v137, v[26:29], s[94:95] offset:128
	global_store_dwordx4 v137, v[22:25], s[94:95] offset:192
	global_store_dwordx4 v137, v[18:21], s[94:95] offset:256
	global_store_dwordx4 v137, v[14:17], s[94:95] offset:320
	global_store_dwordx4 v137, v[10:13], s[94:95] offset:384
	global_store_dwordx4 v137, v[6:9], s[94:95] offset:448
	s_add_u32 s94, s78, 0x30000
	s_addc_u32 s95, s79, 0
	global_store_dwordx4 v137, v[62:65], s[94:95]
	global_store_dwordx4 v137, v[58:61], s[94:95] offset:64
	global_store_dwordx4 v137, v[54:57], s[94:95] offset:128
	global_store_dwordx4 v137, v[50:53], s[94:95] offset:192
	global_store_dwordx4 v137, v[46:49], s[94:95] offset:256
	global_store_dwordx4 v137, v[42:45], s[94:95] offset:320
	global_store_dwordx4 v137, v[38:41], s[94:95] offset:384
	global_store_dwordx4 v137, v[2:5], s[94:95] offset:448

;     ...
;     auto compute = [&](int cb, bool do_issue, int ikt, int ib) {
;         const char* base = lds + cb * BUF;
;         bf16x8 af[MT], bfr[NT];
; #pragma unroll
;         for (int nt = 0; nt < NT; ++nt) {
;             const int br = BM + (nt / NTS) * (BN / NSEG) + wc * (NTS * 16) + (nt % NTS) * 16;
;             bfr[nt] = *(const bf16x8*)(base + (br + l15) * 64 + rsw);
;         }
; #pragma unroll
;         for (int mt = 0; mt < MT; ++mt) af[mt] = *(const bf16x8*)(base + (wr * WM + mt * 16 + l15) * 64 + rsw);
;         constexpr int TOT = MT * NT, PER = (TOT + NIT - 1) / NIT;
; #pragma unroll
;         for (int part = 0; part < NIT; ++part) {
; #pragma unroll
;             for (int q = 0; q < PER; ++q) {
;                 const int idx = part * PER + q;
;                 if (idx < TOT) {
;                     const int mt = idx / NT, nt = idx % NT;
;                     acc[mt][nt] = SWAP ? mfma16(bfr[nt], af[mt], acc[mt][nt]) : mfma16(af[mt], bfr[nt], acc[mt][nt]);
;                 }
;             }
;             __builtin_amdgcn_sched_barrier(0);
;             if (do_issue) issue_one(ikt, ib, part);
;             __builtin_amdgcn_sched_barrier(0);
;         }
; DI void unit_O(const Params& p, char* lds, int l, int tile, int glu_tiles, int tile_b) {
;     ...
;     auto issue_x = [&](int half) {
;         if (l == 0) {
; #pragma unroll 1
;             for (int i = 0; i < 16; ++i) {
;                 const int pc = (wid * 16 + i + xrot) & 127, row = pc >> 2, phys = (pc & 3) * 64 + lane, logical = phys ^ (row & 15);
;                 __builtin_amdgcn_global_load_lds((const unsigned*)(xres + (r0 + half * 32 + row) * 1024 + logical * 4), (unsigned*)(XR + pc * 1024 + lane * 16), 16, 0, 0);
;             }
;         } else {
; #pragma unroll 1
;             for (int i = 0; i < 8; ++i) {
;                 const int pc = (wid * 8 + i + (xrot >> 1)) & 63, kt = pc >> 1, sub = pc & 1;
;                 __builtin_amdgcn_global_load_lds((const unsigned*)(xbres + ((size_t)kt * 128 + half * 32) * 32 + sub * 512 + lane * 8), (unsigned*)(XR + pc * 1024 + lane * 16), 16, 0, 0);
;             }
;         }
;     };
;     issue_x(0);
;     {
;         const float* gsrc = (tid < 256) ? (p.ln_g + l * 1024 + tid * 4) : (p.ln_b + l * 1024 + (tid - 256) * 4);
;         *(f32x4*)(GB + tid * 4) = *(const f32x4*)gsrc;
;     }
;     float* xo = (l == 0) ? WS_PTR(float, OFF_X1) : p.out;
.Lpo2_join:
.LBB0_382:
	s_waitcnt vmcnt(0)
	v_add_u32_e32 v0, 0x11000, v140
	s_barrier
	v_add_u32_e32 v134, v0, v141
	v_add_u32_e32 v0, v0, v139
	ds_read_b128 v[130:133], v134 offset:4096
	ds_read_b128 v[138:141], v0
	ds_read_b128 v[142:145], v134 offset:5120
	ds_read_b128 v[146:149], v0 offset:1024
	ds_read_b128 v[150:153], v134 offset:6144
	ds_read_b128 v[154:157], v134 offset:7168
	ds_read_b128 v[158:161], v134 offset:8192
	ds_read_b128 v[162:165], v134 offset:9216
	ds_read_b128 v[166:169], v134 offset:10240
	ds_read_b128 v[170:173], v134 offset:11264
	ds_read_b128 v[174:177], v0 offset:2048
	ds_read_b128 v[178:181], v0 offset:3072
	s_waitcnt lgkmcnt(0)
	v_mfma_f32_16x16x32_bf16 v[98:101], v[130:133], v[138:141], v[98:101]
	v_and_b32_e32 v197, 63, v136
	v_ashrrev_i32_e32 v236, 6, v136
	v_mfma_f32_16x16x32_bf16 v[94:97], v[142:145], v[138:141], v[94:97]
	v_mfma_f32_16x16x32_bf16 v[90:93], v[150:153], v[138:141], v[90:93]
	v_mfma_f32_16x16x32_bf16 v[86:89], v[154:157], v[138:141], v[86:89]
	v_mfma_f32_16x16x32_bf16 v[82:85], v[158:161], v[138:141], v[82:85]
	v_mfma_f32_16x16x32_bf16 v[78:81], v[162:165], v[138:141], v[78:81]
	v_mfma_f32_16x16x32_bf16 v[74:77], v[166:169], v[138:141], v[74:77]
	v_mfma_f32_16x16x32_bf16 v[70:73], v[170:173], v[138:141], v[70:73]
	v_mfma_f32_16x16x32_bf16 v[126:129], v[130:133], v[146:149], v[126:129]
	v_mfma_f32_16x16x32_bf16 v[122:125], v[142:145], v[146:149], v[122:125]
	v_mfma_f32_16x16x32_bf16 v[118:121], v[150:153], v[146:149], v[118:121]
	v_mfma_f32_16x16x32_bf16 v[114:117], v[154:157], v[146:149], v[114:117]
	v_mfma_f32_16x16x32_bf16 v[110:113], v[158:161], v[146:149], v[110:113]
	v_mfma_f32_16x16x32_bf16 v[106:109], v[162:165], v[146:149], v[106:109]
	v_mfma_f32_16x16x32_bf16 v[102:105], v[166:169], v[146:149], v[102:105]
	v_mfma_f32_16x16x32_bf16 v[66:69], v[170:173], v[146:149], v[66:69]
	v_mfma_f32_16x16x32_bf16 v[34:37], v[130:133], v[174:177], v[34:37]
	v_mfma_f32_16x16x32_bf16 v[30:33], v[142:145], v[174:177], v[30:33]
	v_mfma_f32_16x16x32_bf16 v[26:29], v[150:153], v[174:177], v[26:29]
	v_mfma_f32_16x16x32_bf16 v[22:25], v[154:157], v[174:177], v[22:25]
	v_mfma_f32_16x16x32_bf16 v[18:21], v[158:161], v[174:177], v[18:21]
	v_mfma_f32_16x16x32_bf16 v[14:17], v[162:165], v[174:177], v[14:17]
	v_mfma_f32_16x16x32_bf16 v[10:13], v[166:169], v[174:177], v[10:13]
	v_mfma_f32_16x16x32_bf16 v[6:9], v[170:173], v[174:177], v[6:9]
	v_mfma_f32_16x16x32_bf16 v[62:65], v[130:133], v[178:181], v[62:65]
	v_mfma_f32_16x16x32_bf16 v[58:61], v[142:145], v[178:181], v[58:61]
	v_mfma_f32_16x16x32_bf16 v[54:57], v[150:153], v[178:181], v[54:57]
	v_mfma_f32_16x16x32_bf16 v[50:53], v[154:157], v[178:181], v[50:53]
	v_mfma_f32_16x16x32_bf16 v[46:49], v[158:161], v[178:181], v[46:49]
	v_mfma_f32_16x16x32_bf16 v[42:45], v[162:165], v[178:181], v[42:45]
	v_mfma_f32_16x16x32_bf16 v[38:41], v[166:169], v[178:181], v[38:41]
	v_mfma_f32_16x16x32_bf16 v[2:5], v[170:173], v[178:181], v[2:5]
	s_barrier
	s_not_b64 s[6:7], s[10:11]
	v_and_b32_e32 v138, 15, v212
	v_bfe_u32 v139, v212, 4, 2
	v_lshrrev_b32_e32 v140, 6, v212
	v_and_b32_e32 v141, 63, v212
	v_readfirstlane_b32 s90, v140
	v_and_b32_e32 v142, 0xff, v212
	v_lshlrev_b32_e32 v142, 4, v142
	s_cmp_lt_u32 s90, 4
	s_cselect_b32 s92, s14, s12
	s_cselect_b32 s93, s15, s13
	s_nop 3
	global_load_dwordx4 v[176:179], v142, s[92:93]
	v_lshlrev_b32_e32 v143, 4, v212
	v_add_u32_e32 v143, 0x20000, v143
	v_lshlrev_b32_e32 v134, 6, v138
	v_add_u32_e32 v135, 0x22000, v134
	v_lshl_add_u32 v134, v140, 3, v135
	v_lshlrev_b32_e32 v136, 9, v140
	v_lshl_add_u32 v136, v139, 4, v136
	v_add_u32_e32 v136, 0x20000, v136
	s_cmp_lg_u64 s[10:11], 0
	s_cbranch_scc1 .Le2_l1
	s_lshl_b32 s40, s48, 18
	s_lshl_b32 s91, s90, 13
	s_add_u32 s96, s52, s40
	s_addc_u32 s97, s53, 0
	s_add_u32 s96, s96, s91
	s_addc_u32 s97, s97, 0
	s_lshl_b32 s40, s90, 1
	v_xor_b32_e32 v208, s40, v141
	v_lshlrev_b32_e32 v208, 4, v208
	s_add_u32 s40, s40, 1
	v_xor_b32_e32 v209, s40, v141
	v_lshlrev_b32_e32 v209, 4, v209
	v_lshlrev_b32_e32 v133, 12, v138
	v_lshl_add_u32 v133, v140, 9, v133
	v_add_u32_e32 v200, 0, v139
	v_xor_b32_e32 v200, v200, v138
	v_lshl_add_u32 v200, v200, 4, v133
	v_add_u32_e32 v204, 0x10000, v200
	v_add_u32_e32 v201, 4, v139
	v_xor_b32_e32 v201, v201, v138
	v_lshl_add_u32 v201, v201, 4, v133
	v_add_u32_e32 v205, 0x10000, v201
	v_add_u32_e32 v202, 8, v139
	v_xor_b32_e32 v202, v202, v138
	v_lshl_add_u32 v202, v202, 4, v133
	v_add_u32_e32 v206, 0x10000, v202
	v_add_u32_e32 v203, 12, v139
	v_xor_b32_e32 v203, v203, v138
	v_lshl_add_u32 v203, v203, 4, v133
	v_add_u32_e32 v207, 0x10000, v203
	v_and_b32_e32 v137, 1, v139
	v_lshlrev_b32_e32 v137, 5, v137
	v_lshrrev_b32_e32 v130, 1, v139
	v_lshl_or_b32 v137, v130, 4, v137
	v_lshl_or_b32 v137, v138, 6, v137
	v_lshl_or_b32 v137, v140, 15, v137
	s_lshr_b32 s40, s48, 1
	s_lshl_b32 s40, s40, 18
	s_and_b32 s46, s48, 1
	s_lshl_b32 s46, s46, 12
	s_add_u32 s40, s40, s46
	s_add_u32 s78, s56, s40
	s_addc_u32 s79, s57, 0
	s_add_u32 s92, s96, 0x0
	s_addc_u32 s93, s97, 0
	s_add_u32 s40, s91, 0x0
	s_mov_b32 m0, s40
	s_nop 0
	global_load_lds_dwordx4 v208, s[92:93]
	global_load_lds_dwordx4 v208, s[92:93] offset:1024
	global_load_lds_dwordx4 v208, s[92:93] offset:2048
	global_load_lds_dwordx4 v208, s[92:93] offset:3072
	s_add_u32 s92, s96, 0x1000
	s_addc_u32 s93, s97, 0
	s_add_u32 s40, s91, 0x1000
	s_mov_b32 m0, s40
	s_nop 0
	global_load_lds_dwordx4 v209, s[92:93]
	global_load_lds_dwordx4 v209, s[92:93] offset:1024
	global_load_lds_dwordx4 v209, s[92:93] offset:2048
	global_load_lds_dwordx4 v209, s[92:93] offset:3072
	s_add_u32 s92, s96, 0x10000
	s_addc_u32 s93, s97, 0
	s_add_u32 s40, s91, 0x10000
	s_mov_b32 m0, s40
	s_nop 0
	global_load_lds_dwordx4 v208, s[92:93]
	global_load_lds_dwordx4 v208, s[92:93] offset:1024
	global_load_lds_dwordx4 v208, s[92:93] offset:2048
	global_load_lds_dwordx4 v208, s[92:93] offset:3072
	s_add_u32 s92, s96, 0x11000
	s_addc_u32 s93, s97, 0
	s_add_u32 s40, s91, 0x11000
	s_mov_b32 m0, s40
	s_nop 0
	global_load_lds_dwordx4 v209, s[92:93]
	global_load_lds_dwordx4 v209, s[92:93] offset:1024
	global_load_lds_dwordx4 v209, s[92:93] offset:2048
	global_load_lds_dwordx4 v209, s[92:93] offset:3072
	s_waitcnt vmcnt(16)
	ds_write_b128 v143, v[176:179]
	s_waitcnt vmcnt(8) lgkmcnt(0)
	s_barrier
; DI void unit_O(const Params& p, char* lds, int l, int tile, int glu_tiles, int tile_b) {
;     ...
;         float s2[2], ss2[2];
; #pragma unroll
;         for (int mh = 0; mh < 2; ++mh) {
;             const int mt = half * 2 + mh, rl = mh * 16 + l15;
;             float s = 0.f, ss = 0.f;
; #pragma unroll
;             for (int nt = 0; nt < 8; ++nt) {
;                 f32x4 xr;
;                 if (l == 0) {
;                     const int chunk = wid * 32 + nt * 4 + quad;
;                     xr = *(const f32x4*)(XR + rl * 4096 + ((chunk ^ l15) << 4));
;                 } else {
;                     const u32x2 hb = *(const u32x2*)(XR + ((wid * 4 + (nt >> 1)) * 32 + rl) * 64 + (nt & 1) * 32 + quad * 8);
;                     xr = (f32x4){bf2f(hb[0] & 0xffffu), bf2f(hb[0] >> 16), bf2f(hb[1] & 0xffffu), bf2f(hb[1] >> 16)};
;                 }
; #pragma unroll
;                 for (int i = 0; i < 4; ++i) { const float v = acc[mt][nt][i] + DN_ALPHA * xr[i]; acc[mt][nt][i] = v; s += v; ss += v * v; }
;             }
;             s2[mh] = s; ss2[mh] = ss;
;         }
; #pragma unroll
;         for (int mh = 0; mh < 2; ++mh) { s2[mh] += __shfl_xor(s2[mh], 16); ss2[mh] += __shfl_xor(ss2[mh], 16); }
; #pragma unroll
;         for (int mh = 0; mh < 2; ++mh) { s2[mh] += __shfl_xor(s2[mh], 32); ss2[mh] += __shfl_xor(ss2[mh], 32); }
;         if (quad == 0) {
; #pragma unroll
;             for (int mh = 0; mh < 2; ++mh) *(f32x2*)&red[((mh * 16 + l15) * 8 + wid) * 2] = (f32x2){s2[mh], ss2[mh]};
;         }
;         __syncthreads();
;         if (half == 0) issue_x(1);
; #pragma unroll
;         for (int mh = 0; mh < 2; ++mh) {
;             const int mt = half * 2 + mh, rl = mh * 16 + l15, row = mt * 16 + l15;
;             float s = 0.f, ss = 0.f;
; #pragma unroll
;             for (int w = 0; w < 4; ++w) { const f32x4 v = *(const f32x4*)&red[rl * 16 + 4 * w]; s += v[0] + v[2]; ss += v[1] + v[3]; }
;             const float mu = s * (1.f / 1024.f);
;             const float var = ss * (1.f / 1024.f) - mu * mu;
;             const float rs = rsqrtf(var + LN_EPS);
;             float* orow = xo + (r0 + row) * 1024 + wid * 128 + quad * 4;
;             bf16_t* brow = xbo + xb_off((int)r0 + row, wid * 128) + quad * 4;
;             const float* gp = GB + wid * 128 + quad * 4;
; #pragma unroll
;             for (int nt = 0; nt < 8; ++nt) {
	ds_read_b128 v[144:147], v200
	ds_read_b128 v[148:151], v201
	ds_read_b128 v[152:155], v202
	ds_read_b128 v[156:159], v203
	ds_read_b128 v[160:163], v200 offset:256
	ds_read_b128 v[164:167], v201 offset:256
	ds_read_b128 v[168:171], v202 offset:256
	ds_read_b128 v[172:175], v203 offset:256
	s_waitcnt lgkmcnt(7)
	v_fmac_f32_e32 v98, s58, v144
	v_fmac_f32_e32 v99, s58, v145
	v_fmac_f32_e32 v100, s58, v146
	v_fmac_f32_e32 v101, s58, v147
	v_mov_b32_e32 v196, v98
	v_mul_f32_e32 v197, v98, v98
	v_mov_b32_e32 v130, v99
	v_mul_f32_e32 v142, v99, v99
	v_add_f32_e32 v196, v196, v100
	v_fmac_f32_e32 v197, v100, v100
	v_add_f32_e32 v130, v130, v101
	v_fmac_f32_e32 v142, v101, v101
	s_waitcnt lgkmcnt(6)
	v_fmac_f32_e32 v94, s58, v148
	v_fmac_f32_e32 v95, s58, v149
	v_fmac_f32_e32 v96, s58, v150
	v_fmac_f32_e32 v97, s58, v151
	v_add_f32_e32 v196, v196, v94
	v_fmac_f32_e32 v197, v94, v94
	v_add_f32_e32 v130, v130, v95
	v_fmac_f32_e32 v142, v95, v95
	v_add_f32_e32 v196, v196, v96
	v_fmac_f32_e32 v197, v96, v96
	v_add_f32_e32 v130, v130, v97
	v_fmac_f32_e32 v142, v97, v97
	s_waitcnt lgkmcnt(5)
	v_fmac_f32_e32 v90, s58, v152
	v_fmac_f32_e32 v91, s58, v153
	v_fmac_f32_e32 v92, s58, v154
	v_fmac_f32_e32 v93, s58, v155
	v_add_f32_e32 v196, v196, v90
	v_fmac_f32_e32 v197, v90, v90
	v_add_f32_e32 v130, v130, v91
	v_fmac_f32_e32 v142, v91, v91
	v_add_f32_e32 v196, v196, v92
	v_fmac_f32_e32 v197, v92, v92
	v_add_f32_e32 v130, v130, v93
	v_fmac_f32_e32 v142, v93, v93
	s_waitcnt lgkmcnt(4)
	v_fmac_f32_e32 v86, s58, v156
	v_fmac_f32_e32 v87, s58, v157
	v_fmac_f32_e32 v88, s58, v158
	v_fmac_f32_e32 v89, s58, v159
	v_add_f32_e32 v196, v196, v86
	v_fmac_f32_e32 v197, v86, v86
	v_add_f32_e32 v130, v130, v87
	v_fmac_f32_e32 v142, v87, v87
	v_add_f32_e32 v196, v196, v88
	v_fmac_f32_e32 v197, v88, v88
	v_add_f32_e32 v130, v130, v89
	v_fmac_f32_e32 v142, v89, v89
	s_waitcnt lgkmcnt(3)
	v_fmac_f32_e32 v82, s58, v160
	v_fmac_f32_e32 v83, s58, v161
	v_fmac_f32_e32 v84, s58, v162
	v_fmac_f32_e32 v85, s58, v163
	v_add_f32_e32 v196, v196, v82
	v_fmac_f32_e32 v197, v82, v82
	v_add_f32_e32 v130, v130, v83
	v_fmac_f32_e32 v142, v83, v83
	v_add_f32_e32 v196, v196, v84
	v_fmac_f32_e32 v197, v84, v84
	v_add_f32_e32 v130, v130, v85
	v_fmac_f32_e32 v142, v85, v85
	s_waitcnt lgkmcnt(2)
	v_fmac_f32_e32 v78, s58, v164
	v_fmac_f32_e32 v79, s58, v165
	v_fmac_f32_e32 v80, s58, v166
	v_fmac_f32_e32 v81, s58, v167
	v_add_f32_e32 v196, v196, v78
	v_fmac_f32_e32 v197, v78, v78
	v_add_f32_e32 v130, v130, v79
	v_fmac_f32_e32 v142, v79, v79
	v_add_f32_e32 v196, v196, v80
	v_fmac_f32_e32 v197, v80, v80
	v_add_f32_e32 v130, v130, v81
	v_fmac_f32_e32 v142, v81, v81
	s_waitcnt lgkmcnt(1)
	v_fmac_f32_e32 v74, s58, v168
	v_fmac_f32_e32 v75, s58, v169
	v_fmac_f32_e32 v76, s58, v170
	v_fmac_f32_e32 v77, s58, v171
	v_add_f32_e32 v196, v196, v74
	v_fmac_f32_e32 v197, v74, v74
	v_add_f32_e32 v130, v130, v75
	v_fmac_f32_e32 v142, v75, v75
	v_add_f32_e32 v196, v196, v76
	v_fmac_f32_e32 v197, v76, v76
	v_add_f32_e32 v130, v130, v77
	v_fmac_f32_e32 v142, v77, v77
	s_waitcnt lgkmcnt(0)
	v_fmac_f32_e32 v70, s58, v172
	v_fmac_f32_e32 v71, s58, v173
	v_fmac_f32_e32 v72, s58, v174
	v_fmac_f32_e32 v73, s58, v175
	v_add_f32_e32 v196, v196, v70
	v_fmac_f32_e32 v197, v70, v70
	v_add_f32_e32 v130, v130, v71
	v_fmac_f32_e32 v142, v71, v71
	v_add_f32_e32 v196, v196, v72
	v_fmac_f32_e32 v197, v72, v72
	v_add_f32_e32 v130, v130, v73
	v_fmac_f32_e32 v142, v73, v73
	v_add_f32_e32 v196, v196, v130
	v_add_f32_e32 v197, v197, v142
	v_mov_b32_e32 v198, v196
	v_mov_b32_e32 v199, v197
	s_nop 1
	v_permlane16_swap_b32 v198, v196
	v_permlane16_swap_b32 v199, v197
	v_add_f32_e32 v196, v196, v198
	v_add_f32_e32 v197, v197, v199
	v_mov_b32_e32 v198, v196
	v_mov_b32_e32 v199, v197
	s_nop 1
	v_permlane32_swap_b32 v198, v196
	v_permlane32_swap_b32 v199, v197
	v_add_f32_e32 v196, v196, v198
	v_add_f32_e32 v197, v197, v199
	s_mov_b64 exec, 0xffff
	ds_write_b64 v134, v[196:197]
	s_mov_b64 exec, -1
	s_waitcnt lgkmcnt(0)
	s_barrier
	s_add_u32 s92, s96, 0x20000
	s_addc_u32 s93, s97, 0
	s_add_u32 s40, s91, 0x0
	s_mov_b32 m0, s40
	s_nop 0
	global_load_lds_dwordx4 v208, s[92:93]
	global_load_lds_dwordx4 v208, s[92:93] offset:1024
	global_load_lds_dwordx4 v208, s[92:93] offset:2048
	global_load_lds_dwordx4 v208, s[92:93] offset:3072
	s_add_u32 s92, s96, 0x21000
	s_addc_u32 s93, s97, 0
	s_add_u32 s40, s91, 0x1000
	s_mov_b32 m0, s40
	s_nop 0
	global_load_lds_dwordx4 v209, s[92:93]
	global_load_lds_dwordx4 v209, s[92:93] offset:1024
	global_load_lds_dwordx4 v209, s[92:93] offset:2048
	global_load_lds_dwordx4 v209, s[92:93] offset:3072
	ds_read_b128 v[160:163], v135 offset:0
	ds_read_b128 v[164:167], v135 offset:16
	ds_read_b128 v[168:171], v135 offset:32
	ds_read_b128 v[172:175], v135 offset:48
	s_waitcnt lgkmcnt(0)
	v_add_f32_e32 v160, v160, v162
	v_add_f32_e32 v161, v161, v163
	v_add_f32_e32 v164, v164, v166
	v_add_f32_e32 v165, v165, v167
	v_add_f32_e32 v168, v168, v170
	v_add_f32_e32 v169, v169, v171
	v_add_f32_e32 v172, v172, v174
	v_add_f32_e32 v173, v173, v175
	v_add_f32_e32 v160, v160, v164
	v_add_f32_e32 v161, v161, v165
	v_add_f32_e32 v168, v168, v172
	v_add_f32_e32 v169, v169, v173
	v_add_f32_e32 v160, v160, v168
	v_add_f32_e32 v161, v161, v169
	v_mul_f32_e32 v192, 0x3a800000, v160
	v_mul_f32_e32 v193, 0x3a800000, v161
	v_fma_f32 v193, -v192, v192, v193
	v_add_f32_e32 v193, 0x3727c5ac, v193
	v_rsq_f32_e32 v193, v193
	s_nop 0
	ds_read_b128 v[176:179], v136
	ds_read_b128 v[180:183], v136 offset:4096
	ds_read_b128 v[184:187], v136 offset:64
	ds_read_b128 v[188:191], v136 offset:4160
	s_waitcnt lgkmcnt(2)
; DI unsigned pk2(float lo, float hi) { const f32x2 v = {lo, hi}; const bf16x2_t b = __builtin_convertvector(v, bf16x2_t); return __builtin_bit_cast(unsigned, b); }
; DI void unit_O(const Params& p, char* lds, int l, int tile, int glu_tiles, int tile_b) {
;     ...
; #pragma unroll
;             for (int nt = 0; nt < 8; ++nt) {
;                 const f32x4 g = *(const f32x4*)(gp + nt * 16), bb = *(const f32x4*)(gp + 1024 + nt * 16);
;                 f32x4 o;
; #pragma unroll
;                 for (int i = 0; i < 4; ++i) o[i] = (acc[mt][nt][i] - mu) * rs * g[i] + bb[i];
;                 if (l == 0) *(u32x2*)(brow + (nt >> 1) * 4096 + (nt & 1) * 16) = (u32x2){pk2(o[0], o[1]), pk2(o[2], o[3])};
;                 else *(f32x4*)(orow + nt * 16) = o;
;             }
	v_sub_f32_e32 v98, v98, v192
	v_mul_f32_e32 v98, v98, v193
	v_fma_f32 v98, v176, v98, v180
	v_sub_f32_e32 v99, v99, v192
	v_mul_f32_e32 v99, v99, v193
	v_fma_f32 v99, v177, v99, v181
	v_sub_f32_e32 v100, v100, v192
	v_mul_f32_e32 v100, v100, v193
	v_fma_f32 v100, v178, v100, v182
	v_sub_f32_e32 v101, v101, v192
	v_mul_f32_e32 v101, v101, v193
	v_fma_f32 v101, v179, v101, v183
	v_cvt_pk_bf16_f32 v98, v98, v99
	v_cvt_pk_bf16_f32 v99, v100, v101
	ds_read_b128 v[176:179], v136 offset:128
	ds_read_b128 v[180:183], v136 offset:4224
	s_waitcnt lgkmcnt(2)
	v_sub_f32_e32 v94, v94, v192
	v_mul_f32_e32 v94, v94, v193
	v_fma_f32 v94, v184, v94, v188
	v_sub_f32_e32 v95, v95, v192
	v_mul_f32_e32 v95, v95, v193
	v_fma_f32 v95, v185, v95, v189
	v_sub_f32_e32 v96, v96, v192
	v_mul_f32_e32 v96, v96, v193
	v_fma_f32 v96, v186, v96, v190
	v_sub_f32_e32 v97, v97, v192
	v_mul_f32_e32 v97, v97, v193
	v_fma_f32 v97, v187, v97, v191
	v_cvt_pk_bf16_f32 v100, v94, v95
	v_cvt_pk_bf16_f32 v101, v96, v97
	s_nop 1
	v_permlane16_swap_b32 v98, v100
	v_permlane16_swap_b32 v99, v101
	ds_read_b128 v[184:187], v136 offset:192
	ds_read_b128 v[188:191], v136 offset:4288
	s_waitcnt lgkmcnt(2)
	v_sub_f32_e32 v90, v90, v192
	v_mul_f32_e32 v90, v90, v193
	v_fma_f32 v90, v176, v90, v180
	v_sub_f32_e32 v91, v91, v192
	v_mul_f32_e32 v91, v91, v193
	v_fma_f32 v91, v177, v91, v181
	v_sub_f32_e32 v92, v92, v192
	v_mul_f32_e32 v92, v92, v193
	v_fma_f32 v92, v178, v92, v182
	v_sub_f32_e32 v93, v93, v192
	v_mul_f32_e32 v93, v93, v193
	v_fma_f32 v93, v179, v93, v183
	v_cvt_pk_bf16_f32 v90, v90, v91
	v_cvt_pk_bf16_f32 v91, v92, v93
	ds_read_b128 v[176:179], v136 offset:256
	ds_read_b128 v[180:183], v136 offset:4352
	s_waitcnt lgkmcnt(2)
	v_sub_f32_e32 v86, v86, v192
	v_mul_f32_e32 v86, v86, v193
	v_fma_f32 v86, v184, v86, v188
	v_sub_f32_e32 v87, v87, v192
	v_mul_f32_e32 v87, v87, v193
	v_fma_f32 v87, v185, v87, v189
	v_sub_f32_e32 v88, v88, v192
	v_mul_f32_e32 v88, v88, v193
	v_fma_f32 v88, v186, v88, v190
	v_sub_f32_e32 v89, v89, v192
	v_mul_f32_e32 v89, v89, v193
	v_fma_f32 v89, v187, v89, v191
	v_cvt_pk_bf16_f32 v92, v86, v87
	v_cvt_pk_bf16_f32 v93, v88, v89
	s_nop 1
	v_permlane16_swap_b32 v90, v92
	v_permlane16_swap_b32 v91, v93
	ds_read_b128 v[184:187], v136 offset:320
	ds_read_b128 v[188:191], v136 offset:4416
	s_waitcnt lgkmcnt(2)
	v_sub_f32_e32 v82, v82, v192
	v_mul_f32_e32 v82, v82, v193
	v_fma_f32 v82, v176, v82, v180
	v_sub_f32_e32 v83, v83, v192
	v_mul_f32_e32 v83, v83, v193
	v_fma_f32 v83, v177, v83, v181
	v_sub_f32_e32 v84, v84, v192
	v_mul_f32_e32 v84, v84, v193
	v_fma_f32 v84, v178, v84, v182
	v_sub_f32_e32 v85, v85, v192
	v_mul_f32_e32 v85, v85, v193
	v_fma_f32 v85, v179, v85, v183
	v_cvt_pk_bf16_f32 v82, v82, v83
	v_cvt_pk_bf16_f32 v83, v84, v85
	ds_read_b128 v[176:179], v136 offset:384
	ds_read_b128 v[180:183], v136 offset:4480
	s_waitcnt lgkmcnt(2)
	v_sub_f32_e32 v78, v78, v192
	v_mul_f32_e32 v78, v78, v193
	v_fma_f32 v78, v184, v78, v188
	v_sub_f32_e32 v79, v79, v192
	v_mul_f32_e32 v79, v79, v193
	v_fma_f32 v79, v185, v79, v189
	v_sub_f32_e32 v80, v80, v192
	v_mul_f32_e32 v80, v80, v193
	v_fma_f32 v80, v186, v80, v190
	v_sub_f32_e32 v81, v81, v192
	v_mul_f32_e32 v81, v81, v193
	v_fma_f32 v81, v187, v81, v191
	v_cvt_pk_bf16_f32 v84, v78, v79
	v_cvt_pk_bf16_f32 v85, v80, v81
	s_nop 1
	v_permlane16_swap_b32 v82, v84
	v_permlane16_swap_b32 v83, v85
	ds_read_b128 v[184:187], v136 offset:448
	ds_read_b128 v[188:191], v136 offset:4544
	s_waitcnt lgkmcnt(2)
	v_sub_f32_e32 v74, v74, v192
	v_mul_f32_e32 v74, v74, v193
	v_fma_f32 v74, v176, v74, v180
	v_sub_f32_e32 v75, v75, v192
	v_mul_f32_e32 v75, v75, v193
	v_fma_f32 v75, v177, v75, v181
	v_sub_f32_e32 v76, v76, v192
	v_mul_f32_e32 v76, v76, v193
	v_fma_f32 v76, v178, v76, v182
	v_sub_f32_e32 v77, v77, v192
	v_mul_f32_e32 v77, v77, v193
	v_fma_f32 v77, v179, v77, v183
	v_cvt_pk_bf16_f32 v74, v74, v75
	v_cvt_pk_bf16_f32 v75, v76, v77
	s_waitcnt lgkmcnt(0)
	v_sub_f32_e32 v70, v70, v192
	v_mul_f32_e32 v70, v70, v193
	v_fma_f32 v70, v184, v70, v188
	v_sub_f32_e32 v71, v71, v192
	v_mul_f32_e32 v71, v71, v193
	v_fma_f32 v71, v185, v71, v189
	v_sub_f32_e32 v72, v72, v192
	v_mul_f32_e32 v72, v72, v193
	v_fma_f32 v72, v186, v72, v190
	v_sub_f32_e32 v73, v73, v192
	v_mul_f32_e32 v73, v73, v193
	v_fma_f32 v73, v187, v73, v191
	v_cvt_pk_bf16_f32 v76, v70, v71
	v_cvt_pk_bf16_f32 v77, v72, v73
	s_nop 1
	v_permlane16_swap_b32 v74, v76
	v_permlane16_swap_b32 v75, v77
	s_waitcnt vmcnt(8) lgkmcnt(0)
	s_barrier
; DI void unit_O(const Params& p, char* lds, int l, int tile, int glu_tiles, int tile_b) {
;     ...
;         float s2[2], ss2[2];
; #pragma unroll
;         for (int mh = 0; mh < 2; ++mh) {
;             const int mt = half * 2 + mh, rl = mh * 16 + l15;
;             float s = 0.f, ss = 0.f;
; #pragma unroll
;             for (int nt = 0; nt < 8; ++nt) {
;                 f32x4 xr;
;                 if (l == 0) {
;                     const int chunk = wid * 32 + nt * 4 + quad;
;                     xr = *(const f32x4*)(XR + rl * 4096 + ((chunk ^ l15) << 4));
;                 } else {
;                     const u32x2 hb = *(const u32x2*)(XR + ((wid * 4 + (nt >> 1)) * 32 + rl) * 64 + (nt & 1) * 32 + quad * 8);
;                     xr = (f32x4){bf2f(hb[0] & 0xffffu), bf2f(hb[0] >> 16), bf2f(hb[1] & 0xffffu), bf2f(hb[1] >> 16)};
;                 }
; #pragma unroll
;                 for (int i = 0; i < 4; ++i) { const float v = acc[mt][nt][i] + DN_ALPHA * xr[i]; acc[mt][nt][i] = v; s += v; ss += v * v; }
;             }
;             s2[mh] = s; ss2[mh] = ss;
;         }
; #pragma unroll
;         for (int mh = 0; mh < 2; ++mh) { s2[mh] += __shfl_xor(s2[mh], 16); ss2[mh] += __shfl_xor(ss2[mh], 16); }
; #pragma unroll
;         for (int mh = 0; mh < 2; ++mh) { s2[mh] += __shfl_xor(s2[mh], 32); ss2[mh] += __shfl_xor(ss2[mh], 32); }
;         if (quad == 0) {
; #pragma unroll
;             for (int mh = 0; mh < 2; ++mh) *(f32x2*)&red[((mh * 16 + l15) * 8 + wid) * 2] = (f32x2){s2[mh], ss2[mh]};
;         }
;         __syncthreads();
;         if (half == 0) issue_x(1);
; #pragma unroll
;         for (int mh = 0; mh < 2; ++mh) {
;             const int mt = half * 2 + mh, rl = mh * 16 + l15, row = mt * 16 + l15;
;             float s = 0.f, ss = 0.f;
; #pragma unroll
;             for (int w = 0; w < 4; ++w) { const f32x4 v = *(const f32x4*)&red[rl * 16 + 4 * w]; s += v[0] + v[2]; ss += v[1] + v[3]; }
;             const float mu = s * (1.f / 1024.f);
;             const float var = ss * (1.f / 1024.f) - mu * mu;
;             const float rs = rsqrtf(var + LN_EPS);
;             float* orow = xo + (r0 + row) * 1024 + wid * 128 + quad * 4;
;             bf16_t* brow = xbo + xb_off((int)r0 + row, wid * 128) + quad * 4;
;             const float* gp = GB + wid * 128 + quad * 4;
; #pragma unroll
;             for (int nt = 0; nt < 8; ++nt) {
	ds_read_b128 v[144:147], v204
	ds_read_b128 v[148:151], v205
	ds_read_b128 v[152:155], v206
	ds_read_b128 v[156:159], v207
	ds_read_b128 v[160:163], v204 offset:256
	ds_read_b128 v[164:167], v205 offset:256
	ds_read_b128 v[168:171], v206 offset:256
	ds_read_b128 v[172:175], v207 offset:256
	s_waitcnt lgkmcnt(7)
	v_fmac_f32_e32 v126, s58, v144
	v_fmac_f32_e32 v127, s58, v145
	v_fmac_f32_e32 v128, s58, v146
	v_fmac_f32_e32 v129, s58, v147
	v_mov_b32_e32 v196, v126
	v_mul_f32_e32 v197, v126, v126
	v_mov_b32_e32 v130, v127
	v_mul_f32_e32 v142, v127, v127
	v_add_f32_e32 v196, v196, v128
	v_fmac_f32_e32 v197, v128, v128
	v_add_f32_e32 v130, v130, v129
	v_fmac_f32_e32 v142, v129, v129
	s_waitcnt lgkmcnt(6)
	v_fmac_f32_e32 v122, s58, v148
	v_fmac_f32_e32 v123, s58, v149
	v_fmac_f32_e32 v124, s58, v150
	v_fmac_f32_e32 v125, s58, v151
	v_add_f32_e32 v196, v196, v122
	v_fmac_f32_e32 v197, v122, v122
	v_add_f32_e32 v130, v130, v123
	v_fmac_f32_e32 v142, v123, v123
	v_add_f32_e32 v196, v196, v124
	v_fmac_f32_e32 v197, v124, v124
	v_add_f32_e32 v130, v130, v125
	v_fmac_f32_e32 v142, v125, v125
	s_waitcnt lgkmcnt(5)
	v_fmac_f32_e32 v118, s58, v152
	v_fmac_f32_e32 v119, s58, v153
	v_fmac_f32_e32 v120, s58, v154
	v_fmac_f32_e32 v121, s58, v155
	v_add_f32_e32 v196, v196, v118
	v_fmac_f32_e32 v197, v118, v118
	v_add_f32_e32 v130, v130, v119
	v_fmac_f32_e32 v142, v119, v119
	v_add_f32_e32 v196, v196, v120
	v_fmac_f32_e32 v197, v120, v120
	v_add_f32_e32 v130, v130, v121
	v_fmac_f32_e32 v142, v121, v121
	s_waitcnt lgkmcnt(4)
	v_fmac_f32_e32 v114, s58, v156
	v_fmac_f32_e32 v115, s58, v157
	v_fmac_f32_e32 v116, s58, v158
	v_fmac_f32_e32 v117, s58, v159
	v_add_f32_e32 v196, v196, v114
	v_fmac_f32_e32 v197, v114, v114
	v_add_f32_e32 v130, v130, v115
	v_fmac_f32_e32 v142, v115, v115
	v_add_f32_e32 v196, v196, v116
	v_fmac_f32_e32 v197, v116, v116
	v_add_f32_e32 v130, v130, v117
	v_fmac_f32_e32 v142, v117, v117
	s_waitcnt lgkmcnt(3)
	v_fmac_f32_e32 v110, s58, v160
	v_fmac_f32_e32 v111, s58, v161
	v_fmac_f32_e32 v112, s58, v162
	v_fmac_f32_e32 v113, s58, v163
	v_add_f32_e32 v196, v196, v110
	v_fmac_f32_e32 v197, v110, v110
	v_add_f32_e32 v130, v130, v111
	v_fmac_f32_e32 v142, v111, v111
	v_add_f32_e32 v196, v196, v112
	v_fmac_f32_e32 v197, v112, v112
	v_add_f32_e32 v130, v130, v113
	v_fmac_f32_e32 v142, v113, v113
	s_waitcnt lgkmcnt(2)
	v_fmac_f32_e32 v106, s58, v164
	v_fmac_f32_e32 v107, s58, v165
	v_fmac_f32_e32 v108, s58, v166
	v_fmac_f32_e32 v109, s58, v167
	v_add_f32_e32 v196, v196, v106
	v_fmac_f32_e32 v197, v106, v106
	v_add_f32_e32 v130, v130, v107
	v_fmac_f32_e32 v142, v107, v107
	v_add_f32_e32 v196, v196, v108
	v_fmac_f32_e32 v197, v108, v108
	v_add_f32_e32 v130, v130, v109
	v_fmac_f32_e32 v142, v109, v109
	s_waitcnt lgkmcnt(1)
	v_fmac_f32_e32 v102, s58, v168
	v_fmac_f32_e32 v103, s58, v169
	v_fmac_f32_e32 v104, s58, v170
	v_fmac_f32_e32 v105, s58, v171
	v_add_f32_e32 v196, v196, v102
	v_fmac_f32_e32 v197, v102, v102
	v_add_f32_e32 v130, v130, v103
	v_fmac_f32_e32 v142, v103, v103
	v_add_f32_e32 v196, v196, v104
	v_fmac_f32_e32 v197, v104, v104
	v_add_f32_e32 v130, v130, v105
	v_fmac_f32_e32 v142, v105, v105
	s_waitcnt lgkmcnt(0)
	v_fmac_f32_e32 v66, s58, v172
	v_fmac_f32_e32 v67, s58, v173
	v_fmac_f32_e32 v68, s58, v174
	v_fmac_f32_e32 v69, s58, v175
	v_add_f32_e32 v196, v196, v66
	v_fmac_f32_e32 v197, v66, v66
	v_add_f32_e32 v130, v130, v67
	v_fmac_f32_e32 v142, v67, v67
	v_add_f32_e32 v196, v196, v68
	v_fmac_f32_e32 v197, v68, v68
	v_add_f32_e32 v130, v130, v69
	v_fmac_f32_e32 v142, v69, v69
	v_add_f32_e32 v196, v196, v130
	v_add_f32_e32 v197, v197, v142
	v_mov_b32_e32 v198, v196
	v_mov_b32_e32 v199, v197
	s_nop 1
	v_permlane16_swap_b32 v198, v196
	v_permlane16_swap_b32 v199, v197
	v_add_f32_e32 v196, v196, v198
	v_add_f32_e32 v197, v197, v199
	v_mov_b32_e32 v198, v196
	v_mov_b32_e32 v199, v197
	s_nop 1
	v_permlane32_swap_b32 v198, v196
	v_permlane32_swap_b32 v199, v197
	v_add_f32_e32 v196, v196, v198
	v_add_f32_e32 v197, v197, v199
	s_mov_b64 exec, 0xffff
	ds_write_b64 v134, v[196:197]
	s_mov_b64 exec, -1
	s_waitcnt lgkmcnt(0)
	s_barrier
	s_add_u32 s92, s96, 0x30000
	s_addc_u32 s93, s97, 0
	s_add_u32 s40, s91, 0x10000
	s_mov_b32 m0, s40
	s_nop 0
	global_load_lds_dwordx4 v208, s[92:93]
	global_load_lds_dwordx4 v208, s[92:93] offset:1024
	global_load_lds_dwordx4 v208, s[92:93] offset:2048
	global_load_lds_dwordx4 v208, s[92:93] offset:3072
	s_add_u32 s92, s96, 0x31000
	s_addc_u32 s93, s97, 0
	s_add_u32 s40, s91, 0x11000
	s_mov_b32 m0, s40
	s_nop 0
	global_load_lds_dwordx4 v209, s[92:93]
	global_load_lds_dwordx4 v209, s[92:93] offset:1024
	global_load_lds_dwordx4 v209, s[92:93] offset:2048
	global_load_lds_dwordx4 v209, s[92:93] offset:3072
	ds_read_b128 v[160:163], v135 offset:0
	ds_read_b128 v[164:167], v135 offset:16
	ds_read_b128 v[168:171], v135 offset:32
	ds_read_b128 v[172:175], v135 offset:48
	s_waitcnt lgkmcnt(0)
	v_add_f32_e32 v160, v160, v162
	v_add_f32_e32 v161, v161, v163
	v_add_f32_e32 v164, v164, v166
	v_add_f32_e32 v165, v165, v167
	v_add_f32_e32 v168, v168, v170
	v_add_f32_e32 v169, v169, v171
	v_add_f32_e32 v172, v172, v174
	v_add_f32_e32 v173, v173, v175
	v_add_f32_e32 v160, v160, v164
	v_add_f32_e32 v161, v161, v165
	v_add_f32_e32 v168, v168, v172
	v_add_f32_e32 v169, v169, v173
	v_add_f32_e32 v160, v160, v168
	v_add_f32_e32 v161, v161, v169
	v_mul_f32_e32 v192, 0x3a800000, v160
	v_mul_f32_e32 v193, 0x3a800000, v161
	v_fma_f32 v193, -v192, v192, v193
	v_add_f32_e32 v193, 0x3727c5ac, v193
	v_rsq_f32_e32 v193, v193
	s_nop 0
	ds_read_b128 v[176:179], v136
	ds_read_b128 v[180:183], v136 offset:4096
	ds_read_b128 v[184:187], v136 offset:64
	ds_read_b128 v[188:191], v136 offset:4160
	s_waitcnt lgkmcnt(2)
; DI unsigned pk2(float lo, float hi) { const f32x2 v = {lo, hi}; const bf16x2_t b = __builtin_convertvector(v, bf16x2_t); return __builtin_bit_cast(unsigned, b); }
; DI void unit_O(const Params& p, char* lds, int l, int tile, int glu_tiles, int tile_b) {
;     ...
; #pragma unroll
;             for (int nt = 0; nt < 8; ++nt) {
;                 const f32x4 g = *(const f32x4*)(gp + nt * 16), bb = *(const f32x4*)(gp + 1024 + nt * 16);
;                 f32x4 o;
; #pragma unroll
;                 for (int i = 0; i < 4; ++i) o[i] = (acc[mt][nt][i] - mu) * rs * g[i] + bb[i];
;                 if (l == 0) *(u32x2*)(brow + (nt >> 1) * 4096 + (nt & 1) * 16) = (u32x2){pk2(o[0], o[1]), pk2(o[2], o[3])};
;                 else *(f32x4*)(orow + nt * 16) = o;
;             }
	v_sub_f32_e32 v126, v126, v192
	v_mul_f32_e32 v126, v126, v193
	v_fma_f32 v126, v176, v126, v180
	v_sub_f32_e32 v127, v127, v192
	v_mul_f32_e32 v127, v127, v193
	v_fma_f32 v127, v177, v127, v181
	v_sub_f32_e32 v128, v128, v192
	v_mul_f32_e32 v128, v128, v193
	v_fma_f32 v128, v178, v128, v182
	v_sub_f32_e32 v129, v129, v192
	v_mul_f32_e32 v129, v129, v193
	v_fma_f32 v129, v179, v129, v183
	v_cvt_pk_bf16_f32 v126, v126, v127
	v_cvt_pk_bf16_f32 v127, v128, v129
	ds_read_b128 v[176:179], v136 offset:128
	ds_read_b128 v[180:183], v136 offset:4224
	s_waitcnt lgkmcnt(2)
	v_sub_f32_e32 v122, v122, v192
	v_mul_f32_e32 v122, v122, v193
	v_fma_f32 v122, v184, v122, v188
	v_sub_f32_e32 v123, v123, v192
	v_mul_f32_e32 v123, v123, v193
	v_fma_f32 v123, v185, v123, v189
	v_sub_f32_e32 v124, v124, v192
	v_mul_f32_e32 v124, v124, v193
	v_fma_f32 v124, v186, v124, v190
	v_sub_f32_e32 v125, v125, v192
	v_mul_f32_e32 v125, v125, v193
	v_fma_f32 v125, v187, v125, v191
	v_cvt_pk_bf16_f32 v128, v122, v123
	v_cvt_pk_bf16_f32 v129, v124, v125
	s_nop 1
	v_permlane16_swap_b32 v126, v128
	v_permlane16_swap_b32 v127, v129
	ds_read_b128 v[184:187], v136 offset:192
	ds_read_b128 v[188:191], v136 offset:4288
	s_waitcnt lgkmcnt(2)
	v_sub_f32_e32 v118, v118, v192
	v_mul_f32_e32 v118, v118, v193
	v_fma_f32 v118, v176, v118, v180
	v_sub_f32_e32 v119, v119, v192
	v_mul_f32_e32 v119, v119, v193
	v_fma_f32 v119, v177, v119, v181
	v_sub_f32_e32 v120, v120, v192
	v_mul_f32_e32 v120, v120, v193
	v_fma_f32 v120, v178, v120, v182
	v_sub_f32_e32 v121, v121, v192
	v_mul_f32_e32 v121, v121, v193
	v_fma_f32 v121, v179, v121, v183
	v_cvt_pk_bf16_f32 v118, v118, v119
	v_cvt_pk_bf16_f32 v119, v120, v121
	ds_read_b128 v[176:179], v136 offset:256
	ds_read_b128 v[180:183], v136 offset:4352
	s_waitcnt lgkmcnt(2)
	v_sub_f32_e32 v114, v114, v192
	v_mul_f32_e32 v114, v114, v193
	v_fma_f32 v114, v184, v114, v188
	v_sub_f32_e32 v115, v115, v192
	v_mul_f32_e32 v115, v115, v193
	v_fma_f32 v115, v185, v115, v189
	v_sub_f32_e32 v116, v116, v192
	v_mul_f32_e32 v116, v116, v193
	v_fma_f32 v116, v186, v116, v190
	v_sub_f32_e32 v117, v117, v192
	v_mul_f32_e32 v117, v117, v193
	v_fma_f32 v117, v187, v117, v191
	v_cvt_pk_bf16_f32 v120, v114, v115
	v_cvt_pk_bf16_f32 v121, v116, v117
	s_nop 1
	v_permlane16_swap_b32 v118, v120
	v_permlane16_swap_b32 v119, v121
	ds_read_b128 v[184:187], v136 offset:320
	ds_read_b128 v[188:191], v136 offset:4416
	s_waitcnt lgkmcnt(2)
	v_sub_f32_e32 v110, v110, v192
	v_mul_f32_e32 v110, v110, v193
	v_fma_f32 v110, v176, v110, v180
	v_sub_f32_e32 v111, v111, v192
	v_mul_f32_e32 v111, v111, v193
	v_fma_f32 v111, v177, v111, v181
	v_sub_f32_e32 v112, v112, v192
	v_mul_f32_e32 v112, v112, v193
	v_fma_f32 v112, v178, v112, v182
	v_sub_f32_e32 v113, v113, v192
	v_mul_f32_e32 v113, v113, v193
	v_fma_f32 v113, v179, v113, v183
	v_cvt_pk_bf16_f32 v110, v110, v111
	v_cvt_pk_bf16_f32 v111, v112, v113
	ds_read_b128 v[176:179], v136 offset:384
	ds_read_b128 v[180:183], v136 offset:4480
	s_waitcnt lgkmcnt(2)
	v_sub_f32_e32 v106, v106, v192
	v_mul_f32_e32 v106, v106, v193
	v_fma_f32 v106, v184, v106, v188
	v_sub_f32_e32 v107, v107, v192
	v_mul_f32_e32 v107, v107, v193
	v_fma_f32 v107, v185, v107, v189
	v_sub_f32_e32 v108, v108, v192
	v_mul_f32_e32 v108, v108, v193
	v_fma_f32 v108, v186, v108, v190
	v_sub_f32_e32 v109, v109, v192
	v_mul_f32_e32 v109, v109, v193
	v_fma_f32 v109, v187, v109, v191
	v_cvt_pk_bf16_f32 v112, v106, v107
	v_cvt_pk_bf16_f32 v113, v108, v109
	s_nop 1
	v_permlane16_swap_b32 v110, v112
	v_permlane16_swap_b32 v111, v113
	ds_read_b128 v[184:187], v136 offset:448
	ds_read_b128 v[188:191], v136 offset:4544
	s_waitcnt lgkmcnt(2)
	v_sub_f32_e32 v102, v102, v192
	v_mul_f32_e32 v102, v102, v193
	v_fma_f32 v102, v176, v102, v180
	v_sub_f32_e32 v103, v103, v192
	v_mul_f32_e32 v103, v103, v193
	v_fma_f32 v103, v177, v103, v181
	v_sub_f32_e32 v104, v104, v192
	v_mul_f32_e32 v104, v104, v193
	v_fma_f32 v104, v178, v104, v182
	v_sub_f32_e32 v105, v105, v192
	v_mul_f32_e32 v105, v105, v193
	v_fma_f32 v105, v179, v105, v183
	v_cvt_pk_bf16_f32 v102, v102, v103
	v_cvt_pk_bf16_f32 v103, v104, v105
	s_waitcnt lgkmcnt(0)
	v_sub_f32_e32 v66, v66, v192
	v_mul_f32_e32 v66, v66, v193
	v_fma_f32 v66, v184, v66, v188
	v_sub_f32_e32 v67, v67, v192
	v_mul_f32_e32 v67, v67, v193
	v_fma_f32 v67, v185, v67, v189
	v_sub_f32_e32 v68, v68, v192
	v_mul_f32_e32 v68, v68, v193
	v_fma_f32 v68, v186, v68, v190
	v_sub_f32_e32 v69, v69, v192
	v_mul_f32_e32 v69, v69, v193
	v_fma_f32 v69, v187, v69, v191
	v_cvt_pk_bf16_f32 v104, v66, v67
	v_cvt_pk_bf16_f32 v105, v68, v69
	s_nop 1
	v_permlane16_swap_b32 v102, v104
	v_permlane16_swap_b32 v103, v105
	s_waitcnt vmcnt(8) lgkmcnt(0)
	s_barrier
; DI void unit_O(const Params& p, char* lds, int l, int tile, int glu_tiles, int tile_b) {
;     ...
;         float s2[2], ss2[2];
; #pragma unroll
;         for (int mh = 0; mh < 2; ++mh) {
;             const int mt = half * 2 + mh, rl = mh * 16 + l15;
;             float s = 0.f, ss = 0.f;
; #pragma unroll
;             for (int nt = 0; nt < 8; ++nt) {
;                 f32x4 xr;
;                 if (l == 0) {
;                     const int chunk = wid * 32 + nt * 4 + quad;
;                     xr = *(const f32x4*)(XR + rl * 4096 + ((chunk ^ l15) << 4));
;                 } else {
;                     const u32x2 hb = *(const u32x2*)(XR + ((wid * 4 + (nt >> 1)) * 32 + rl) * 64 + (nt & 1) * 32 + quad * 8);
;                     xr = (f32x4){bf2f(hb[0] & 0xffffu), bf2f(hb[0] >> 16), bf2f(hb[1] & 0xffffu), bf2f(hb[1] >> 16)};
;                 }
; #pragma unroll
;                 for (int i = 0; i < 4; ++i) { const float v = acc[mt][nt][i] + DN_ALPHA * xr[i]; acc[mt][nt][i] = v; s += v; ss += v * v; }
;             }
;             s2[mh] = s; ss2[mh] = ss;
;         }
; #pragma unroll
;         for (int mh = 0; mh < 2; ++mh) { s2[mh] += __shfl_xor(s2[mh], 16); ss2[mh] += __shfl_xor(ss2[mh], 16); }
; #pragma unroll
;         for (int mh = 0; mh < 2; ++mh) { s2[mh] += __shfl_xor(s2[mh], 32); ss2[mh] += __shfl_xor(ss2[mh], 32); }
;         if (quad == 0) {
; #pragma unroll
;             for (int mh = 0; mh < 2; ++mh) *(f32x2*)&red[((mh * 16 + l15) * 8 + wid) * 2] = (f32x2){s2[mh], ss2[mh]};
;         }
;         __syncthreads();
;         if (half == 0) issue_x(1);
; #pragma unroll
;         for (int mh = 0; mh < 2; ++mh) {
;             const int mt = half * 2 + mh, rl = mh * 16 + l15, row = mt * 16 + l15;
;             float s = 0.f, ss = 0.f;
; #pragma unroll
;             for (int w = 0; w < 4; ++w) { const f32x4 v = *(const f32x4*)&red[rl * 16 + 4 * w]; s += v[0] + v[2]; ss += v[1] + v[3]; }
;             const float mu = s * (1.f / 1024.f);
;             const float var = ss * (1.f / 1024.f) - mu * mu;
;             const float rs = rsqrtf(var + LN_EPS);
;             float* orow = xo + (r0 + row) * 1024 + wid * 128 + quad * 4;
;             bf16_t* brow = xbo + xb_off((int)r0 + row, wid * 128) + quad * 4;
;             const float* gp = GB + wid * 128 + quad * 4;
; #pragma unroll
;             for (int nt = 0; nt < 8; ++nt) {
	ds_read_b128 v[144:147], v200
	ds_read_b128 v[148:151], v201
	ds_read_b128 v[152:155], v202
	ds_read_b128 v[156:159], v203
	ds_read_b128 v[160:163], v200 offset:256
	ds_read_b128 v[164:167], v201 offset:256
	ds_read_b128 v[168:171], v202 offset:256
	ds_read_b128 v[172:175], v203 offset:256
	s_waitcnt lgkmcnt(7)
	v_fmac_f32_e32 v34, s58, v144
	v_fmac_f32_e32 v35, s58, v145
	v_fmac_f32_e32 v36, s58, v146
	v_fmac_f32_e32 v37, s58, v147
	v_mov_b32_e32 v196, v34
	v_mul_f32_e32 v197, v34, v34
	v_mov_b32_e32 v130, v35
	v_mul_f32_e32 v142, v35, v35
	v_add_f32_e32 v196, v196, v36
	v_fmac_f32_e32 v197, v36, v36
	v_add_f32_e32 v130, v130, v37
	v_fmac_f32_e32 v142, v37, v37
	s_waitcnt lgkmcnt(6)
	v_fmac_f32_e32 v30, s58, v148
	v_fmac_f32_e32 v31, s58, v149
	v_fmac_f32_e32 v32, s58, v150
	v_fmac_f32_e32 v33, s58, v151
	v_add_f32_e32 v196, v196, v30
	v_fmac_f32_e32 v197, v30, v30
	v_add_f32_e32 v130, v130, v31
	v_fmac_f32_e32 v142, v31, v31
	v_add_f32_e32 v196, v196, v32
	v_fmac_f32_e32 v197, v32, v32
	v_add_f32_e32 v130, v130, v33
	v_fmac_f32_e32 v142, v33, v33
	s_waitcnt lgkmcnt(5)
	v_fmac_f32_e32 v26, s58, v152
	v_fmac_f32_e32 v27, s58, v153
	v_fmac_f32_e32 v28, s58, v154
	v_fmac_f32_e32 v29, s58, v155
	v_add_f32_e32 v196, v196, v26
	v_fmac_f32_e32 v197, v26, v26
	v_add_f32_e32 v130, v130, v27
	v_fmac_f32_e32 v142, v27, v27
	v_add_f32_e32 v196, v196, v28
	v_fmac_f32_e32 v197, v28, v28
	v_add_f32_e32 v130, v130, v29
	v_fmac_f32_e32 v142, v29, v29
	s_waitcnt lgkmcnt(4)
	v_fmac_f32_e32 v22, s58, v156
	v_fmac_f32_e32 v23, s58, v157
	v_fmac_f32_e32 v24, s58, v158
	v_fmac_f32_e32 v25, s58, v159
	v_add_f32_e32 v196, v196, v22
	v_fmac_f32_e32 v197, v22, v22
	v_add_f32_e32 v130, v130, v23
	v_fmac_f32_e32 v142, v23, v23
	v_add_f32_e32 v196, v196, v24
	v_fmac_f32_e32 v197, v24, v24
	v_add_f32_e32 v130, v130, v25
	v_fmac_f32_e32 v142, v25, v25
	s_waitcnt lgkmcnt(3)
	v_fmac_f32_e32 v18, s58, v160
	v_fmac_f32_e32 v19, s58, v161
	v_fmac_f32_e32 v20, s58, v162
	v_fmac_f32_e32 v21, s58, v163
	v_add_f32_e32 v196, v196, v18
	v_fmac_f32_e32 v197, v18, v18
	v_add_f32_e32 v130, v130, v19
	v_fmac_f32_e32 v142, v19, v19
	v_add_f32_e32 v196, v196, v20
	v_fmac_f32_e32 v197, v20, v20
	v_add_f32_e32 v130, v130, v21
	v_fmac_f32_e32 v142, v21, v21
	s_waitcnt lgkmcnt(2)
	v_fmac_f32_e32 v14, s58, v164
	v_fmac_f32_e32 v15, s58, v165
	v_fmac_f32_e32 v16, s58, v166
	v_fmac_f32_e32 v17, s58, v167
	v_add_f32_e32 v196, v196, v14
	v_fmac_f32_e32 v197, v14, v14
	v_add_f32_e32 v130, v130, v15
	v_fmac_f32_e32 v142, v15, v15
	v_add_f32_e32 v196, v196, v16
	v_fmac_f32_e32 v197, v16, v16
	v_add_f32_e32 v130, v130, v17
	v_fmac_f32_e32 v142, v17, v17
	s_waitcnt lgkmcnt(1)
	v_fmac_f32_e32 v10, s58, v168
	v_fmac_f32_e32 v11, s58, v169
	v_fmac_f32_e32 v12, s58, v170
	v_fmac_f32_e32 v13, s58, v171
	v_add_f32_e32 v196, v196, v10
	v_fmac_f32_e32 v197, v10, v10
	v_add_f32_e32 v130, v130, v11
	v_fmac_f32_e32 v142, v11, v11
	v_add_f32_e32 v196, v196, v12
	v_fmac_f32_e32 v197, v12, v12
	v_add_f32_e32 v130, v130, v13
	v_fmac_f32_e32 v142, v13, v13
	s_waitcnt lgkmcnt(0)
	v_fmac_f32_e32 v6, s58, v172
	v_fmac_f32_e32 v7, s58, v173
	v_fmac_f32_e32 v8, s58, v174
	v_fmac_f32_e32 v9, s58, v175
	v_add_f32_e32 v196, v196, v6
	v_fmac_f32_e32 v197, v6, v6
	v_add_f32_e32 v130, v130, v7
	v_fmac_f32_e32 v142, v7, v7
	v_add_f32_e32 v196, v196, v8
	v_fmac_f32_e32 v197, v8, v8
	v_add_f32_e32 v130, v130, v9
	v_fmac_f32_e32 v142, v9, v9
	v_add_f32_e32 v196, v196, v130
	v_add_f32_e32 v197, v197, v142
	v_mov_b32_e32 v198, v196
	v_mov_b32_e32 v199, v197
	s_nop 1
	v_permlane16_swap_b32 v198, v196
	v_permlane16_swap_b32 v199, v197
	v_add_f32_e32 v196, v196, v198
	v_add_f32_e32 v197, v197, v199
	v_mov_b32_e32 v198, v196
	v_mov_b32_e32 v199, v197
	s_nop 1
	v_permlane32_swap_b32 v198, v196
	v_permlane32_swap_b32 v199, v197
	v_add_f32_e32 v196, v196, v198
	v_add_f32_e32 v197, v197, v199
	s_mov_b64 exec, 0xffff
	ds_write_b64 v134, v[196:197]
	s_mov_b64 exec, -1
	s_waitcnt lgkmcnt(0)
	s_barrier
	ds_read_b128 v[160:163], v135 offset:0
	ds_read_b128 v[164:167], v135 offset:16
	ds_read_b128 v[168:171], v135 offset:32
	ds_read_b128 v[172:175], v135 offset:48
	s_waitcnt lgkmcnt(0)
	v_add_f32_e32 v160, v160, v162
	v_add_f32_e32 v161, v161, v163
	v_add_f32_e32 v164, v164, v166
	v_add_f32_e32 v165, v165, v167
	v_add_f32_e32 v168, v168, v170
	v_add_f32_e32 v169, v169, v171
	v_add_f32_e32 v172, v172, v174
	v_add_f32_e32 v173, v173, v175
	v_add_f32_e32 v160, v160, v164
	v_add_f32_e32 v161, v161, v165
	v_add_f32_e32 v168, v168, v172
	v_add_f32_e32 v169, v169, v173
	v_add_f32_e32 v160, v160, v168
	v_add_f32_e32 v161, v161, v169
	v_mul_f32_e32 v192, 0x3a800000, v160
	v_mul_f32_e32 v193, 0x3a800000, v161
	v_fma_f32 v193, -v192, v192, v193
	v_add_f32_e32 v193, 0x3727c5ac, v193
	v_rsq_f32_e32 v193, v193
	s_nop 0
	ds_read_b128 v[176:179], v136
	ds_read_b128 v[180:183], v136 offset:4096
	ds_read_b128 v[184:187], v136 offset:64
	ds_read_b128 v[188:191], v136 offset:4160
	s_waitcnt lgkmcnt(2)
	v_sub_f32_e32 v34, v34, v192
	v_mul_f32_e32 v34, v34, v193
	v_fma_f32 v34, v176, v34, v180
	v_sub_f32_e32 v35, v35, v192
	v_mul_f32_e32 v35, v35, v193
	v_fma_f32 v35, v177, v35, v181
	v_sub_f32_e32 v36, v36, v192
	v_mul_f32_e32 v36, v36, v193
	v_fma_f32 v36, v178, v36, v182
	v_sub_f32_e32 v37, v37, v192
	v_mul_f32_e32 v37, v37, v193
	v_fma_f32 v37, v179, v37, v183
	v_cvt_pk_bf16_f32 v34, v34, v35
	v_cvt_pk_bf16_f32 v35, v36, v37
	ds_read_b128 v[176:179], v136 offset:128
	ds_read_b128 v[180:183], v136 offset:4224
	s_waitcnt lgkmcnt(2)
; DI unsigned pk2(float lo, float hi) { const f32x2 v = {lo, hi}; const bf16x2_t b = __builtin_convertvector(v, bf16x2_t); return __builtin_bit_cast(unsigned, b); }
; DI float bf2f(unsigned b) { return __uint_as_float(b << 16); }
; DI void unit_O(const Params& p, char* lds, int l, int tile, int glu_tiles, int tile_b) {
;     ...
;         float s2[2], ss2[2];
; #pragma unroll
;         for (int mh = 0; mh < 2; ++mh) {
;             const int mt = half * 2 + mh, rl = mh * 16 + l15;
;             float s = 0.f, ss = 0.f;
; #pragma unroll
;             for (int nt = 0; nt < 8; ++nt) {
;                 f32x4 xr;
;                 if (l == 0) {
;                     const int chunk = wid * 32 + nt * 4 + quad;
;                     xr = *(const f32x4*)(XR + rl * 4096 + ((chunk ^ l15) << 4));
;                 } else {
;                     const u32x2 hb = *(const u32x2*)(XR + ((wid * 4 + (nt >> 1)) * 32 + rl) * 64 + (nt & 1) * 32 + quad * 8);
;                     xr = (f32x4){bf2f(hb[0] & 0xffffu), bf2f(hb[0] >> 16), bf2f(hb[1] & 0xffffu), bf2f(hb[1] >> 16)};
;                 }
; #pragma unroll
;                 for (int i = 0; i < 4; ++i) { const float v = acc[mt][nt][i] + DN_ALPHA * xr[i]; acc[mt][nt][i] = v; s += v; ss += v * v; }
;             }
;             s2[mh] = s; ss2[mh] = ss;
;         }
; #pragma unroll
;         for (int mh = 0; mh < 2; ++mh) { s2[mh] += __shfl_xor(s2[mh], 16); ss2[mh] += __shfl_xor(ss2[mh], 16); }
; #pragma unroll
;         for (int mh = 0; mh < 2; ++mh) { s2[mh] += __shfl_xor(s2[mh], 32); ss2[mh] += __shfl_xor(ss2[mh], 32); }
;         if (quad == 0) {
; #pragma unroll
;             for (int mh = 0; mh < 2; ++mh) *(f32x2*)&red[((mh * 16 + l15) * 8 + wid) * 2] = (f32x2){s2[mh], ss2[mh]};
;         }
;         __syncthreads();
;     ...
; #pragma unroll
;             for (int nt = 0; nt < 8; ++nt) {
;                 const f32x4 g = *(const f32x4*)(gp + nt * 16), bb = *(const f32x4*)(gp + 1024 + nt * 16);
;                 f32x4 o;
; #pragma unroll
;                 for (int i = 0; i < 4; ++i) o[i] = (acc[mt][nt][i] - mu) * rs * g[i] + bb[i];
;                 if (l == 0) *(u32x2*)(brow + (nt >> 1) * 4096 + (nt & 1) * 16) = (u32x2){pk2(o[0], o[1]), pk2(o[2], o[3])};
;                 else *(f32x4*)(orow + nt * 16) = o;
;             }
;         }
	v_sub_f32_e32 v30, v30, v192
	v_mul_f32_e32 v30, v30, v193
	v_fma_f32 v30, v184, v30, v188
	v_sub_f32_e32 v31, v31, v192
	v_mul_f32_e32 v31, v31, v193
	v_fma_f32 v31, v185, v31, v189
	v_sub_f32_e32 v32, v32, v192
	v_mul_f32_e32 v32, v32, v193
	v_fma_f32 v32, v186, v32, v190
	v_sub_f32_e32 v33, v33, v192
	v_mul_f32_e32 v33, v33, v193
	v_fma_f32 v33, v187, v33, v191
	v_cvt_pk_bf16_f32 v36, v30, v31
	v_cvt_pk_bf16_f32 v37, v32, v33
	s_nop 1
	v_permlane16_swap_b32 v34, v36
	v_permlane16_swap_b32 v35, v37
	ds_read_b128 v[184:187], v136 offset:192
	ds_read_b128 v[188:191], v136 offset:4288
	s_waitcnt lgkmcnt(2)
	v_sub_f32_e32 v26, v26, v192
	v_mul_f32_e32 v26, v26, v193
	v_fma_f32 v26, v176, v26, v180
	v_sub_f32_e32 v27, v27, v192
	v_mul_f32_e32 v27, v27, v193
	v_fma_f32 v27, v177, v27, v181
	v_sub_f32_e32 v28, v28, v192
	v_mul_f32_e32 v28, v28, v193
	v_fma_f32 v28, v178, v28, v182
	v_sub_f32_e32 v29, v29, v192
	v_mul_f32_e32 v29, v29, v193
	v_fma_f32 v29, v179, v29, v183
	v_cvt_pk_bf16_f32 v26, v26, v27
	v_cvt_pk_bf16_f32 v27, v28, v29
	ds_read_b128 v[176:179], v136 offset:256
	ds_read_b128 v[180:183], v136 offset:4352
	s_waitcnt lgkmcnt(2)
	v_sub_f32_e32 v22, v22, v192
	v_mul_f32_e32 v22, v22, v193
	v_fma_f32 v22, v184, v22, v188
	v_sub_f32_e32 v23, v23, v192
	v_mul_f32_e32 v23, v23, v193
	v_fma_f32 v23, v185, v23, v189
	v_sub_f32_e32 v24, v24, v192
	v_mul_f32_e32 v24, v24, v193
	v_fma_f32 v24, v186, v24, v190
	v_sub_f32_e32 v25, v25, v192
	v_mul_f32_e32 v25, v25, v193
	v_fma_f32 v25, v187, v25, v191
	v_cvt_pk_bf16_f32 v28, v22, v23
	v_cvt_pk_bf16_f32 v29, v24, v25
	s_nop 1
	v_permlane16_swap_b32 v26, v28
	v_permlane16_swap_b32 v27, v29
	ds_read_b128 v[184:187], v136 offset:320
	ds_read_b128 v[188:191], v136 offset:4416
	s_waitcnt lgkmcnt(2)
	v_sub_f32_e32 v18, v18, v192
	v_mul_f32_e32 v18, v18, v193
	v_fma_f32 v18, v176, v18, v180
	v_sub_f32_e32 v19, v19, v192
	v_mul_f32_e32 v19, v19, v193
	v_fma_f32 v19, v177, v19, v181
	v_sub_f32_e32 v20, v20, v192
	v_mul_f32_e32 v20, v20, v193
	v_fma_f32 v20, v178, v20, v182
	v_sub_f32_e32 v21, v21, v192
	v_mul_f32_e32 v21, v21, v193
	v_fma_f32 v21, v179, v21, v183
	v_cvt_pk_bf16_f32 v18, v18, v19
	v_cvt_pk_bf16_f32 v19, v20, v21
	ds_read_b128 v[176:179], v136 offset:384
	ds_read_b128 v[180:183], v136 offset:4480
	s_waitcnt lgkmcnt(2)
	v_sub_f32_e32 v14, v14, v192
	v_mul_f32_e32 v14, v14, v193
	v_fma_f32 v14, v184, v14, v188
	v_sub_f32_e32 v15, v15, v192
	v_mul_f32_e32 v15, v15, v193
	v_fma_f32 v15, v185, v15, v189
	v_sub_f32_e32 v16, v16, v192
	v_mul_f32_e32 v16, v16, v193
	v_fma_f32 v16, v186, v16, v190
	v_sub_f32_e32 v17, v17, v192
	v_mul_f32_e32 v17, v17, v193
	v_fma_f32 v17, v187, v17, v191
	v_cvt_pk_bf16_f32 v20, v14, v15
	v_cvt_pk_bf16_f32 v21, v16, v17
	s_nop 1
	v_permlane16_swap_b32 v18, v20
	v_permlane16_swap_b32 v19, v21
	ds_read_b128 v[184:187], v136 offset:448
	ds_read_b128 v[188:191], v136 offset:4544
	s_waitcnt lgkmcnt(2)
	v_sub_f32_e32 v10, v10, v192
	v_mul_f32_e32 v10, v10, v193
	v_fma_f32 v10, v176, v10, v180
	v_sub_f32_e32 v11, v11, v192
	v_mul_f32_e32 v11, v11, v193
	v_fma_f32 v11, v177, v11, v181
	v_sub_f32_e32 v12, v12, v192
	v_mul_f32_e32 v12, v12, v193
	v_fma_f32 v12, v178, v12, v182
	v_sub_f32_e32 v13, v13, v192
	v_mul_f32_e32 v13, v13, v193
	v_fma_f32 v13, v179, v13, v183
	v_cvt_pk_bf16_f32 v10, v10, v11
	v_cvt_pk_bf16_f32 v11, v12, v13
	s_waitcnt lgkmcnt(0)
	v_sub_f32_e32 v6, v6, v192
	v_mul_f32_e32 v6, v6, v193
	v_fma_f32 v6, v184, v6, v188
	v_sub_f32_e32 v7, v7, v192
	v_mul_f32_e32 v7, v7, v193
	v_fma_f32 v7, v185, v7, v189
	v_sub_f32_e32 v8, v8, v192
	v_mul_f32_e32 v8, v8, v193
	v_fma_f32 v8, v186, v8, v190
	v_sub_f32_e32 v9, v9, v192
	v_mul_f32_e32 v9, v9, v193
	v_fma_f32 v9, v187, v9, v191
	v_cvt_pk_bf16_f32 v12, v6, v7
	v_cvt_pk_bf16_f32 v13, v8, v9
	s_nop 1
	v_permlane16_swap_b32 v10, v12
	v_permlane16_swap_b32 v11, v13
	s_waitcnt vmcnt(0) lgkmcnt(0)
	s_barrier
	ds_read_b128 v[144:147], v204
	ds_read_b128 v[148:151], v205
	ds_read_b128 v[152:155], v206
	ds_read_b128 v[156:159], v207
	ds_read_b128 v[160:163], v204 offset:256
	ds_read_b128 v[164:167], v205 offset:256
	ds_read_b128 v[168:171], v206 offset:256
	ds_read_b128 v[172:175], v207 offset:256
	s_waitcnt lgkmcnt(7)
	v_fmac_f32_e32 v62, s58, v144
	v_fmac_f32_e32 v63, s58, v145
	v_fmac_f32_e32 v64, s58, v146
	v_fmac_f32_e32 v65, s58, v147
	v_mov_b32_e32 v196, v62
	v_mul_f32_e32 v197, v62, v62
	v_mov_b32_e32 v130, v63
	v_mul_f32_e32 v142, v63, v63
	v_add_f32_e32 v196, v196, v64
	v_fmac_f32_e32 v197, v64, v64
	v_add_f32_e32 v130, v130, v65
	v_fmac_f32_e32 v142, v65, v65
	s_waitcnt lgkmcnt(6)
	v_fmac_f32_e32 v58, s58, v148
	v_fmac_f32_e32 v59, s58, v149
	v_fmac_f32_e32 v60, s58, v150
	v_fmac_f32_e32 v61, s58, v151
	v_add_f32_e32 v196, v196, v58
	v_fmac_f32_e32 v197, v58, v58
	v_add_f32_e32 v130, v130, v59
	v_fmac_f32_e32 v142, v59, v59
	v_add_f32_e32 v196, v196, v60
	v_fmac_f32_e32 v197, v60, v60
	v_add_f32_e32 v130, v130, v61
	v_fmac_f32_e32 v142, v61, v61
	s_waitcnt lgkmcnt(5)
	v_fmac_f32_e32 v54, s58, v152
	v_fmac_f32_e32 v55, s58, v153
	v_fmac_f32_e32 v56, s58, v154
	v_fmac_f32_e32 v57, s58, v155
	v_add_f32_e32 v196, v196, v54
	v_fmac_f32_e32 v197, v54, v54
	v_add_f32_e32 v130, v130, v55
	v_fmac_f32_e32 v142, v55, v55
	v_add_f32_e32 v196, v196, v56
	v_fmac_f32_e32 v197, v56, v56
	v_add_f32_e32 v130, v130, v57
	v_fmac_f32_e32 v142, v57, v57
	s_waitcnt lgkmcnt(4)
	v_fmac_f32_e32 v50, s58, v156
	v_fmac_f32_e32 v51, s58, v157
	v_fmac_f32_e32 v52, s58, v158
	v_fmac_f32_e32 v53, s58, v159
	v_add_f32_e32 v196, v196, v50
	v_fmac_f32_e32 v197, v50, v50
	v_add_f32_e32 v130, v130, v51
	v_fmac_f32_e32 v142, v51, v51
	v_add_f32_e32 v196, v196, v52
	v_fmac_f32_e32 v197, v52, v52
	v_add_f32_e32 v130, v130, v53
	v_fmac_f32_e32 v142, v53, v53
	s_waitcnt lgkmcnt(3)
; DI void unit_O(const Params& p, char* lds, int l, int tile, int glu_tiles, int tile_b) {
;     ...
;         float s2[2], ss2[2];
; #pragma unroll
;         for (int mh = 0; mh < 2; ++mh) {
;             const int mt = half * 2 + mh, rl = mh * 16 + l15;
;             float s = 0.f, ss = 0.f;
; #pragma unroll
;             for (int nt = 0; nt < 8; ++nt) {
;                 f32x4 xr;
;                 if (l == 0) {
;                     const int chunk = wid * 32 + nt * 4 + quad;
;                     xr = *(const f32x4*)(XR + rl * 4096 + ((chunk ^ l15) << 4));
;                 } else {
;                     const u32x2 hb = *(const u32x2*)(XR + ((wid * 4 + (nt >> 1)) * 32 + rl) * 64 + (nt & 1) * 32 + quad * 8);
;                     xr = (f32x4){bf2f(hb[0] & 0xffffu), bf2f(hb[0] >> 16), bf2f(hb[1] & 0xffffu), bf2f(hb[1] >> 16)};
;                 }
; #pragma unroll
;                 for (int i = 0; i < 4; ++i) { const float v = acc[mt][nt][i] + DN_ALPHA * xr[i]; acc[mt][nt][i] = v; s += v; ss += v * v; }
;             }
;             s2[mh] = s; ss2[mh] = ss;
;         }
; #pragma unroll
;         for (int mh = 0; mh < 2; ++mh) { s2[mh] += __shfl_xor(s2[mh], 16); ss2[mh] += __shfl_xor(ss2[mh], 16); }
; #pragma unroll
;         for (int mh = 0; mh < 2; ++mh) { s2[mh] += __shfl_xor(s2[mh], 32); ss2[mh] += __shfl_xor(ss2[mh], 32); }
;         if (quad == 0) {
; #pragma unroll
;             for (int mh = 0; mh < 2; ++mh) *(f32x2*)&red[((mh * 16 + l15) * 8 + wid) * 2] = (f32x2){s2[mh], ss2[mh]};
;         }
;         __syncthreads();
;         if (half == 0) issue_x(1);
; #pragma unroll
;         for (int mh = 0; mh < 2; ++mh) {
;             const int mt = half * 2 + mh, rl = mh * 16 + l15, row = mt * 16 + l15;
;             float s = 0.f, ss = 0.f;
; #pragma unroll
;             for (int w = 0; w < 4; ++w) { const f32x4 v = *(const f32x4*)&red[rl * 16 + 4 * w]; s += v[0] + v[2]; ss += v[1] + v[3]; }
;             const float mu = s * (1.f / 1024.f);
;             const float var = ss * (1.f / 1024.f) - mu * mu;
;             const float rs = rsqrtf(var + LN_EPS);
;             float* orow = xo + (r0 + row) * 1024 + wid * 128 + quad * 4;
;             bf16_t* brow = xbo + xb_off((int)r0 + row, wid * 128) + quad * 4;
;             const float* gp = GB + wid * 128 + quad * 4;
; #pragma unroll
;             for (int nt = 0; nt < 8; ++nt) {
	v_fmac_f32_e32 v46, s58, v160
	v_fmac_f32_e32 v47, s58, v161
	v_fmac_f32_e32 v48, s58, v162
	v_fmac_f32_e32 v49, s58, v163
	v_add_f32_e32 v196, v196, v46
	v_fmac_f32_e32 v197, v46, v46
	v_add_f32_e32 v130, v130, v47
	v_fmac_f32_e32 v142, v47, v47
	v_add_f32_e32 v196, v196, v48
	v_fmac_f32_e32 v197, v48, v48
	v_add_f32_e32 v130, v130, v49
	v_fmac_f32_e32 v142, v49, v49
	s_waitcnt lgkmcnt(2)
	v_fmac_f32_e32 v42, s58, v164
	v_fmac_f32_e32 v43, s58, v165
	v_fmac_f32_e32 v44, s58, v166
	v_fmac_f32_e32 v45, s58, v167
	v_add_f32_e32 v196, v196, v42
	v_fmac_f32_e32 v197, v42, v42
	v_add_f32_e32 v130, v130, v43
	v_fmac_f32_e32 v142, v43, v43
	v_add_f32_e32 v196, v196, v44
	v_fmac_f32_e32 v197, v44, v44
	v_add_f32_e32 v130, v130, v45
	v_fmac_f32_e32 v142, v45, v45
	s_waitcnt lgkmcnt(1)
	v_fmac_f32_e32 v38, s58, v168
	v_fmac_f32_e32 v39, s58, v169
	v_fmac_f32_e32 v40, s58, v170
	v_fmac_f32_e32 v41, s58, v171
	v_add_f32_e32 v196, v196, v38
	v_fmac_f32_e32 v197, v38, v38
	v_add_f32_e32 v130, v130, v39
	v_fmac_f32_e32 v142, v39, v39
	v_add_f32_e32 v196, v196, v40
	v_fmac_f32_e32 v197, v40, v40
	v_add_f32_e32 v130, v130, v41
	v_fmac_f32_e32 v142, v41, v41
	s_waitcnt lgkmcnt(0)
	v_fmac_f32_e32 v2, s58, v172
	v_fmac_f32_e32 v3, s58, v173
	v_fmac_f32_e32 v4, s58, v174
	v_fmac_f32_e32 v5, s58, v175
	v_add_f32_e32 v196, v196, v2
	v_fmac_f32_e32 v197, v2, v2
	v_add_f32_e32 v130, v130, v3
	v_fmac_f32_e32 v142, v3, v3
	v_add_f32_e32 v196, v196, v4
	v_fmac_f32_e32 v197, v4, v4
	v_add_f32_e32 v130, v130, v5
	v_fmac_f32_e32 v142, v5, v5
	v_add_f32_e32 v196, v196, v130
	v_add_f32_e32 v197, v197, v142
	v_mov_b32_e32 v198, v196
	v_mov_b32_e32 v199, v197
	s_nop 1
	v_permlane16_swap_b32 v198, v196
	v_permlane16_swap_b32 v199, v197
	v_add_f32_e32 v196, v196, v198
	v_add_f32_e32 v197, v197, v199
	v_mov_b32_e32 v198, v196
	v_mov_b32_e32 v199, v197
	s_nop 1
	v_permlane32_swap_b32 v198, v196
	v_permlane32_swap_b32 v199, v197
	v_add_f32_e32 v196, v196, v198
	v_add_f32_e32 v197, v197, v199
	s_mov_b64 exec, 0xffff
	ds_write_b64 v134, v[196:197]
	s_mov_b64 exec, -1
	s_waitcnt lgkmcnt(0)
	s_barrier
	ds_read_b128 v[160:163], v135 offset:0
	ds_read_b128 v[164:167], v135 offset:16
	ds_read_b128 v[168:171], v135 offset:32
	ds_read_b128 v[172:175], v135 offset:48
	s_waitcnt lgkmcnt(0)
	v_add_f32_e32 v160, v160, v162
	v_add_f32_e32 v161, v161, v163
	v_add_f32_e32 v164, v164, v166
	v_add_f32_e32 v165, v165, v167
	v_add_f32_e32 v168, v168, v170
	v_add_f32_e32 v169, v169, v171
	v_add_f32_e32 v172, v172, v174
	v_add_f32_e32 v173, v173, v175
	v_add_f32_e32 v160, v160, v164
	v_add_f32_e32 v161, v161, v165
	v_add_f32_e32 v168, v168, v172
	v_add_f32_e32 v169, v169, v173
	v_add_f32_e32 v160, v160, v168
	v_add_f32_e32 v161, v161, v169
	v_mul_f32_e32 v192, 0x3a800000, v160
	v_mul_f32_e32 v193, 0x3a800000, v161
	v_fma_f32 v193, -v192, v192, v193
	v_add_f32_e32 v193, 0x3727c5ac, v193
	v_rsq_f32_e32 v193, v193
	s_nop 0
	ds_read_b128 v[176:179], v136
	ds_read_b128 v[180:183], v136 offset:4096
	ds_read_b128 v[184:187], v136 offset:64
	ds_read_b128 v[188:191], v136 offset:4160
	s_waitcnt lgkmcnt(2)
	v_sub_f32_e32 v62, v62, v192
	v_mul_f32_e32 v62, v62, v193
	v_fma_f32 v62, v176, v62, v180
	v_sub_f32_e32 v63, v63, v192
	v_mul_f32_e32 v63, v63, v193
	v_fma_f32 v63, v177, v63, v181
	v_sub_f32_e32 v64, v64, v192
	v_mul_f32_e32 v64, v64, v193
	v_fma_f32 v64, v178, v64, v182
	v_sub_f32_e32 v65, v65, v192
	v_mul_f32_e32 v65, v65, v193
	v_fma_f32 v65, v179, v65, v183
	v_cvt_pk_bf16_f32 v62, v62, v63
	v_cvt_pk_bf16_f32 v63, v64, v65
	ds_read_b128 v[176:179], v136 offset:128
	ds_read_b128 v[180:183], v136 offset:4224
	s_waitcnt lgkmcnt(2)
	v_sub_f32_e32 v58, v58, v192
	v_mul_f32_e32 v58, v58, v193
	v_fma_f32 v58, v184, v58, v188
	v_sub_f32_e32 v59, v59, v192
	v_mul_f32_e32 v59, v59, v193
	v_fma_f32 v59, v185, v59, v189
	v_sub_f32_e32 v60, v60, v192
	v_mul_f32_e32 v60, v60, v193
	v_fma_f32 v60, v186, v60, v190
	v_sub_f32_e32 v61, v61, v192
	v_mul_f32_e32 v61, v61, v193
	v_fma_f32 v61, v187, v61, v191
	v_cvt_pk_bf16_f32 v64, v58, v59
	v_cvt_pk_bf16_f32 v65, v60, v61
	s_nop 1
	v_permlane16_swap_b32 v62, v64
	v_permlane16_swap_b32 v63, v65
	ds_read_b128 v[184:187], v136 offset:192
	ds_read_b128 v[188:191], v136 offset:4288
	s_waitcnt lgkmcnt(2)
	v_sub_f32_e32 v54, v54, v192
	v_mul_f32_e32 v54, v54, v193
	v_fma_f32 v54, v176, v54, v180
	v_sub_f32_e32 v55, v55, v192
	v_mul_f32_e32 v55, v55, v193
	v_fma_f32 v55, v177, v55, v181
	v_sub_f32_e32 v56, v56, v192
	v_mul_f32_e32 v56, v56, v193
	v_fma_f32 v56, v178, v56, v182
	v_sub_f32_e32 v57, v57, v192
	v_mul_f32_e32 v57, v57, v193
	v_fma_f32 v57, v179, v57, v183
	v_cvt_pk_bf16_f32 v54, v54, v55
	v_cvt_pk_bf16_f32 v55, v56, v57
	ds_read_b128 v[176:179], v136 offset:256
	ds_read_b128 v[180:183], v136 offset:4352
	s_waitcnt lgkmcnt(2)
	v_sub_f32_e32 v50, v50, v192
	v_mul_f32_e32 v50, v50, v193
	v_fma_f32 v50, v184, v50, v188
	v_sub_f32_e32 v51, v51, v192
	v_mul_f32_e32 v51, v51, v193
	v_fma_f32 v51, v185, v51, v189
	v_sub_f32_e32 v52, v52, v192
	v_mul_f32_e32 v52, v52, v193
	v_fma_f32 v52, v186, v52, v190
	v_sub_f32_e32 v53, v53, v192
	v_mul_f32_e32 v53, v53, v193
	v_fma_f32 v53, v187, v53, v191
	v_cvt_pk_bf16_f32 v56, v50, v51
	v_cvt_pk_bf16_f32 v57, v52, v53
	s_nop 1
	v_permlane16_swap_b32 v54, v56
	v_permlane16_swap_b32 v55, v57
	ds_read_b128 v[184:187], v136 offset:320
	ds_read_b128 v[188:191], v136 offset:4416
	s_waitcnt lgkmcnt(2)
; DI unsigned pk2(float lo, float hi) { const f32x2 v = {lo, hi}; const bf16x2_t b = __builtin_convertvector(v, bf16x2_t); return __builtin_bit_cast(unsigned, b); }
; DI void unit_O(const Params& p, char* lds, int l, int tile, int glu_tiles, int tile_b) {
;     ...
;     auto issue_x = [&](int half) {
;         if (l == 0) {
; #pragma unroll 1
;             for (int i = 0; i < 16; ++i) {
;                 const int pc = (wid * 16 + i + xrot) & 127, row = pc >> 2, phys = (pc & 3) * 64 + lane, logical = phys ^ (row & 15);
;                 __builtin_amdgcn_global_load_lds((const unsigned*)(xres + (r0 + half * 32 + row) * 1024 + logical * 4), (unsigned*)(XR + pc * 1024 + lane * 16), 16, 0, 0);
;             }
;         } else {
; #pragma unroll 1
;             for (int i = 0; i < 8; ++i) {
;                 const int pc = (wid * 8 + i + (xrot >> 1)) & 63, kt = pc >> 1, sub = pc & 1;
;                 __builtin_amdgcn_global_load_lds((const unsigned*)(xbres + ((size_t)kt * 128 + half * 32) * 32 + sub * 512 + lane * 8), (unsigned*)(XR + pc * 1024 + lane * 16), 16, 0, 0);
;             }
;         }
;     };
;     issue_x(0);
;     ...
; #pragma unroll
;             for (int nt = 0; nt < 8; ++nt) {
;                 const f32x4 g = *(const f32x4*)(gp + nt * 16), bb = *(const f32x4*)(gp + 1024 + nt * 16);
;                 f32x4 o;
; #pragma unroll
;                 for (int i = 0; i < 4; ++i) o[i] = (acc[mt][nt][i] - mu) * rs * g[i] + bb[i];
;                 if (l == 0) *(u32x2*)(brow + (nt >> 1) * 4096 + (nt & 1) * 16) = (u32x2){pk2(o[0], o[1]), pk2(o[2], o[3])};
;                 else *(f32x4*)(orow + nt * 16) = o;
;             }
	v_sub_f32_e32 v46, v46, v192
	v_mul_f32_e32 v46, v46, v193
	v_fma_f32 v46, v176, v46, v180
	v_sub_f32_e32 v47, v47, v192
	v_mul_f32_e32 v47, v47, v193
	v_fma_f32 v47, v177, v47, v181
	v_sub_f32_e32 v48, v48, v192
	v_mul_f32_e32 v48, v48, v193
	v_fma_f32 v48, v178, v48, v182
	v_sub_f32_e32 v49, v49, v192
	v_mul_f32_e32 v49, v49, v193
	v_fma_f32 v49, v179, v49, v183
	v_cvt_pk_bf16_f32 v46, v46, v47
	v_cvt_pk_bf16_f32 v47, v48, v49
	ds_read_b128 v[176:179], v136 offset:384
	ds_read_b128 v[180:183], v136 offset:4480
	s_waitcnt lgkmcnt(2)
	v_sub_f32_e32 v42, v42, v192
	v_mul_f32_e32 v42, v42, v193
	v_fma_f32 v42, v184, v42, v188
	v_sub_f32_e32 v43, v43, v192
	v_mul_f32_e32 v43, v43, v193
	v_fma_f32 v43, v185, v43, v189
	v_sub_f32_e32 v44, v44, v192
	v_mul_f32_e32 v44, v44, v193
	v_fma_f32 v44, v186, v44, v190
	v_sub_f32_e32 v45, v45, v192
	v_mul_f32_e32 v45, v45, v193
	v_fma_f32 v45, v187, v45, v191
	v_cvt_pk_bf16_f32 v48, v42, v43
	v_cvt_pk_bf16_f32 v49, v44, v45
	s_nop 1
	v_permlane16_swap_b32 v46, v48
	v_permlane16_swap_b32 v47, v49
	ds_read_b128 v[184:187], v136 offset:448
	ds_read_b128 v[188:191], v136 offset:4544
	s_waitcnt lgkmcnt(2)
	v_sub_f32_e32 v38, v38, v192
	v_mul_f32_e32 v38, v38, v193
	v_fma_f32 v38, v176, v38, v180
	v_sub_f32_e32 v39, v39, v192
	v_mul_f32_e32 v39, v39, v193
	v_fma_f32 v39, v177, v39, v181
	v_sub_f32_e32 v40, v40, v192
	v_mul_f32_e32 v40, v40, v193
	v_fma_f32 v40, v178, v40, v182
	v_sub_f32_e32 v41, v41, v192
	v_mul_f32_e32 v41, v41, v193
	v_fma_f32 v41, v179, v41, v183
	v_cvt_pk_bf16_f32 v38, v38, v39
	v_cvt_pk_bf16_f32 v39, v40, v41
	s_waitcnt lgkmcnt(0)
	v_sub_f32_e32 v2, v2, v192
	v_mul_f32_e32 v2, v2, v193
	v_fma_f32 v2, v184, v2, v188
	v_sub_f32_e32 v3, v3, v192
	v_mul_f32_e32 v3, v3, v193
	v_fma_f32 v3, v185, v3, v189
	v_sub_f32_e32 v4, v4, v192
	v_mul_f32_e32 v4, v4, v193
	v_fma_f32 v4, v186, v4, v190
	v_sub_f32_e32 v5, v5, v192
	v_mul_f32_e32 v5, v5, v193
	v_fma_f32 v5, v187, v5, v191
	v_cvt_pk_bf16_f32 v40, v2, v3
	v_cvt_pk_bf16_f32 v41, v4, v5
	s_nop 1
	v_permlane16_swap_b32 v38, v40
	v_permlane16_swap_b32 v39, v41
	s_add_u32 s94, s78, 0x0
	s_addc_u32 s95, s79, 0
	global_store_dwordx4 v137, v[98:101], s[94:95]
	s_add_u32 s94, s94, 0x2000
	s_addc_u32 s95, s95, 0
	global_store_dwordx4 v137, v[90:93], s[94:95]
	s_add_u32 s94, s94, 0x2000
	s_addc_u32 s95, s95, 0
	global_store_dwordx4 v137, v[82:85], s[94:95]
	s_add_u32 s94, s94, 0x2000
	s_addc_u32 s95, s95, 0
	global_store_dwordx4 v137, v[74:77], s[94:95]
	s_add_u32 s94, s78, 0x400
	s_addc_u32 s95, s79, 0
	global_store_dwordx4 v137, v[126:129], s[94:95]
	s_add_u32 s94, s94, 0x2000
	s_addc_u32 s95, s95, 0
	global_store_dwordx4 v137, v[118:121], s[94:95]
	s_add_u32 s94, s94, 0x2000
	s_addc_u32 s95, s95, 0
	global_store_dwordx4 v137, v[110:113], s[94:95]
	s_add_u32 s94, s94, 0x2000
	s_addc_u32 s95, s95, 0
	global_store_dwordx4 v137, v[102:105], s[94:95]
	s_add_u32 s94, s78, 0x800
	s_addc_u32 s95, s79, 0
	global_store_dwordx4 v137, v[34:37], s[94:95]
	s_add_u32 s94, s94, 0x2000
	s_addc_u32 s95, s95, 0
	global_store_dwordx4 v137, v[26:29], s[94:95]
	s_add_u32 s94, s94, 0x2000
	s_addc_u32 s95, s95, 0
	global_store_dwordx4 v137, v[18:21], s[94:95]
	s_add_u32 s94, s94, 0x2000
	s_addc_u32 s95, s95, 0
	global_store_dwordx4 v137, v[10:13], s[94:95]
	s_add_u32 s94, s78, 0xc00
	s_addc_u32 s95, s79, 0
	global_store_dwordx4 v137, v[62:65], s[94:95]
	s_add_u32 s94, s94, 0x2000
	s_addc_u32 s95, s95, 0
	global_store_dwordx4 v137, v[54:57], s[94:95]
	s_add_u32 s94, s94, 0x2000
	s_addc_u32 s95, s95, 0
	global_store_dwordx4 v137, v[46:49], s[94:95]
	s_add_u32 s94, s94, 0x2000
	s_addc_u32 s95, s95, 0
	global_store_dwordx4 v137, v[38:41], s[94:95]
	s_branch .Le2_done
.Le2_l1:
	s_lshr_b32 s40, s48, 1
	s_lshl_b32 s40, s40, 18
	s_and_b32 s94, s48, 1
	s_lshl_b32 s94, s94, 12
	s_add_u32 s40, s40, s94
	s_lshl_b32 s91, s90, 12
	s_lshl_b32 s94, s90, 15
	s_add_u32 s96, s56, s40
	s_addc_u32 s97, s57, 0
	s_add_u32 s96, s96, s94
	s_addc_u32 s97, s97, 0
	v_lshlrev_b32_e32 v208, 4, v141
	v_lshlrev_b32_e32 v133, 12, v140
	v_lshl_add_u32 v133, v138, 6, v133
	v_lshl_add_u32 v133, v139, 3, v133
	v_lshlrev_b32_e32 v137, 12, v138
	v_lshl_add_u32 v137, v140, 9, v137
	v_lshl_add_u32 v137, v139, 4, v137
	s_lshl_b32 s40, s48, 18
	s_add_u32 s78, s16, s40
	s_addc_u32 s79, s17, 0
	s_add_u32 s92, s96, 0x0
	s_addc_u32 s93, s97, 0
	s_add_u32 s40, s91, 0x0
	s_mov_b32 m0, s40
	s_nop 0
	global_load_lds_dwordx4 v208, s[92:93]
	s_add_u32 s92, s92, 0x2000
	s_addc_u32 s93, s93, 0
	s_add_u32 m0, m0, 0x400
	s_nop 0
	global_load_lds_dwordx4 v208, s[92:93]
	s_add_u32 s92, s92, 0x2000
	s_addc_u32 s93, s93, 0
	s_add_u32 m0, m0, 0x400
	s_nop 0
	global_load_lds_dwordx4 v208, s[92:93]
	s_add_u32 s92, s92, 0x2000
	s_addc_u32 s93, s93, 0
	s_add_u32 m0, m0, 0x400
	s_nop 0
	global_load_lds_dwordx4 v208, s[92:93]
	s_add_u32 s92, s96, 0x400
	s_addc_u32 s93, s97, 0
	s_add_u32 s40, s91, 0x8000
	s_mov_b32 m0, s40
	s_nop 0
	global_load_lds_dwordx4 v208, s[92:93]
	s_add_u32 s92, s92, 0x2000
	s_addc_u32 s93, s93, 0
	s_add_u32 m0, m0, 0x400
	s_nop 0
	global_load_lds_dwordx4 v208, s[92:93]
	s_add_u32 s92, s92, 0x2000
	s_addc_u32 s93, s93, 0
	s_add_u32 m0, m0, 0x400
	s_nop 0
	global_load_lds_dwordx4 v208, s[92:93]
	s_add_u32 s92, s92, 0x2000
	s_addc_u32 s93, s93, 0
	s_add_u32 m0, m0, 0x400
	s_nop 0
	global_load_lds_dwordx4 v208, s[92:93]
	s_waitcnt vmcnt(8)
	ds_write_b128 v143, v[176:179]
	s_waitcnt vmcnt(4) lgkmcnt(0)
	s_barrier
; DI float bf2f(unsigned b) { return __uint_as_float(b << 16); }
; DI void unit_O(const Params& p, char* lds, int l, int tile, int glu_tiles, int tile_b) {
;     ...
;         float s2[2], ss2[2];
; #pragma unroll
;         for (int mh = 0; mh < 2; ++mh) {
;             const int mt = half * 2 + mh, rl = mh * 16 + l15;
;             float s = 0.f, ss = 0.f;
; #pragma unroll
;             for (int nt = 0; nt < 8; ++nt) {
;                 f32x4 xr;
;                 if (l == 0) {
;                     const int chunk = wid * 32 + nt * 4 + quad;
;                     xr = *(const f32x4*)(XR + rl * 4096 + ((chunk ^ l15) << 4));
;                 } else {
;                     const u32x2 hb = *(const u32x2*)(XR + ((wid * 4 + (nt >> 1)) * 32 + rl) * 64 + (nt & 1) * 32 + quad * 8);
;                     xr = (f32x4){bf2f(hb[0] & 0xffffu), bf2f(hb[0] >> 16), bf2f(hb[1] & 0xffffu), bf2f(hb[1] >> 16)};
;                 }
; #pragma unroll
;                 for (int i = 0; i < 4; ++i) { const float v = acc[mt][nt][i] + DN_ALPHA * xr[i]; acc[mt][nt][i] = v; s += v; ss += v * v; }
;             }
;             s2[mh] = s; ss2[mh] = ss;
;         }
; #pragma unroll
;         for (int mh = 0; mh < 2; ++mh) { s2[mh] += __shfl_xor(s2[mh], 16); ss2[mh] += __shfl_xor(ss2[mh], 16); }
; #pragma unroll
;         for (int mh = 0; mh < 2; ++mh) { s2[mh] += __shfl_xor(s2[mh], 32); ss2[mh] += __shfl_xor(ss2[mh], 32); }
;         if (quad == 0) {
; #pragma unroll
;             for (int mh = 0; mh < 2; ++mh) *(f32x2*)&red[((mh * 16 + l15) * 8 + wid) * 2] = (f32x2){s2[mh], ss2[mh]};
;         }
;         __syncthreads();
	ds_read_b64 v[180:181], v133 offset:0
	ds_read_b64 v[182:183], v133 offset:32
	ds_read_b64 v[184:185], v133 offset:1024
	ds_read_b64 v[186:187], v133 offset:1056
	ds_read_b64 v[188:189], v133 offset:2048
	ds_read_b64 v[190:191], v133 offset:2080
	ds_read_b64 v[192:193], v133 offset:3072
	ds_read_b64 v[194:195], v133 offset:3104
	s_waitcnt lgkmcnt(7)
	v_lshlrev_b32_e32 v144, 16, v180
	v_and_b32_e32 v145, 0xffff0000, v180
	v_lshlrev_b32_e32 v146, 16, v181
	v_and_b32_e32 v147, 0xffff0000, v181
	v_fmac_f32_e32 v98, s58, v144
	v_fmac_f32_e32 v99, s58, v145
	v_fmac_f32_e32 v100, s58, v146
	v_fmac_f32_e32 v101, s58, v147
	v_mov_b32_e32 v196, v98
	v_mul_f32_e32 v197, v98, v98
	v_mov_b32_e32 v130, v99
	v_mul_f32_e32 v142, v99, v99
	v_add_f32_e32 v196, v196, v100
	v_fmac_f32_e32 v197, v100, v100
	v_add_f32_e32 v130, v130, v101
	v_fmac_f32_e32 v142, v101, v101
	s_waitcnt lgkmcnt(6)
	v_lshlrev_b32_e32 v148, 16, v182
	v_and_b32_e32 v149, 0xffff0000, v182
	v_lshlrev_b32_e32 v150, 16, v183
	v_and_b32_e32 v151, 0xffff0000, v183
	v_fmac_f32_e32 v94, s58, v148
	v_fmac_f32_e32 v95, s58, v149
	v_fmac_f32_e32 v96, s58, v150
	v_fmac_f32_e32 v97, s58, v151
	v_add_f32_e32 v196, v196, v94
	v_fmac_f32_e32 v197, v94, v94
	v_add_f32_e32 v130, v130, v95
	v_fmac_f32_e32 v142, v95, v95
	v_add_f32_e32 v196, v196, v96
	v_fmac_f32_e32 v197, v96, v96
	v_add_f32_e32 v130, v130, v97
	v_fmac_f32_e32 v142, v97, v97
	s_waitcnt lgkmcnt(5)
	v_lshlrev_b32_e32 v152, 16, v184
	v_and_b32_e32 v153, 0xffff0000, v184
	v_lshlrev_b32_e32 v154, 16, v185
	v_and_b32_e32 v155, 0xffff0000, v185
	v_fmac_f32_e32 v90, s58, v152
	v_fmac_f32_e32 v91, s58, v153
	v_fmac_f32_e32 v92, s58, v154
	v_fmac_f32_e32 v93, s58, v155
	v_add_f32_e32 v196, v196, v90
	v_fmac_f32_e32 v197, v90, v90
	v_add_f32_e32 v130, v130, v91
	v_fmac_f32_e32 v142, v91, v91
	v_add_f32_e32 v196, v196, v92
	v_fmac_f32_e32 v197, v92, v92
	v_add_f32_e32 v130, v130, v93
	v_fmac_f32_e32 v142, v93, v93
	s_waitcnt lgkmcnt(4)
	v_lshlrev_b32_e32 v156, 16, v186
	v_and_b32_e32 v157, 0xffff0000, v186
	v_lshlrev_b32_e32 v158, 16, v187
	v_and_b32_e32 v159, 0xffff0000, v187
	v_fmac_f32_e32 v86, s58, v156
	v_fmac_f32_e32 v87, s58, v157
	v_fmac_f32_e32 v88, s58, v158
	v_fmac_f32_e32 v89, s58, v159
	v_add_f32_e32 v196, v196, v86
	v_fmac_f32_e32 v197, v86, v86
	v_add_f32_e32 v130, v130, v87
	v_fmac_f32_e32 v142, v87, v87
	v_add_f32_e32 v196, v196, v88
	v_fmac_f32_e32 v197, v88, v88
	v_add_f32_e32 v130, v130, v89
	v_fmac_f32_e32 v142, v89, v89
	s_waitcnt lgkmcnt(3)
	v_lshlrev_b32_e32 v160, 16, v188
	v_and_b32_e32 v161, 0xffff0000, v188
	v_lshlrev_b32_e32 v162, 16, v189
	v_and_b32_e32 v163, 0xffff0000, v189
	v_fmac_f32_e32 v82, s58, v160
	v_fmac_f32_e32 v83, s58, v161
	v_fmac_f32_e32 v84, s58, v162
	v_fmac_f32_e32 v85, s58, v163
	v_add_f32_e32 v196, v196, v82
	v_fmac_f32_e32 v197, v82, v82
	v_add_f32_e32 v130, v130, v83
	v_fmac_f32_e32 v142, v83, v83
	v_add_f32_e32 v196, v196, v84
	v_fmac_f32_e32 v197, v84, v84
	v_add_f32_e32 v130, v130, v85
	v_fmac_f32_e32 v142, v85, v85
	s_waitcnt lgkmcnt(2)
	v_lshlrev_b32_e32 v164, 16, v190
	v_and_b32_e32 v165, 0xffff0000, v190
	v_lshlrev_b32_e32 v166, 16, v191
	v_and_b32_e32 v167, 0xffff0000, v191
	v_fmac_f32_e32 v78, s58, v164
	v_fmac_f32_e32 v79, s58, v165
	v_fmac_f32_e32 v80, s58, v166
	v_fmac_f32_e32 v81, s58, v167
	v_add_f32_e32 v196, v196, v78
	v_fmac_f32_e32 v197, v78, v78
	v_add_f32_e32 v130, v130, v79
	v_fmac_f32_e32 v142, v79, v79
	v_add_f32_e32 v196, v196, v80
	v_fmac_f32_e32 v197, v80, v80
	v_add_f32_e32 v130, v130, v81
	v_fmac_f32_e32 v142, v81, v81
	s_waitcnt lgkmcnt(1)
	v_lshlrev_b32_e32 v168, 16, v192
	v_and_b32_e32 v169, 0xffff0000, v192
	v_lshlrev_b32_e32 v170, 16, v193
	v_and_b32_e32 v171, 0xffff0000, v193
	v_fmac_f32_e32 v74, s58, v168
	v_fmac_f32_e32 v75, s58, v169
	v_fmac_f32_e32 v76, s58, v170
	v_fmac_f32_e32 v77, s58, v171
	v_add_f32_e32 v196, v196, v74
	v_fmac_f32_e32 v197, v74, v74
	v_add_f32_e32 v130, v130, v75
	v_fmac_f32_e32 v142, v75, v75
	v_add_f32_e32 v196, v196, v76
	v_fmac_f32_e32 v197, v76, v76
	v_add_f32_e32 v130, v130, v77
	v_fmac_f32_e32 v142, v77, v77
	s_waitcnt lgkmcnt(0)
	v_lshlrev_b32_e32 v172, 16, v194
	v_and_b32_e32 v173, 0xffff0000, v194
	v_lshlrev_b32_e32 v174, 16, v195
	v_and_b32_e32 v175, 0xffff0000, v195
	v_fmac_f32_e32 v70, s58, v172
	v_fmac_f32_e32 v71, s58, v173
	v_fmac_f32_e32 v72, s58, v174
	v_fmac_f32_e32 v73, s58, v175
	v_add_f32_e32 v196, v196, v70
	v_fmac_f32_e32 v197, v70, v70
	v_add_f32_e32 v130, v130, v71
	v_fmac_f32_e32 v142, v71, v71
	v_add_f32_e32 v196, v196, v72
	v_fmac_f32_e32 v197, v72, v72
	v_add_f32_e32 v130, v130, v73
	v_fmac_f32_e32 v142, v73, v73
	v_add_f32_e32 v196, v196, v130
	v_add_f32_e32 v197, v197, v142
	v_mov_b32_e32 v198, v196
	v_mov_b32_e32 v199, v197
	s_nop 1
	v_permlane16_swap_b32 v198, v196
	v_permlane16_swap_b32 v199, v197
	v_add_f32_e32 v196, v196, v198
	v_add_f32_e32 v197, v197, v199
	v_mov_b32_e32 v198, v196
	v_mov_b32_e32 v199, v197
	s_nop 1
	v_permlane32_swap_b32 v198, v196
	v_permlane32_swap_b32 v199, v197
	v_add_f32_e32 v196, v196, v198
	v_add_f32_e32 v197, v197, v199
	s_mov_b64 exec, 0xffff
	ds_write_b64 v134, v[196:197]
	s_mov_b64 exec, -1
	s_waitcnt lgkmcnt(0)
	s_barrier
; DI unsigned pk2(float lo, float hi) { const f32x2 v = {lo, hi}; const bf16x2_t b = __builtin_convertvector(v, bf16x2_t); return __builtin_bit_cast(unsigned, b); }
; DI void unit_O(const Params& p, char* lds, int l, int tile, int glu_tiles, int tile_b) {
;     ...
;     auto issue_x = [&](int half) {
;         if (l == 0) {
; #pragma unroll 1
;             for (int i = 0; i < 16; ++i) {
;                 const int pc = (wid * 16 + i + xrot) & 127, row = pc >> 2, phys = (pc & 3) * 64 + lane, logical = phys ^ (row & 15);
;                 __builtin_amdgcn_global_load_lds((const unsigned*)(xres + (r0 + half * 32 + row) * 1024 + logical * 4), (unsigned*)(XR + pc * 1024 + lane * 16), 16, 0, 0);
;             }
;         } else {
; #pragma unroll 1
;             for (int i = 0; i < 8; ++i) {
;                 const int pc = (wid * 8 + i + (xrot >> 1)) & 63, kt = pc >> 1, sub = pc & 1;
;                 __builtin_amdgcn_global_load_lds((const unsigned*)(xbres + ((size_t)kt * 128 + half * 32) * 32 + sub * 512 + lane * 8), (unsigned*)(XR + pc * 1024 + lane * 16), 16, 0, 0);
;             }
;         }
;     ...
; #pragma unroll
;         for (int mh = 0; mh < 2; ++mh) {
;             const int mt = half * 2 + mh, rl = mh * 16 + l15, row = mt * 16 + l15;
;             float s = 0.f, ss = 0.f;
; #pragma unroll
;             for (int w = 0; w < 4; ++w) { const f32x4 v = *(const f32x4*)&red[rl * 16 + 4 * w]; s += v[0] + v[2]; ss += v[1] + v[3]; }
;             const float mu = s * (1.f / 1024.f);
;             const float var = ss * (1.f / 1024.f) - mu * mu;
;             const float rs = rsqrtf(var + LN_EPS);
;             float* orow = xo + (r0 + row) * 1024 + wid * 128 + quad * 4;
;             bf16_t* brow = xbo + xb_off((int)r0 + row, wid * 128) + quad * 4;
;             const float* gp = GB + wid * 128 + quad * 4;
; #pragma unroll
;             for (int nt = 0; nt < 8; ++nt) {
;                 const f32x4 g = *(const f32x4*)(gp + nt * 16), bb = *(const f32x4*)(gp + 1024 + nt * 16);
;                 f32x4 o;
; #pragma unroll
;                 for (int i = 0; i < 4; ++i) o[i] = (acc[mt][nt][i] - mu) * rs * g[i] + bb[i];
;                 if (l == 0) *(u32x2*)(brow + (nt >> 1) * 4096 + (nt & 1) * 16) = (u32x2){pk2(o[0], o[1]), pk2(o[2], o[3])};
;                 else *(f32x4*)(orow + nt * 16) = o;
;             }
;         }
	s_add_u32 s92, s96, 0x800
	s_addc_u32 s93, s97, 0
	s_add_u32 s40, s91, 0x0
	s_mov_b32 m0, s40
	s_nop 0
	global_load_lds_dwordx4 v208, s[92:93]
	s_add_u32 s92, s92, 0x2000
	s_addc_u32 s93, s93, 0
	s_add_u32 m0, m0, 0x400
	s_nop 0
	global_load_lds_dwordx4 v208, s[92:93]
	s_add_u32 s92, s92, 0x2000
	s_addc_u32 s93, s93, 0
	s_add_u32 m0, m0, 0x400
	s_nop 0
	global_load_lds_dwordx4 v208, s[92:93]
	s_add_u32 s92, s92, 0x2000
	s_addc_u32 s93, s93, 0
	s_add_u32 m0, m0, 0x400
	s_nop 0
	global_load_lds_dwordx4 v208, s[92:93]
	ds_read_b128 v[160:163], v135 offset:0
	ds_read_b128 v[164:167], v135 offset:16
	ds_read_b128 v[168:171], v135 offset:32
	ds_read_b128 v[172:175], v135 offset:48
	s_waitcnt lgkmcnt(0)
	v_add_f32_e32 v160, v160, v162
	v_add_f32_e32 v161, v161, v163
	v_add_f32_e32 v164, v164, v166
	v_add_f32_e32 v165, v165, v167
	v_add_f32_e32 v168, v168, v170
	v_add_f32_e32 v169, v169, v171
	v_add_f32_e32 v172, v172, v174
	v_add_f32_e32 v173, v173, v175
	v_add_f32_e32 v160, v160, v164
	v_add_f32_e32 v161, v161, v165
	v_add_f32_e32 v168, v168, v172
	v_add_f32_e32 v169, v169, v173
	v_add_f32_e32 v160, v160, v168
	v_add_f32_e32 v161, v161, v169
	v_mul_f32_e32 v192, 0x3a800000, v160
	v_mul_f32_e32 v193, 0x3a800000, v161
	v_fma_f32 v193, -v192, v192, v193
	v_add_f32_e32 v193, 0x3727c5ac, v193
	v_rsq_f32_e32 v193, v193
	s_nop 0
	ds_read_b128 v[176:179], v136
	ds_read_b128 v[180:183], v136 offset:4096
	ds_read_b128 v[184:187], v136 offset:64
	ds_read_b128 v[188:191], v136 offset:4160
	s_waitcnt lgkmcnt(2)
	v_sub_f32_e32 v98, v98, v192
	v_mul_f32_e32 v98, v98, v193
	v_fma_f32 v98, v176, v98, v180
	v_sub_f32_e32 v99, v99, v192
	v_mul_f32_e32 v99, v99, v193
	v_fma_f32 v99, v177, v99, v181
	v_sub_f32_e32 v100, v100, v192
	v_mul_f32_e32 v100, v100, v193
	v_fma_f32 v100, v178, v100, v182
	v_sub_f32_e32 v101, v101, v192
	v_mul_f32_e32 v101, v101, v193
	v_fma_f32 v101, v179, v101, v183
	ds_read_b128 v[176:179], v136 offset:128
	ds_read_b128 v[180:183], v136 offset:4224
	s_waitcnt lgkmcnt(2)
	v_sub_f32_e32 v94, v94, v192
	v_mul_f32_e32 v94, v94, v193
	v_fma_f32 v94, v184, v94, v188
	v_sub_f32_e32 v95, v95, v192
	v_mul_f32_e32 v95, v95, v193
	v_fma_f32 v95, v185, v95, v189
	v_sub_f32_e32 v96, v96, v192
	v_mul_f32_e32 v96, v96, v193
	v_fma_f32 v96, v186, v96, v190
	v_sub_f32_e32 v97, v97, v192
	v_mul_f32_e32 v97, v97, v193
	v_fma_f32 v97, v187, v97, v191
	ds_read_b128 v[184:187], v136 offset:192
	ds_read_b128 v[188:191], v136 offset:4288
	s_waitcnt lgkmcnt(2)
	v_sub_f32_e32 v90, v90, v192
	v_mul_f32_e32 v90, v90, v193
	v_fma_f32 v90, v176, v90, v180
	v_sub_f32_e32 v91, v91, v192
	v_mul_f32_e32 v91, v91, v193
	v_fma_f32 v91, v177, v91, v181
	v_sub_f32_e32 v92, v92, v192
	v_mul_f32_e32 v92, v92, v193
	v_fma_f32 v92, v178, v92, v182
	v_sub_f32_e32 v93, v93, v192
	v_mul_f32_e32 v93, v93, v193
	v_fma_f32 v93, v179, v93, v183
	ds_read_b128 v[176:179], v136 offset:256
	ds_read_b128 v[180:183], v136 offset:4352
	s_waitcnt lgkmcnt(2)
	v_sub_f32_e32 v86, v86, v192
	v_mul_f32_e32 v86, v86, v193
	v_fma_f32 v86, v184, v86, v188
	v_sub_f32_e32 v87, v87, v192
	v_mul_f32_e32 v87, v87, v193
	v_fma_f32 v87, v185, v87, v189
	v_sub_f32_e32 v88, v88, v192
	v_mul_f32_e32 v88, v88, v193
	v_fma_f32 v88, v186, v88, v190
	v_sub_f32_e32 v89, v89, v192
	v_mul_f32_e32 v89, v89, v193
	v_fma_f32 v89, v187, v89, v191
	ds_read_b128 v[184:187], v136 offset:320
	ds_read_b128 v[188:191], v136 offset:4416
	s_waitcnt lgkmcnt(2)
	v_sub_f32_e32 v82, v82, v192
	v_mul_f32_e32 v82, v82, v193
	v_fma_f32 v82, v176, v82, v180
	v_sub_f32_e32 v83, v83, v192
	v_mul_f32_e32 v83, v83, v193
	v_fma_f32 v83, v177, v83, v181
	v_sub_f32_e32 v84, v84, v192
	v_mul_f32_e32 v84, v84, v193
	v_fma_f32 v84, v178, v84, v182
	v_sub_f32_e32 v85, v85, v192
	v_mul_f32_e32 v85, v85, v193
	v_fma_f32 v85, v179, v85, v183
	ds_read_b128 v[176:179], v136 offset:384
	ds_read_b128 v[180:183], v136 offset:4480
	s_waitcnt lgkmcnt(2)
	v_sub_f32_e32 v78, v78, v192
	v_mul_f32_e32 v78, v78, v193
	v_fma_f32 v78, v184, v78, v188
	v_sub_f32_e32 v79, v79, v192
	v_mul_f32_e32 v79, v79, v193
	v_fma_f32 v79, v185, v79, v189
	v_sub_f32_e32 v80, v80, v192
	v_mul_f32_e32 v80, v80, v193
	v_fma_f32 v80, v186, v80, v190
	v_sub_f32_e32 v81, v81, v192
	v_mul_f32_e32 v81, v81, v193
	v_fma_f32 v81, v187, v81, v191
	ds_read_b128 v[184:187], v136 offset:448
	ds_read_b128 v[188:191], v136 offset:4544
	s_waitcnt lgkmcnt(2)
	v_sub_f32_e32 v74, v74, v192
	v_mul_f32_e32 v74, v74, v193
	v_fma_f32 v74, v176, v74, v180
	v_sub_f32_e32 v75, v75, v192
	v_mul_f32_e32 v75, v75, v193
	v_fma_f32 v75, v177, v75, v181
	v_sub_f32_e32 v76, v76, v192
	v_mul_f32_e32 v76, v76, v193
	v_fma_f32 v76, v178, v76, v182
	v_sub_f32_e32 v77, v77, v192
	v_mul_f32_e32 v77, v77, v193
	v_fma_f32 v77, v179, v77, v183
	s_waitcnt lgkmcnt(0)
	v_sub_f32_e32 v70, v70, v192
	v_mul_f32_e32 v70, v70, v193
	v_fma_f32 v70, v184, v70, v188
	v_sub_f32_e32 v71, v71, v192
	v_mul_f32_e32 v71, v71, v193
	v_fma_f32 v71, v185, v71, v189
	v_sub_f32_e32 v72, v72, v192
	v_mul_f32_e32 v72, v72, v193
	v_fma_f32 v72, v186, v72, v190
	v_sub_f32_e32 v73, v73, v192
	v_mul_f32_e32 v73, v73, v193
	v_fma_f32 v73, v187, v73, v191
	s_waitcnt vmcnt(4) lgkmcnt(0)
	s_barrier
; DI float bf2f(unsigned b) { return __uint_as_float(b << 16); }
; DI void unit_O(const Params& p, char* lds, int l, int tile, int glu_tiles, int tile_b) {
;     ...
;         float s2[2], ss2[2];
; #pragma unroll
;         for (int mh = 0; mh < 2; ++mh) {
;             const int mt = half * 2 + mh, rl = mh * 16 + l15;
;             float s = 0.f, ss = 0.f;
; #pragma unroll
;             for (int nt = 0; nt < 8; ++nt) {
;                 f32x4 xr;
;                 if (l == 0) {
;                     const int chunk = wid * 32 + nt * 4 + quad;
;                     xr = *(const f32x4*)(XR + rl * 4096 + ((chunk ^ l15) << 4));
;                 } else {
;                     const u32x2 hb = *(const u32x2*)(XR + ((wid * 4 + (nt >> 1)) * 32 + rl) * 64 + (nt & 1) * 32 + quad * 8);
;                     xr = (f32x4){bf2f(hb[0] & 0xffffu), bf2f(hb[0] >> 16), bf2f(hb[1] & 0xffffu), bf2f(hb[1] >> 16)};
;                 }
; #pragma unroll
;                 for (int i = 0; i < 4; ++i) { const float v = acc[mt][nt][i] + DN_ALPHA * xr[i]; acc[mt][nt][i] = v; s += v; ss += v * v; }
;             }
;             s2[mh] = s; ss2[mh] = ss;
;         }
; #pragma unroll
;         for (int mh = 0; mh < 2; ++mh) { s2[mh] += __shfl_xor(s2[mh], 16); ss2[mh] += __shfl_xor(ss2[mh], 16); }
; #pragma unroll
;         for (int mh = 0; mh < 2; ++mh) { s2[mh] += __shfl_xor(s2[mh], 32); ss2[mh] += __shfl_xor(ss2[mh], 32); }
;         if (quad == 0) {
; #pragma unroll
;             for (int mh = 0; mh < 2; ++mh) *(f32x2*)&red[((mh * 16 + l15) * 8 + wid) * 2] = (f32x2){s2[mh], ss2[mh]};
;         }
;         __syncthreads();
	ds_read_b64 v[180:181], v133 offset:32768
	ds_read_b64 v[182:183], v133 offset:32800
	ds_read_b64 v[184:185], v133 offset:33792
	ds_read_b64 v[186:187], v133 offset:33824
	ds_read_b64 v[188:189], v133 offset:34816
	ds_read_b64 v[190:191], v133 offset:34848
	ds_read_b64 v[192:193], v133 offset:35840
	ds_read_b64 v[194:195], v133 offset:35872
	s_waitcnt lgkmcnt(7)
	v_lshlrev_b32_e32 v144, 16, v180
	v_and_b32_e32 v145, 0xffff0000, v180
	v_lshlrev_b32_e32 v146, 16, v181
	v_and_b32_e32 v147, 0xffff0000, v181
	v_fmac_f32_e32 v126, s58, v144
	v_fmac_f32_e32 v127, s58, v145
	v_fmac_f32_e32 v128, s58, v146
	v_fmac_f32_e32 v129, s58, v147
	v_mov_b32_e32 v196, v126
	v_mul_f32_e32 v197, v126, v126
	v_mov_b32_e32 v130, v127
	v_mul_f32_e32 v142, v127, v127
	v_add_f32_e32 v196, v196, v128
	v_fmac_f32_e32 v197, v128, v128
	v_add_f32_e32 v130, v130, v129
	v_fmac_f32_e32 v142, v129, v129
	s_waitcnt lgkmcnt(6)
	v_lshlrev_b32_e32 v148, 16, v182
	v_and_b32_e32 v149, 0xffff0000, v182
	v_lshlrev_b32_e32 v150, 16, v183
	v_and_b32_e32 v151, 0xffff0000, v183
	v_fmac_f32_e32 v122, s58, v148
	v_fmac_f32_e32 v123, s58, v149
	v_fmac_f32_e32 v124, s58, v150
	v_fmac_f32_e32 v125, s58, v151
	v_add_f32_e32 v196, v196, v122
	v_fmac_f32_e32 v197, v122, v122
	v_add_f32_e32 v130, v130, v123
	v_fmac_f32_e32 v142, v123, v123
	v_add_f32_e32 v196, v196, v124
	v_fmac_f32_e32 v197, v124, v124
	v_add_f32_e32 v130, v130, v125
	v_fmac_f32_e32 v142, v125, v125
	s_waitcnt lgkmcnt(5)
	v_lshlrev_b32_e32 v152, 16, v184
	v_and_b32_e32 v153, 0xffff0000, v184
	v_lshlrev_b32_e32 v154, 16, v185
	v_and_b32_e32 v155, 0xffff0000, v185
	v_fmac_f32_e32 v118, s58, v152
	v_fmac_f32_e32 v119, s58, v153
	v_fmac_f32_e32 v120, s58, v154
	v_fmac_f32_e32 v121, s58, v155
	v_add_f32_e32 v196, v196, v118
	v_fmac_f32_e32 v197, v118, v118
	v_add_f32_e32 v130, v130, v119
	v_fmac_f32_e32 v142, v119, v119
	v_add_f32_e32 v196, v196, v120
	v_fmac_f32_e32 v197, v120, v120
	v_add_f32_e32 v130, v130, v121
	v_fmac_f32_e32 v142, v121, v121
	s_waitcnt lgkmcnt(4)
	v_lshlrev_b32_e32 v156, 16, v186
	v_and_b32_e32 v157, 0xffff0000, v186
	v_lshlrev_b32_e32 v158, 16, v187
	v_and_b32_e32 v159, 0xffff0000, v187
	v_fmac_f32_e32 v114, s58, v156
	v_fmac_f32_e32 v115, s58, v157
	v_fmac_f32_e32 v116, s58, v158
	v_fmac_f32_e32 v117, s58, v159
	v_add_f32_e32 v196, v196, v114
	v_fmac_f32_e32 v197, v114, v114
	v_add_f32_e32 v130, v130, v115
	v_fmac_f32_e32 v142, v115, v115
	v_add_f32_e32 v196, v196, v116
	v_fmac_f32_e32 v197, v116, v116
	v_add_f32_e32 v130, v130, v117
	v_fmac_f32_e32 v142, v117, v117
	s_waitcnt lgkmcnt(3)
	v_lshlrev_b32_e32 v160, 16, v188
	v_and_b32_e32 v161, 0xffff0000, v188
	v_lshlrev_b32_e32 v162, 16, v189
	v_and_b32_e32 v163, 0xffff0000, v189
	v_fmac_f32_e32 v110, s58, v160
	v_fmac_f32_e32 v111, s58, v161
	v_fmac_f32_e32 v112, s58, v162
	v_fmac_f32_e32 v113, s58, v163
	v_add_f32_e32 v196, v196, v110
	v_fmac_f32_e32 v197, v110, v110
	v_add_f32_e32 v130, v130, v111
	v_fmac_f32_e32 v142, v111, v111
	v_add_f32_e32 v196, v196, v112
	v_fmac_f32_e32 v197, v112, v112
	v_add_f32_e32 v130, v130, v113
	v_fmac_f32_e32 v142, v113, v113
	s_waitcnt lgkmcnt(2)
	v_lshlrev_b32_e32 v164, 16, v190
	v_and_b32_e32 v165, 0xffff0000, v190
	v_lshlrev_b32_e32 v166, 16, v191
	v_and_b32_e32 v167, 0xffff0000, v191
	v_fmac_f32_e32 v106, s58, v164
	v_fmac_f32_e32 v107, s58, v165
	v_fmac_f32_e32 v108, s58, v166
	v_fmac_f32_e32 v109, s58, v167
	v_add_f32_e32 v196, v196, v106
	v_fmac_f32_e32 v197, v106, v106
	v_add_f32_e32 v130, v130, v107
	v_fmac_f32_e32 v142, v107, v107
	v_add_f32_e32 v196, v196, v108
	v_fmac_f32_e32 v197, v108, v108
	v_add_f32_e32 v130, v130, v109
	v_fmac_f32_e32 v142, v109, v109
	s_waitcnt lgkmcnt(1)
	v_lshlrev_b32_e32 v168, 16, v192
	v_and_b32_e32 v169, 0xffff0000, v192
	v_lshlrev_b32_e32 v170, 16, v193
	v_and_b32_e32 v171, 0xffff0000, v193
	v_fmac_f32_e32 v102, s58, v168
	v_fmac_f32_e32 v103, s58, v169
	v_fmac_f32_e32 v104, s58, v170
	v_fmac_f32_e32 v105, s58, v171
	v_add_f32_e32 v196, v196, v102
	v_fmac_f32_e32 v197, v102, v102
	v_add_f32_e32 v130, v130, v103
	v_fmac_f32_e32 v142, v103, v103
	v_add_f32_e32 v196, v196, v104
	v_fmac_f32_e32 v197, v104, v104
	v_add_f32_e32 v130, v130, v105
	v_fmac_f32_e32 v142, v105, v105
	s_waitcnt lgkmcnt(0)
	v_lshlrev_b32_e32 v172, 16, v194
	v_and_b32_e32 v173, 0xffff0000, v194
	v_lshlrev_b32_e32 v174, 16, v195
	v_and_b32_e32 v175, 0xffff0000, v195
	v_fmac_f32_e32 v66, s58, v172
	v_fmac_f32_e32 v67, s58, v173
	v_fmac_f32_e32 v68, s58, v174
	v_fmac_f32_e32 v69, s58, v175
	v_add_f32_e32 v196, v196, v66
	v_fmac_f32_e32 v197, v66, v66
	v_add_f32_e32 v130, v130, v67
	v_fmac_f32_e32 v142, v67, v67
	v_add_f32_e32 v196, v196, v68
	v_fmac_f32_e32 v197, v68, v68
	v_add_f32_e32 v130, v130, v69
	v_fmac_f32_e32 v142, v69, v69
	v_add_f32_e32 v196, v196, v130
	v_add_f32_e32 v197, v197, v142
	v_mov_b32_e32 v198, v196
	v_mov_b32_e32 v199, v197
	s_nop 1
	v_permlane16_swap_b32 v198, v196
	v_permlane16_swap_b32 v199, v197
	v_add_f32_e32 v196, v196, v198
	v_add_f32_e32 v197, v197, v199
	v_mov_b32_e32 v198, v196
	v_mov_b32_e32 v199, v197
	s_nop 1
	v_permlane32_swap_b32 v198, v196
	v_permlane32_swap_b32 v199, v197
	v_add_f32_e32 v196, v196, v198
	v_add_f32_e32 v197, v197, v199
	s_mov_b64 exec, 0xffff
	ds_write_b64 v134, v[196:197]
	s_mov_b64 exec, -1
	s_waitcnt lgkmcnt(0)
	s_barrier
; DI unsigned pk2(float lo, float hi) { const f32x2 v = {lo, hi}; const bf16x2_t b = __builtin_convertvector(v, bf16x2_t); return __builtin_bit_cast(unsigned, b); }
; DI void unit_O(const Params& p, char* lds, int l, int tile, int glu_tiles, int tile_b) {
;     ...
;     auto issue_x = [&](int half) {
;         if (l == 0) {
; #pragma unroll 1
;             for (int i = 0; i < 16; ++i) {
;                 const int pc = (wid * 16 + i + xrot) & 127, row = pc >> 2, phys = (pc & 3) * 64 + lane, logical = phys ^ (row & 15);
;                 __builtin_amdgcn_global_load_lds((const unsigned*)(xres + (r0 + half * 32 + row) * 1024 + logical * 4), (unsigned*)(XR + pc * 1024 + lane * 16), 16, 0, 0);
;             }
;         } else {
; #pragma unroll 1
;             for (int i = 0; i < 8; ++i) {
;                 const int pc = (wid * 8 + i + (xrot >> 1)) & 63, kt = pc >> 1, sub = pc & 1;
;                 __builtin_amdgcn_global_load_lds((const unsigned*)(xbres + ((size_t)kt * 128 + half * 32) * 32 + sub * 512 + lane * 8), (unsigned*)(XR + pc * 1024 + lane * 16), 16, 0, 0);
;             }
;         }
;     ...
; #pragma unroll
;         for (int mh = 0; mh < 2; ++mh) {
;             const int mt = half * 2 + mh, rl = mh * 16 + l15, row = mt * 16 + l15;
;             float s = 0.f, ss = 0.f;
; #pragma unroll
;             for (int w = 0; w < 4; ++w) { const f32x4 v = *(const f32x4*)&red[rl * 16 + 4 * w]; s += v[0] + v[2]; ss += v[1] + v[3]; }
;             const float mu = s * (1.f / 1024.f);
;             const float var = ss * (1.f / 1024.f) - mu * mu;
;             const float rs = rsqrtf(var + LN_EPS);
;             float* orow = xo + (r0 + row) * 1024 + wid * 128 + quad * 4;
;             bf16_t* brow = xbo + xb_off((int)r0 + row, wid * 128) + quad * 4;
;             const float* gp = GB + wid * 128 + quad * 4;
; #pragma unroll
;             for (int nt = 0; nt < 8; ++nt) {
;                 const f32x4 g = *(const f32x4*)(gp + nt * 16), bb = *(const f32x4*)(gp + 1024 + nt * 16);
;                 f32x4 o;
; #pragma unroll
;                 for (int i = 0; i < 4; ++i) o[i] = (acc[mt][nt][i] - mu) * rs * g[i] + bb[i];
;                 if (l == 0) *(u32x2*)(brow + (nt >> 1) * 4096 + (nt & 1) * 16) = (u32x2){pk2(o[0], o[1]), pk2(o[2], o[3])};
;                 else *(f32x4*)(orow + nt * 16) = o;
;             }
;         }
	s_add_u32 s92, s96, 0xc00
	s_addc_u32 s93, s97, 0
	s_add_u32 s40, s91, 0x8000
	s_mov_b32 m0, s40
	s_nop 0
	global_load_lds_dwordx4 v208, s[92:93]
	s_add_u32 s92, s92, 0x2000
	s_addc_u32 s93, s93, 0
	s_add_u32 m0, m0, 0x400
	s_nop 0
	global_load_lds_dwordx4 v208, s[92:93]
	s_add_u32 s92, s92, 0x2000
	s_addc_u32 s93, s93, 0
	s_add_u32 m0, m0, 0x400
	s_nop 0
	global_load_lds_dwordx4 v208, s[92:93]
	s_add_u32 s92, s92, 0x2000
	s_addc_u32 s93, s93, 0
	s_add_u32 m0, m0, 0x400
	s_nop 0
	global_load_lds_dwordx4 v208, s[92:93]
	ds_read_b128 v[160:163], v135 offset:0
	ds_read_b128 v[164:167], v135 offset:16
	ds_read_b128 v[168:171], v135 offset:32
	ds_read_b128 v[172:175], v135 offset:48
	s_waitcnt lgkmcnt(0)
	v_add_f32_e32 v160, v160, v162
	v_add_f32_e32 v161, v161, v163
	v_add_f32_e32 v164, v164, v166
	v_add_f32_e32 v165, v165, v167
	v_add_f32_e32 v168, v168, v170
	v_add_f32_e32 v169, v169, v171
	v_add_f32_e32 v172, v172, v174
	v_add_f32_e32 v173, v173, v175
	v_add_f32_e32 v160, v160, v164
	v_add_f32_e32 v161, v161, v165
	v_add_f32_e32 v168, v168, v172
	v_add_f32_e32 v169, v169, v173
	v_add_f32_e32 v160, v160, v168
	v_add_f32_e32 v161, v161, v169
	v_mul_f32_e32 v192, 0x3a800000, v160
	v_mul_f32_e32 v193, 0x3a800000, v161
	v_fma_f32 v193, -v192, v192, v193
	v_add_f32_e32 v193, 0x3727c5ac, v193
	v_rsq_f32_e32 v193, v193
	s_nop 0
	ds_read_b128 v[176:179], v136
	ds_read_b128 v[180:183], v136 offset:4096
	ds_read_b128 v[184:187], v136 offset:64
	ds_read_b128 v[188:191], v136 offset:4160
	s_waitcnt lgkmcnt(2)
	v_sub_f32_e32 v126, v126, v192
	v_mul_f32_e32 v126, v126, v193
	v_fma_f32 v126, v176, v126, v180
	v_sub_f32_e32 v127, v127, v192
	v_mul_f32_e32 v127, v127, v193
	v_fma_f32 v127, v177, v127, v181
	v_sub_f32_e32 v128, v128, v192
	v_mul_f32_e32 v128, v128, v193
	v_fma_f32 v128, v178, v128, v182
	v_sub_f32_e32 v129, v129, v192
	v_mul_f32_e32 v129, v129, v193
	v_fma_f32 v129, v179, v129, v183
	ds_read_b128 v[176:179], v136 offset:128
	ds_read_b128 v[180:183], v136 offset:4224
	s_waitcnt lgkmcnt(2)
	v_sub_f32_e32 v122, v122, v192
	v_mul_f32_e32 v122, v122, v193
	v_fma_f32 v122, v184, v122, v188
	v_sub_f32_e32 v123, v123, v192
	v_mul_f32_e32 v123, v123, v193
	v_fma_f32 v123, v185, v123, v189
	v_sub_f32_e32 v124, v124, v192
	v_mul_f32_e32 v124, v124, v193
	v_fma_f32 v124, v186, v124, v190
	v_sub_f32_e32 v125, v125, v192
	v_mul_f32_e32 v125, v125, v193
	v_fma_f32 v125, v187, v125, v191
	ds_read_b128 v[184:187], v136 offset:192
	ds_read_b128 v[188:191], v136 offset:4288
	s_waitcnt lgkmcnt(2)
	v_sub_f32_e32 v118, v118, v192
	v_mul_f32_e32 v118, v118, v193
	v_fma_f32 v118, v176, v118, v180
	v_sub_f32_e32 v119, v119, v192
	v_mul_f32_e32 v119, v119, v193
	v_fma_f32 v119, v177, v119, v181
	v_sub_f32_e32 v120, v120, v192
	v_mul_f32_e32 v120, v120, v193
	v_fma_f32 v120, v178, v120, v182
	v_sub_f32_e32 v121, v121, v192
	v_mul_f32_e32 v121, v121, v193
	v_fma_f32 v121, v179, v121, v183
	ds_read_b128 v[176:179], v136 offset:256
	ds_read_b128 v[180:183], v136 offset:4352
	s_waitcnt lgkmcnt(2)
	v_sub_f32_e32 v114, v114, v192
	v_mul_f32_e32 v114, v114, v193
	v_fma_f32 v114, v184, v114, v188
	v_sub_f32_e32 v115, v115, v192
	v_mul_f32_e32 v115, v115, v193
	v_fma_f32 v115, v185, v115, v189
	v_sub_f32_e32 v116, v116, v192
	v_mul_f32_e32 v116, v116, v193
	v_fma_f32 v116, v186, v116, v190
	v_sub_f32_e32 v117, v117, v192
	v_mul_f32_e32 v117, v117, v193
	v_fma_f32 v117, v187, v117, v191
	ds_read_b128 v[184:187], v136 offset:320
	ds_read_b128 v[188:191], v136 offset:4416
	s_waitcnt lgkmcnt(2)
	v_sub_f32_e32 v110, v110, v192
	v_mul_f32_e32 v110, v110, v193
	v_fma_f32 v110, v176, v110, v180
	v_sub_f32_e32 v111, v111, v192
	v_mul_f32_e32 v111, v111, v193
	v_fma_f32 v111, v177, v111, v181
	v_sub_f32_e32 v112, v112, v192
	v_mul_f32_e32 v112, v112, v193
	v_fma_f32 v112, v178, v112, v182
	v_sub_f32_e32 v113, v113, v192
	v_mul_f32_e32 v113, v113, v193
	v_fma_f32 v113, v179, v113, v183
	ds_read_b128 v[176:179], v136 offset:384
	ds_read_b128 v[180:183], v136 offset:4480
	s_waitcnt lgkmcnt(2)
	v_sub_f32_e32 v106, v106, v192
	v_mul_f32_e32 v106, v106, v193
	v_fma_f32 v106, v184, v106, v188
	v_sub_f32_e32 v107, v107, v192
	v_mul_f32_e32 v107, v107, v193
	v_fma_f32 v107, v185, v107, v189
	v_sub_f32_e32 v108, v108, v192
	v_mul_f32_e32 v108, v108, v193
	v_fma_f32 v108, v186, v108, v190
	v_sub_f32_e32 v109, v109, v192
	v_mul_f32_e32 v109, v109, v193
	v_fma_f32 v109, v187, v109, v191
	ds_read_b128 v[184:187], v136 offset:448
	ds_read_b128 v[188:191], v136 offset:4544
	s_waitcnt lgkmcnt(2)
	v_sub_f32_e32 v102, v102, v192
	v_mul_f32_e32 v102, v102, v193
	v_fma_f32 v102, v176, v102, v180
	v_sub_f32_e32 v103, v103, v192
	v_mul_f32_e32 v103, v103, v193
	v_fma_f32 v103, v177, v103, v181
	v_sub_f32_e32 v104, v104, v192
	v_mul_f32_e32 v104, v104, v193
	v_fma_f32 v104, v178, v104, v182
	v_sub_f32_e32 v105, v105, v192
	v_mul_f32_e32 v105, v105, v193
	v_fma_f32 v105, v179, v105, v183
	s_waitcnt lgkmcnt(0)
	v_sub_f32_e32 v66, v66, v192
	v_mul_f32_e32 v66, v66, v193
	v_fma_f32 v66, v184, v66, v188
	v_sub_f32_e32 v67, v67, v192
	v_mul_f32_e32 v67, v67, v193
	v_fma_f32 v67, v185, v67, v189
	v_sub_f32_e32 v68, v68, v192
	v_mul_f32_e32 v68, v68, v193
	v_fma_f32 v68, v186, v68, v190
	v_sub_f32_e32 v69, v69, v192
	v_mul_f32_e32 v69, v69, v193
	v_fma_f32 v69, v187, v69, v191
	s_waitcnt vmcnt(4) lgkmcnt(0)
	s_barrier
; DI float bf2f(unsigned b) { return __uint_as_float(b << 16); }
; DI void unit_O(const Params& p, char* lds, int l, int tile, int glu_tiles, int tile_b) {
;     ...
;         float s2[2], ss2[2];
; #pragma unroll
;         for (int mh = 0; mh < 2; ++mh) {
;             const int mt = half * 2 + mh, rl = mh * 16 + l15;
;             float s = 0.f, ss = 0.f;
; #pragma unroll
;             for (int nt = 0; nt < 8; ++nt) {
;                 f32x4 xr;
;                 if (l == 0) {
;                     const int chunk = wid * 32 + nt * 4 + quad;
;                     xr = *(const f32x4*)(XR + rl * 4096 + ((chunk ^ l15) << 4));
;                 } else {
;                     const u32x2 hb = *(const u32x2*)(XR + ((wid * 4 + (nt >> 1)) * 32 + rl) * 64 + (nt & 1) * 32 + quad * 8);
;                     xr = (f32x4){bf2f(hb[0] & 0xffffu), bf2f(hb[0] >> 16), bf2f(hb[1] & 0xffffu), bf2f(hb[1] >> 16)};
;                 }
; #pragma unroll
;                 for (int i = 0; i < 4; ++i) { const float v = acc[mt][nt][i] + DN_ALPHA * xr[i]; acc[mt][nt][i] = v; s += v; ss += v * v; }
;             }
;             s2[mh] = s; ss2[mh] = ss;
;         }
; #pragma unroll
;         for (int mh = 0; mh < 2; ++mh) { s2[mh] += __shfl_xor(s2[mh], 16); ss2[mh] += __shfl_xor(ss2[mh], 16); }
; #pragma unroll
;         for (int mh = 0; mh < 2; ++mh) { s2[mh] += __shfl_xor(s2[mh], 32); ss2[mh] += __shfl_xor(ss2[mh], 32); }
;         if (quad == 0) {
; #pragma unroll
;             for (int mh = 0; mh < 2; ++mh) *(f32x2*)&red[((mh * 16 + l15) * 8 + wid) * 2] = (f32x2){s2[mh], ss2[mh]};
;         }
;         __syncthreads();
	ds_read_b64 v[180:181], v133 offset:0
	ds_read_b64 v[182:183], v133 offset:32
	ds_read_b64 v[184:185], v133 offset:1024
	ds_read_b64 v[186:187], v133 offset:1056
	ds_read_b64 v[188:189], v133 offset:2048
	ds_read_b64 v[190:191], v133 offset:2080
	ds_read_b64 v[192:193], v133 offset:3072
	ds_read_b64 v[194:195], v133 offset:3104
	s_waitcnt lgkmcnt(7)
	v_lshlrev_b32_e32 v144, 16, v180
	v_and_b32_e32 v145, 0xffff0000, v180
	v_lshlrev_b32_e32 v146, 16, v181
	v_and_b32_e32 v147, 0xffff0000, v181
	v_fmac_f32_e32 v34, s58, v144
	v_fmac_f32_e32 v35, s58, v145
	v_fmac_f32_e32 v36, s58, v146
	v_fmac_f32_e32 v37, s58, v147
	v_mov_b32_e32 v196, v34
	v_mul_f32_e32 v197, v34, v34
	v_mov_b32_e32 v130, v35
	v_mul_f32_e32 v142, v35, v35
	v_add_f32_e32 v196, v196, v36
	v_fmac_f32_e32 v197, v36, v36
	v_add_f32_e32 v130, v130, v37
	v_fmac_f32_e32 v142, v37, v37
	s_waitcnt lgkmcnt(6)
	v_lshlrev_b32_e32 v148, 16, v182
	v_and_b32_e32 v149, 0xffff0000, v182
	v_lshlrev_b32_e32 v150, 16, v183
	v_and_b32_e32 v151, 0xffff0000, v183
	v_fmac_f32_e32 v30, s58, v148
	v_fmac_f32_e32 v31, s58, v149
	v_fmac_f32_e32 v32, s58, v150
	v_fmac_f32_e32 v33, s58, v151
	v_add_f32_e32 v196, v196, v30
	v_fmac_f32_e32 v197, v30, v30
	v_add_f32_e32 v130, v130, v31
	v_fmac_f32_e32 v142, v31, v31
	v_add_f32_e32 v196, v196, v32
	v_fmac_f32_e32 v197, v32, v32
	v_add_f32_e32 v130, v130, v33
	v_fmac_f32_e32 v142, v33, v33
	s_waitcnt lgkmcnt(5)
	v_lshlrev_b32_e32 v152, 16, v184
	v_and_b32_e32 v153, 0xffff0000, v184
	v_lshlrev_b32_e32 v154, 16, v185
	v_and_b32_e32 v155, 0xffff0000, v185
	v_fmac_f32_e32 v26, s58, v152
	v_fmac_f32_e32 v27, s58, v153
	v_fmac_f32_e32 v28, s58, v154
	v_fmac_f32_e32 v29, s58, v155
	v_add_f32_e32 v196, v196, v26
	v_fmac_f32_e32 v197, v26, v26
	v_add_f32_e32 v130, v130, v27
	v_fmac_f32_e32 v142, v27, v27
	v_add_f32_e32 v196, v196, v28
	v_fmac_f32_e32 v197, v28, v28
	v_add_f32_e32 v130, v130, v29
	v_fmac_f32_e32 v142, v29, v29
	s_waitcnt lgkmcnt(4)
	v_lshlrev_b32_e32 v156, 16, v186
	v_and_b32_e32 v157, 0xffff0000, v186
	v_lshlrev_b32_e32 v158, 16, v187
	v_and_b32_e32 v159, 0xffff0000, v187
	v_fmac_f32_e32 v22, s58, v156
	v_fmac_f32_e32 v23, s58, v157
	v_fmac_f32_e32 v24, s58, v158
	v_fmac_f32_e32 v25, s58, v159
	v_add_f32_e32 v196, v196, v22
	v_fmac_f32_e32 v197, v22, v22
	v_add_f32_e32 v130, v130, v23
	v_fmac_f32_e32 v142, v23, v23
	v_add_f32_e32 v196, v196, v24
	v_fmac_f32_e32 v197, v24, v24
	v_add_f32_e32 v130, v130, v25
	v_fmac_f32_e32 v142, v25, v25
	s_waitcnt lgkmcnt(3)
	v_lshlrev_b32_e32 v160, 16, v188
	v_and_b32_e32 v161, 0xffff0000, v188
	v_lshlrev_b32_e32 v162, 16, v189
	v_and_b32_e32 v163, 0xffff0000, v189
	v_fmac_f32_e32 v18, s58, v160
	v_fmac_f32_e32 v19, s58, v161
	v_fmac_f32_e32 v20, s58, v162
	v_fmac_f32_e32 v21, s58, v163
	v_add_f32_e32 v196, v196, v18
	v_fmac_f32_e32 v197, v18, v18
	v_add_f32_e32 v130, v130, v19
	v_fmac_f32_e32 v142, v19, v19
	v_add_f32_e32 v196, v196, v20
	v_fmac_f32_e32 v197, v20, v20
	v_add_f32_e32 v130, v130, v21
	v_fmac_f32_e32 v142, v21, v21
	s_waitcnt lgkmcnt(2)
	v_lshlrev_b32_e32 v164, 16, v190
	v_and_b32_e32 v165, 0xffff0000, v190
	v_lshlrev_b32_e32 v166, 16, v191
	v_and_b32_e32 v167, 0xffff0000, v191
	v_fmac_f32_e32 v14, s58, v164
	v_fmac_f32_e32 v15, s58, v165
	v_fmac_f32_e32 v16, s58, v166
	v_fmac_f32_e32 v17, s58, v167
	v_add_f32_e32 v196, v196, v14
	v_fmac_f32_e32 v197, v14, v14
	v_add_f32_e32 v130, v130, v15
	v_fmac_f32_e32 v142, v15, v15
	v_add_f32_e32 v196, v196, v16
	v_fmac_f32_e32 v197, v16, v16
	v_add_f32_e32 v130, v130, v17
	v_fmac_f32_e32 v142, v17, v17
	s_waitcnt lgkmcnt(1)
	v_lshlrev_b32_e32 v168, 16, v192
	v_and_b32_e32 v169, 0xffff0000, v192
	v_lshlrev_b32_e32 v170, 16, v193
	v_and_b32_e32 v171, 0xffff0000, v193
	v_fmac_f32_e32 v10, s58, v168
	v_fmac_f32_e32 v11, s58, v169
	v_fmac_f32_e32 v12, s58, v170
	v_fmac_f32_e32 v13, s58, v171
	v_add_f32_e32 v196, v196, v10
	v_fmac_f32_e32 v197, v10, v10
	v_add_f32_e32 v130, v130, v11
	v_fmac_f32_e32 v142, v11, v11
	v_add_f32_e32 v196, v196, v12
	v_fmac_f32_e32 v197, v12, v12
	v_add_f32_e32 v130, v130, v13
	v_fmac_f32_e32 v142, v13, v13
	s_waitcnt lgkmcnt(0)
	v_lshlrev_b32_e32 v172, 16, v194
	v_and_b32_e32 v173, 0xffff0000, v194
	v_lshlrev_b32_e32 v174, 16, v195
	v_and_b32_e32 v175, 0xffff0000, v195
	v_fmac_f32_e32 v6, s58, v172
	v_fmac_f32_e32 v7, s58, v173
	v_fmac_f32_e32 v8, s58, v174
	v_fmac_f32_e32 v9, s58, v175
	v_add_f32_e32 v196, v196, v6
	v_fmac_f32_e32 v197, v6, v6
	v_add_f32_e32 v130, v130, v7
	v_fmac_f32_e32 v142, v7, v7
	v_add_f32_e32 v196, v196, v8
	v_fmac_f32_e32 v197, v8, v8
	v_add_f32_e32 v130, v130, v9
	v_fmac_f32_e32 v142, v9, v9
	v_add_f32_e32 v196, v196, v130
	v_add_f32_e32 v197, v197, v142
	v_mov_b32_e32 v198, v196
	v_mov_b32_e32 v199, v197
	s_nop 1
	v_permlane16_swap_b32 v198, v196
	v_permlane16_swap_b32 v199, v197
	v_add_f32_e32 v196, v196, v198
	v_add_f32_e32 v197, v197, v199
	v_mov_b32_e32 v198, v196
	v_mov_b32_e32 v199, v197
	s_nop 1
	v_permlane32_swap_b32 v198, v196
	v_permlane32_swap_b32 v199, v197
	v_add_f32_e32 v196, v196, v198
	v_add_f32_e32 v197, v197, v199
	s_mov_b64 exec, 0xffff
	ds_write_b64 v134, v[196:197]
	s_mov_b64 exec, -1
	s_waitcnt lgkmcnt(0)
	s_barrier
; DI unsigned pk2(float lo, float hi) { const f32x2 v = {lo, hi}; const bf16x2_t b = __builtin_convertvector(v, bf16x2_t); return __builtin_bit_cast(unsigned, b); }
; DI size_t xb_off(int tok, int col) { return ((size_t)(((tok >> 7) * 32 + (col >> 5)) * 128 + (tok & 127))) * 32 + (col & 31); }
; DI void unit_O(const Params& p, char* lds, int l, int tile, int glu_tiles, int tile_b) {
;     ...
; #pragma unroll
;         for (int mh = 0; mh < 2; ++mh) {
;             const int mt = half * 2 + mh, rl = mh * 16 + l15, row = mt * 16 + l15;
;             float s = 0.f, ss = 0.f;
; #pragma unroll
;             for (int w = 0; w < 4; ++w) { const f32x4 v = *(const f32x4*)&red[rl * 16 + 4 * w]; s += v[0] + v[2]; ss += v[1] + v[3]; }
;             const float mu = s * (1.f / 1024.f);
;             const float var = ss * (1.f / 1024.f) - mu * mu;
;             const float rs = rsqrtf(var + LN_EPS);
;             float* orow = xo + (r0 + row) * 1024 + wid * 128 + quad * 4;
;             bf16_t* brow = xbo + xb_off((int)r0 + row, wid * 128) + quad * 4;
;             const float* gp = GB + wid * 128 + quad * 4;
; #pragma unroll
;             for (int nt = 0; nt < 8; ++nt) {
;                 const f32x4 g = *(const f32x4*)(gp + nt * 16), bb = *(const f32x4*)(gp + 1024 + nt * 16);
;                 f32x4 o;
; #pragma unroll
;                 for (int i = 0; i < 4; ++i) o[i] = (acc[mt][nt][i] - mu) * rs * g[i] + bb[i];
;                 if (l == 0) *(u32x2*)(brow + (nt >> 1) * 4096 + (nt & 1) * 16) = (u32x2){pk2(o[0], o[1]), pk2(o[2], o[3])};
;                 else *(f32x4*)(orow + nt * 16) = o;
;             }
;         }
	ds_read_b128 v[160:163], v135 offset:0
	ds_read_b128 v[164:167], v135 offset:16
	ds_read_b128 v[168:171], v135 offset:32
	ds_read_b128 v[172:175], v135 offset:48
	s_waitcnt lgkmcnt(0)
	v_add_f32_e32 v160, v160, v162
	v_add_f32_e32 v161, v161, v163
	v_add_f32_e32 v164, v164, v166
	v_add_f32_e32 v165, v165, v167
	v_add_f32_e32 v168, v168, v170
	v_add_f32_e32 v169, v169, v171
	v_add_f32_e32 v172, v172, v174
	v_add_f32_e32 v173, v173, v175
	v_add_f32_e32 v160, v160, v164
	v_add_f32_e32 v161, v161, v165
	v_add_f32_e32 v168, v168, v172
	v_add_f32_e32 v169, v169, v173
	v_add_f32_e32 v160, v160, v168
	v_add_f32_e32 v161, v161, v169
	v_mul_f32_e32 v192, 0x3a800000, v160
	v_mul_f32_e32 v193, 0x3a800000, v161
	v_fma_f32 v193, -v192, v192, v193
	v_add_f32_e32 v193, 0x3727c5ac, v193
	v_rsq_f32_e32 v193, v193
	s_nop 0
	ds_read_b128 v[176:179], v136
	ds_read_b128 v[180:183], v136 offset:4096
	ds_read_b128 v[184:187], v136 offset:64
	ds_read_b128 v[188:191], v136 offset:4160
	s_waitcnt lgkmcnt(2)
	v_sub_f32_e32 v34, v34, v192
	v_mul_f32_e32 v34, v34, v193
	v_fma_f32 v34, v176, v34, v180
	v_sub_f32_e32 v35, v35, v192
	v_mul_f32_e32 v35, v35, v193
	v_fma_f32 v35, v177, v35, v181
	v_sub_f32_e32 v36, v36, v192
	v_mul_f32_e32 v36, v36, v193
	v_fma_f32 v36, v178, v36, v182
	v_sub_f32_e32 v37, v37, v192
	v_mul_f32_e32 v37, v37, v193
	v_fma_f32 v37, v179, v37, v183
	ds_read_b128 v[176:179], v136 offset:128
	ds_read_b128 v[180:183], v136 offset:4224
	s_waitcnt lgkmcnt(2)
	v_sub_f32_e32 v30, v30, v192
	v_mul_f32_e32 v30, v30, v193
	v_fma_f32 v30, v184, v30, v188
	v_sub_f32_e32 v31, v31, v192
	v_mul_f32_e32 v31, v31, v193
	v_fma_f32 v31, v185, v31, v189
	v_sub_f32_e32 v32, v32, v192
	v_mul_f32_e32 v32, v32, v193
	v_fma_f32 v32, v186, v32, v190
	v_sub_f32_e32 v33, v33, v192
	v_mul_f32_e32 v33, v33, v193
	v_fma_f32 v33, v187, v33, v191
	ds_read_b128 v[184:187], v136 offset:192
	ds_read_b128 v[188:191], v136 offset:4288
	s_waitcnt lgkmcnt(2)
	v_sub_f32_e32 v26, v26, v192
	v_mul_f32_e32 v26, v26, v193
	v_fma_f32 v26, v176, v26, v180
	v_sub_f32_e32 v27, v27, v192
	v_mul_f32_e32 v27, v27, v193
	v_fma_f32 v27, v177, v27, v181
	v_sub_f32_e32 v28, v28, v192
	v_mul_f32_e32 v28, v28, v193
	v_fma_f32 v28, v178, v28, v182
	v_sub_f32_e32 v29, v29, v192
	v_mul_f32_e32 v29, v29, v193
	v_fma_f32 v29, v179, v29, v183
	ds_read_b128 v[176:179], v136 offset:256
	ds_read_b128 v[180:183], v136 offset:4352
	s_waitcnt lgkmcnt(2)
	v_sub_f32_e32 v22, v22, v192
	v_mul_f32_e32 v22, v22, v193
	v_fma_f32 v22, v184, v22, v188
	v_sub_f32_e32 v23, v23, v192
	v_mul_f32_e32 v23, v23, v193
	v_fma_f32 v23, v185, v23, v189
	v_sub_f32_e32 v24, v24, v192
	v_mul_f32_e32 v24, v24, v193
	v_fma_f32 v24, v186, v24, v190
	v_sub_f32_e32 v25, v25, v192
	v_mul_f32_e32 v25, v25, v193
	v_fma_f32 v25, v187, v25, v191
	ds_read_b128 v[184:187], v136 offset:320
	ds_read_b128 v[188:191], v136 offset:4416
	s_waitcnt lgkmcnt(2)
	v_sub_f32_e32 v18, v18, v192
	v_mul_f32_e32 v18, v18, v193
	v_fma_f32 v18, v176, v18, v180
	v_sub_f32_e32 v19, v19, v192
	v_mul_f32_e32 v19, v19, v193
	v_fma_f32 v19, v177, v19, v181
	v_sub_f32_e32 v20, v20, v192
	v_mul_f32_e32 v20, v20, v193
	v_fma_f32 v20, v178, v20, v182
	v_sub_f32_e32 v21, v21, v192
	v_mul_f32_e32 v21, v21, v193
	v_fma_f32 v21, v179, v21, v183
	ds_read_b128 v[176:179], v136 offset:384
	ds_read_b128 v[180:183], v136 offset:4480
	s_waitcnt lgkmcnt(2)
	v_sub_f32_e32 v14, v14, v192
	v_mul_f32_e32 v14, v14, v193
	v_fma_f32 v14, v184, v14, v188
	v_sub_f32_e32 v15, v15, v192
	v_mul_f32_e32 v15, v15, v193
	v_fma_f32 v15, v185, v15, v189
	v_sub_f32_e32 v16, v16, v192
	v_mul_f32_e32 v16, v16, v193
	v_fma_f32 v16, v186, v16, v190
	v_sub_f32_e32 v17, v17, v192
	v_mul_f32_e32 v17, v17, v193
	v_fma_f32 v17, v187, v17, v191
	ds_read_b128 v[184:187], v136 offset:448
	ds_read_b128 v[188:191], v136 offset:4544
	s_waitcnt lgkmcnt(2)
	v_sub_f32_e32 v10, v10, v192
	v_mul_f32_e32 v10, v10, v193
	v_fma_f32 v10, v176, v10, v180
	v_sub_f32_e32 v11, v11, v192
	v_mul_f32_e32 v11, v11, v193
	v_fma_f32 v11, v177, v11, v181
	v_sub_f32_e32 v12, v12, v192
	v_mul_f32_e32 v12, v12, v193
	v_fma_f32 v12, v178, v12, v182
	v_sub_f32_e32 v13, v13, v192
	v_mul_f32_e32 v13, v13, v193
	v_fma_f32 v13, v179, v13, v183
	s_waitcnt lgkmcnt(0)
	v_sub_f32_e32 v6, v6, v192
	v_mul_f32_e32 v6, v6, v193
	v_fma_f32 v6, v184, v6, v188
	v_sub_f32_e32 v7, v7, v192
	v_mul_f32_e32 v7, v7, v193
	v_fma_f32 v7, v185, v7, v189
	v_sub_f32_e32 v8, v8, v192
	v_mul_f32_e32 v8, v8, v193
	v_fma_f32 v8, v186, v8, v190
	v_sub_f32_e32 v9, v9, v192
	v_mul_f32_e32 v9, v9, v193
	v_fma_f32 v9, v187, v9, v191
	s_waitcnt vmcnt(0) lgkmcnt(0)
	s_barrier
; DI float bf2f(unsigned b) { return __uint_as_float(b << 16); }
; DI void unit_O(const Params& p, char* lds, int l, int tile, int glu_tiles, int tile_b) {
;     ...
;         float s2[2], ss2[2];
; #pragma unroll
;         for (int mh = 0; mh < 2; ++mh) {
;             const int mt = half * 2 + mh, rl = mh * 16 + l15;
;             float s = 0.f, ss = 0.f;
; #pragma unroll
;             for (int nt = 0; nt < 8; ++nt) {
;                 f32x4 xr;
;                 if (l == 0) {
;                     const int chunk = wid * 32 + nt * 4 + quad;
;                     xr = *(const f32x4*)(XR + rl * 4096 + ((chunk ^ l15) << 4));
;                 } else {
;                     const u32x2 hb = *(const u32x2*)(XR + ((wid * 4 + (nt >> 1)) * 32 + rl) * 64 + (nt & 1) * 32 + quad * 8);
;                     xr = (f32x4){bf2f(hb[0] & 0xffffu), bf2f(hb[0] >> 16), bf2f(hb[1] & 0xffffu), bf2f(hb[1] >> 16)};
;                 }
; #pragma unroll
;                 for (int i = 0; i < 4; ++i) { const float v = acc[mt][nt][i] + DN_ALPHA * xr[i]; acc[mt][nt][i] = v; s += v; ss += v * v; }
;             }
;             s2[mh] = s; ss2[mh] = ss;
;         }
; #pragma unroll
;         for (int mh = 0; mh < 2; ++mh) { s2[mh] += __shfl_xor(s2[mh], 16); ss2[mh] += __shfl_xor(ss2[mh], 16); }
; #pragma unroll
;         for (int mh = 0; mh < 2; ++mh) { s2[mh] += __shfl_xor(s2[mh], 32); ss2[mh] += __shfl_xor(ss2[mh], 32); }
;         if (quad == 0) {
; #pragma unroll
;             for (int mh = 0; mh < 2; ++mh) *(f32x2*)&red[((mh * 16 + l15) * 8 + wid) * 2] = (f32x2){s2[mh], ss2[mh]};
;         }
;         __syncthreads();
	ds_read_b64 v[180:181], v133 offset:32768
	ds_read_b64 v[182:183], v133 offset:32800
	ds_read_b64 v[184:185], v133 offset:33792
	ds_read_b64 v[186:187], v133 offset:33824
	ds_read_b64 v[188:189], v133 offset:34816
	ds_read_b64 v[190:191], v133 offset:34848
	ds_read_b64 v[192:193], v133 offset:35840
	ds_read_b64 v[194:195], v133 offset:35872
	s_waitcnt lgkmcnt(7)
	v_lshlrev_b32_e32 v144, 16, v180
	v_and_b32_e32 v145, 0xffff0000, v180
	v_lshlrev_b32_e32 v146, 16, v181
	v_and_b32_e32 v147, 0xffff0000, v181
	v_fmac_f32_e32 v62, s58, v144
	v_fmac_f32_e32 v63, s58, v145
	v_fmac_f32_e32 v64, s58, v146
	v_fmac_f32_e32 v65, s58, v147
	v_mov_b32_e32 v196, v62
	v_mul_f32_e32 v197, v62, v62
	v_mov_b32_e32 v130, v63
	v_mul_f32_e32 v142, v63, v63
	v_add_f32_e32 v196, v196, v64
	v_fmac_f32_e32 v197, v64, v64
	v_add_f32_e32 v130, v130, v65
	v_fmac_f32_e32 v142, v65, v65
	s_waitcnt lgkmcnt(6)
	v_lshlrev_b32_e32 v148, 16, v182
	v_and_b32_e32 v149, 0xffff0000, v182
	v_lshlrev_b32_e32 v150, 16, v183
	v_and_b32_e32 v151, 0xffff0000, v183
	v_fmac_f32_e32 v58, s58, v148
	v_fmac_f32_e32 v59, s58, v149
	v_fmac_f32_e32 v60, s58, v150
	v_fmac_f32_e32 v61, s58, v151
	v_add_f32_e32 v196, v196, v58
	v_fmac_f32_e32 v197, v58, v58
	v_add_f32_e32 v130, v130, v59
	v_fmac_f32_e32 v142, v59, v59
	v_add_f32_e32 v196, v196, v60
	v_fmac_f32_e32 v197, v60, v60
	v_add_f32_e32 v130, v130, v61
	v_fmac_f32_e32 v142, v61, v61
	s_waitcnt lgkmcnt(5)
	v_lshlrev_b32_e32 v152, 16, v184
	v_and_b32_e32 v153, 0xffff0000, v184
	v_lshlrev_b32_e32 v154, 16, v185
	v_and_b32_e32 v155, 0xffff0000, v185
	v_fmac_f32_e32 v54, s58, v152
	v_fmac_f32_e32 v55, s58, v153
	v_fmac_f32_e32 v56, s58, v154
	v_fmac_f32_e32 v57, s58, v155
	v_add_f32_e32 v196, v196, v54
	v_fmac_f32_e32 v197, v54, v54
	v_add_f32_e32 v130, v130, v55
	v_fmac_f32_e32 v142, v55, v55
	v_add_f32_e32 v196, v196, v56
	v_fmac_f32_e32 v197, v56, v56
	v_add_f32_e32 v130, v130, v57
	v_fmac_f32_e32 v142, v57, v57
	s_waitcnt lgkmcnt(4)
	v_lshlrev_b32_e32 v156, 16, v186
	v_and_b32_e32 v157, 0xffff0000, v186
	v_lshlrev_b32_e32 v158, 16, v187
	v_and_b32_e32 v159, 0xffff0000, v187
	v_fmac_f32_e32 v50, s58, v156
	v_fmac_f32_e32 v51, s58, v157
	v_fmac_f32_e32 v52, s58, v158
	v_fmac_f32_e32 v53, s58, v159
	v_add_f32_e32 v196, v196, v50
	v_fmac_f32_e32 v197, v50, v50
	v_add_f32_e32 v130, v130, v51
	v_fmac_f32_e32 v142, v51, v51
	v_add_f32_e32 v196, v196, v52
	v_fmac_f32_e32 v197, v52, v52
	v_add_f32_e32 v130, v130, v53
	v_fmac_f32_e32 v142, v53, v53
	s_waitcnt lgkmcnt(3)
	v_lshlrev_b32_e32 v160, 16, v188
	v_and_b32_e32 v161, 0xffff0000, v188
	v_lshlrev_b32_e32 v162, 16, v189
	v_and_b32_e32 v163, 0xffff0000, v189
	v_fmac_f32_e32 v46, s58, v160
	v_fmac_f32_e32 v47, s58, v161
	v_fmac_f32_e32 v48, s58, v162
	v_fmac_f32_e32 v49, s58, v163
	v_add_f32_e32 v196, v196, v46
	v_fmac_f32_e32 v197, v46, v46
	v_add_f32_e32 v130, v130, v47
	v_fmac_f32_e32 v142, v47, v47
	v_add_f32_e32 v196, v196, v48
	v_fmac_f32_e32 v197, v48, v48
	v_add_f32_e32 v130, v130, v49
	v_fmac_f32_e32 v142, v49, v49
	s_waitcnt lgkmcnt(2)
	v_lshlrev_b32_e32 v164, 16, v190
	v_and_b32_e32 v165, 0xffff0000, v190
	v_lshlrev_b32_e32 v166, 16, v191
	v_and_b32_e32 v167, 0xffff0000, v191
	v_fmac_f32_e32 v42, s58, v164
	v_fmac_f32_e32 v43, s58, v165
	v_fmac_f32_e32 v44, s58, v166
	v_fmac_f32_e32 v45, s58, v167
	v_add_f32_e32 v196, v196, v42
	v_fmac_f32_e32 v197, v42, v42
	v_add_f32_e32 v130, v130, v43
	v_fmac_f32_e32 v142, v43, v43
	v_add_f32_e32 v196, v196, v44
	v_fmac_f32_e32 v197, v44, v44
	v_add_f32_e32 v130, v130, v45
	v_fmac_f32_e32 v142, v45, v45
	s_waitcnt lgkmcnt(1)
	v_lshlrev_b32_e32 v168, 16, v192
	v_and_b32_e32 v169, 0xffff0000, v192
	v_lshlrev_b32_e32 v170, 16, v193
	v_and_b32_e32 v171, 0xffff0000, v193
	v_fmac_f32_e32 v38, s58, v168
	v_fmac_f32_e32 v39, s58, v169
	v_fmac_f32_e32 v40, s58, v170
	v_fmac_f32_e32 v41, s58, v171
	v_add_f32_e32 v196, v196, v38
	v_fmac_f32_e32 v197, v38, v38
	v_add_f32_e32 v130, v130, v39
	v_fmac_f32_e32 v142, v39, v39
	v_add_f32_e32 v196, v196, v40
	v_fmac_f32_e32 v197, v40, v40
	v_add_f32_e32 v130, v130, v41
	v_fmac_f32_e32 v142, v41, v41
	s_waitcnt lgkmcnt(0)
	v_lshlrev_b32_e32 v172, 16, v194
	v_and_b32_e32 v173, 0xffff0000, v194
	v_lshlrev_b32_e32 v174, 16, v195
	v_and_b32_e32 v175, 0xffff0000, v195
	v_fmac_f32_e32 v2, s58, v172
	v_fmac_f32_e32 v3, s58, v173
	v_fmac_f32_e32 v4, s58, v174
	v_fmac_f32_e32 v5, s58, v175
	v_add_f32_e32 v196, v196, v2
	v_fmac_f32_e32 v197, v2, v2
	v_add_f32_e32 v130, v130, v3
	v_fmac_f32_e32 v142, v3, v3
	v_add_f32_e32 v196, v196, v4
	v_fmac_f32_e32 v197, v4, v4
	v_add_f32_e32 v130, v130, v5
	v_fmac_f32_e32 v142, v5, v5
	v_add_f32_e32 v196, v196, v130
	v_add_f32_e32 v197, v197, v142
	v_mov_b32_e32 v198, v196
	v_mov_b32_e32 v199, v197
	s_nop 1
	v_permlane16_swap_b32 v198, v196
	v_permlane16_swap_b32 v199, v197
	v_add_f32_e32 v196, v196, v198
	v_add_f32_e32 v197, v197, v199
	v_mov_b32_e32 v198, v196
	v_mov_b32_e32 v199, v197
	s_nop 1
	v_permlane32_swap_b32 v198, v196
	v_permlane32_swap_b32 v199, v197
	v_add_f32_e32 v196, v196, v198
	v_add_f32_e32 v197, v197, v199
	s_mov_b64 exec, 0xffff
	ds_write_b64 v134, v[196:197]
	s_mov_b64 exec, -1
	s_waitcnt lgkmcnt(0)
	s_barrier
; DI unsigned pk2(float lo, float hi) { const f32x2 v = {lo, hi}; const bf16x2_t b = __builtin_convertvector(v, bf16x2_t); return __builtin_bit_cast(unsigned, b); }
; DI size_t xb_off(int tok, int col) { return ((size_t)(((tok >> 7) * 32 + (col >> 5)) * 128 + (tok & 127))) * 32 + (col & 31); }
; DI void unit_O(const Params& p, char* lds, int l, int tile, int glu_tiles, int tile_b) {
;     ...
; #pragma unroll
;         for (int mh = 0; mh < 2; ++mh) {
;             const int mt = half * 2 + mh, rl = mh * 16 + l15, row = mt * 16 + l15;
;             float s = 0.f, ss = 0.f;
; #pragma unroll
;             for (int w = 0; w < 4; ++w) { const f32x4 v = *(const f32x4*)&red[rl * 16 + 4 * w]; s += v[0] + v[2]; ss += v[1] + v[3]; }
;             const float mu = s * (1.f / 1024.f);
;             const float var = ss * (1.f / 1024.f) - mu * mu;
;             const float rs = rsqrtf(var + LN_EPS);
;             float* orow = xo + (r0 + row) * 1024 + wid * 128 + quad * 4;
;             bf16_t* brow = xbo + xb_off((int)r0 + row, wid * 128) + quad * 4;
;             const float* gp = GB + wid * 128 + quad * 4;
; #pragma unroll
;             for (int nt = 0; nt < 8; ++nt) {
;                 const f32x4 g = *(const f32x4*)(gp + nt * 16), bb = *(const f32x4*)(gp + 1024 + nt * 16);
;                 f32x4 o;
; #pragma unroll
;                 for (int i = 0; i < 4; ++i) o[i] = (acc[mt][nt][i] - mu) * rs * g[i] + bb[i];
;                 if (l == 0) *(u32x2*)(brow + (nt >> 1) * 4096 + (nt & 1) * 16) = (u32x2){pk2(o[0], o[1]), pk2(o[2], o[3])};
;                 else *(f32x4*)(orow + nt * 16) = o;
;             }
;         }
	ds_read_b128 v[160:163], v135 offset:0
	ds_read_b128 v[164:167], v135 offset:16
	ds_read_b128 v[168:171], v135 offset:32
	ds_read_b128 v[172:175], v135 offset:48
	s_waitcnt lgkmcnt(0)
	v_add_f32_e32 v160, v160, v162
	v_add_f32_e32 v161, v161, v163
	v_add_f32_e32 v164, v164, v166
	v_add_f32_e32 v165, v165, v167
	v_add_f32_e32 v168, v168, v170
	v_add_f32_e32 v169, v169, v171
	v_add_f32_e32 v172, v172, v174
	v_add_f32_e32 v173, v173, v175
	v_add_f32_e32 v160, v160, v164
	v_add_f32_e32 v161, v161, v165
	v_add_f32_e32 v168, v168, v172
	v_add_f32_e32 v169, v169, v173
	v_add_f32_e32 v160, v160, v168
	v_add_f32_e32 v161, v161, v169
	v_mul_f32_e32 v192, 0x3a800000, v160
	v_mul_f32_e32 v193, 0x3a800000, v161
	v_fma_f32 v193, -v192, v192, v193
	v_add_f32_e32 v193, 0x3727c5ac, v193
	v_rsq_f32_e32 v193, v193
	s_nop 0
	ds_read_b128 v[176:179], v136
	ds_read_b128 v[180:183], v136 offset:4096
	ds_read_b128 v[184:187], v136 offset:64
	ds_read_b128 v[188:191], v136 offset:4160
	s_waitcnt lgkmcnt(2)
	v_sub_f32_e32 v62, v62, v192
	v_mul_f32_e32 v62, v62, v193
	v_fma_f32 v62, v176, v62, v180
	v_sub_f32_e32 v63, v63, v192
	v_mul_f32_e32 v63, v63, v193
	v_fma_f32 v63, v177, v63, v181
	v_sub_f32_e32 v64, v64, v192
	v_mul_f32_e32 v64, v64, v193
	v_fma_f32 v64, v178, v64, v182
	v_sub_f32_e32 v65, v65, v192
	v_mul_f32_e32 v65, v65, v193
	v_fma_f32 v65, v179, v65, v183
	ds_read_b128 v[176:179], v136 offset:128
	ds_read_b128 v[180:183], v136 offset:4224
	s_waitcnt lgkmcnt(2)
	v_sub_f32_e32 v58, v58, v192
	v_mul_f32_e32 v58, v58, v193
	v_fma_f32 v58, v184, v58, v188
	v_sub_f32_e32 v59, v59, v192
	v_mul_f32_e32 v59, v59, v193
	v_fma_f32 v59, v185, v59, v189
	v_sub_f32_e32 v60, v60, v192
	v_mul_f32_e32 v60, v60, v193
	v_fma_f32 v60, v186, v60, v190
	v_sub_f32_e32 v61, v61, v192
	v_mul_f32_e32 v61, v61, v193
	v_fma_f32 v61, v187, v61, v191
	ds_read_b128 v[184:187], v136 offset:192
	ds_read_b128 v[188:191], v136 offset:4288
	s_waitcnt lgkmcnt(2)
	v_sub_f32_e32 v54, v54, v192
	v_mul_f32_e32 v54, v54, v193
	v_fma_f32 v54, v176, v54, v180
	v_sub_f32_e32 v55, v55, v192
	v_mul_f32_e32 v55, v55, v193
	v_fma_f32 v55, v177, v55, v181
	v_sub_f32_e32 v56, v56, v192
	v_mul_f32_e32 v56, v56, v193
	v_fma_f32 v56, v178, v56, v182
	v_sub_f32_e32 v57, v57, v192
	v_mul_f32_e32 v57, v57, v193
	v_fma_f32 v57, v179, v57, v183
	ds_read_b128 v[176:179], v136 offset:256
	ds_read_b128 v[180:183], v136 offset:4352
	s_waitcnt lgkmcnt(2)
	v_sub_f32_e32 v50, v50, v192
	v_mul_f32_e32 v50, v50, v193
	v_fma_f32 v50, v184, v50, v188
	v_sub_f32_e32 v51, v51, v192
	v_mul_f32_e32 v51, v51, v193
	v_fma_f32 v51, v185, v51, v189
	v_sub_f32_e32 v52, v52, v192
	v_mul_f32_e32 v52, v52, v193
	v_fma_f32 v52, v186, v52, v190
	v_sub_f32_e32 v53, v53, v192
	v_mul_f32_e32 v53, v53, v193
	v_fma_f32 v53, v187, v53, v191
	ds_read_b128 v[184:187], v136 offset:320
	ds_read_b128 v[188:191], v136 offset:4416
	s_waitcnt lgkmcnt(2)
	v_sub_f32_e32 v46, v46, v192
	v_mul_f32_e32 v46, v46, v193
	v_fma_f32 v46, v176, v46, v180
	v_sub_f32_e32 v47, v47, v192
	v_mul_f32_e32 v47, v47, v193
	v_fma_f32 v47, v177, v47, v181
	v_sub_f32_e32 v48, v48, v192
	v_mul_f32_e32 v48, v48, v193
	v_fma_f32 v48, v178, v48, v182
	v_sub_f32_e32 v49, v49, v192
	v_mul_f32_e32 v49, v49, v193
	v_fma_f32 v49, v179, v49, v183
	ds_read_b128 v[176:179], v136 offset:384
	ds_read_b128 v[180:183], v136 offset:4480
	s_waitcnt lgkmcnt(2)
	v_sub_f32_e32 v42, v42, v192
	v_mul_f32_e32 v42, v42, v193
	v_fma_f32 v42, v184, v42, v188
	v_sub_f32_e32 v43, v43, v192
	v_mul_f32_e32 v43, v43, v193
	v_fma_f32 v43, v185, v43, v189
	v_sub_f32_e32 v44, v44, v192
	v_mul_f32_e32 v44, v44, v193
	v_fma_f32 v44, v186, v44, v190
	v_sub_f32_e32 v45, v45, v192
	v_mul_f32_e32 v45, v45, v193
	v_fma_f32 v45, v187, v45, v191
	ds_read_b128 v[184:187], v136 offset:448
	ds_read_b128 v[188:191], v136 offset:4544
	s_waitcnt lgkmcnt(2)
	v_sub_f32_e32 v38, v38, v192
	v_mul_f32_e32 v38, v38, v193
	v_fma_f32 v38, v176, v38, v180
	v_sub_f32_e32 v39, v39, v192
	v_mul_f32_e32 v39, v39, v193
	v_fma_f32 v39, v177, v39, v181
	v_sub_f32_e32 v40, v40, v192
	v_mul_f32_e32 v40, v40, v193
	v_fma_f32 v40, v178, v40, v182
	v_sub_f32_e32 v41, v41, v192
	v_mul_f32_e32 v41, v41, v193
	v_fma_f32 v41, v179, v41, v183
	s_waitcnt lgkmcnt(0)
	v_sub_f32_e32 v2, v2, v192
	v_mul_f32_e32 v2, v2, v193
	v_fma_f32 v2, v184, v2, v188
	v_sub_f32_e32 v3, v3, v192
	v_mul_f32_e32 v3, v3, v193
	v_fma_f32 v3, v185, v3, v189
	v_sub_f32_e32 v4, v4, v192
	v_mul_f32_e32 v4, v4, v193
	v_fma_f32 v4, v186, v4, v190
	v_sub_f32_e32 v5, v5, v192
	v_mul_f32_e32 v5, v5, v193
	v_fma_f32 v5, v187, v5, v191
	s_add_u32 s94, s78, 0x0
	s_addc_u32 s95, s79, 0
	global_store_dwordx4 v137, v[98:101], s[94:95]
	global_store_dwordx4 v137, v[94:97], s[94:95] offset:64
	global_store_dwordx4 v137, v[90:93], s[94:95] offset:128
	global_store_dwordx4 v137, v[86:89], s[94:95] offset:192
	global_store_dwordx4 v137, v[82:85], s[94:95] offset:256
	global_store_dwordx4 v137, v[78:81], s[94:95] offset:320
	global_store_dwordx4 v137, v[74:77], s[94:95] offset:384
	global_store_dwordx4 v137, v[70:73], s[94:95] offset:448
	s_add_u32 s94, s78, 0x10000
	s_addc_u32 s95, s79, 0
	global_store_dwordx4 v137, v[126:129], s[94:95]
	global_store_dwordx4 v137, v[122:125], s[94:95] offset:64
	global_store_dwordx4 v137, v[118:121], s[94:95] offset:128
	global_store_dwordx4 v137, v[114:117], s[94:95] offset:192
	global_store_dwordx4 v137, v[110:113], s[94:95] offset:256
	global_store_dwordx4 v137, v[106:109], s[94:95] offset:320
	global_store_dwordx4 v137, v[102:105], s[94:95] offset:384
	global_store_dwordx4 v137, v[66:69], s[94:95] offset:448
	s_add_u32 s94, s78, 0x20000
	s_addc_u32 s95, s79, 0
	global_store_dwordx4 v137, v[34:37], s[94:95]
	global_store_dwordx4 v137, v[30:33], s[94:95] offset:64
	global_store_dwordx4 v137, v[26:29], s[94:95] offset:128
	global_store_dwordx4 v137, v[22:25], s[94:95] offset:192
	global_store_dwordx4 v137, v[18:21], s[94:95] offset:256
	global_store_dwordx4 v137, v[14:17], s[94:95] offset:320
	global_store_dwordx4 v137, v[10:13], s[94:95] offset:384
	global_store_dwordx4 v137, v[6:9], s[94:95] offset:448
	s_add_u32 s94, s78, 0x30000
	s_addc_u32 s95, s79, 0
	global_store_dwordx4 v137, v[62:65], s[94:95]
	global_store_dwordx4 v137, v[58:61], s[94:95] offset:64
	global_store_dwordx4 v137, v[54:57], s[94:95] offset:128
	global_store_dwordx4 v137, v[50:53], s[94:95] offset:192
	global_store_dwordx4 v137, v[46:49], s[94:95] offset:256
	global_store_dwordx4 v137, v[42:45], s[94:95] offset:320
	global_store_dwordx4 v137, v[38:41], s[94:95] offset:384
	global_store_dwordx4 v137, v[2:5], s[94:95] offset:448
